# q5 + scan recurrence DPP-block nops shrunk to the 2-wait-state minimum
# speedup vs baseline: 1.0132x; 1.0040x over previous
; #define LAS __attribute__((address_space(3)))
; DI unsigned pk2(float a, float b) { f32x2 v = {a, b}; bf2_t r = __builtin_convertvector(v, bf2_t); return __builtin_bit_cast(unsigned, r); }
; DI f32x2 red16p(f32x2 x) { float a = x.x, b = x.y; red16x2(a, b); return (f32x2){a, b}; }
; DI void scan_bh2(const Args& a, int l, int bh, int halfsel, LAS unsigned char* lds) {
;     ...
;         for (int c = 0; c < SEQ / T; ++c) {
;             const LAS float* cur = opbuf + (c & 1) * CH;
;             LAS unsigned char* yb = ybuf + (c & 1) * (T * 128);
;             f32x4 r4 = *(const LAS f32x4*)(cur + kq * 4), d4 = *(const LAS f32x4*)(cur + 64 + kq * 4), k4 = *(const LAS f32x4*)(cur + 128 + kq * 4),
;                   kk4 = *(const LAS f32x4*)(cur + 192 + kq * 4), b4 = *(const LAS f32x4*)(cur + 256 + kq * 4);
;             f32x2 v2 = *(const LAS f32x2*)(cur + 320 + row0);
; #pragma unroll
;             for (int st = 0; st < T; ++st) {
;                 f32x4 nr4, nd4, nk4, nkk4, nb4; f32x2 nv2;
;                 if (st < T - 1) {
;                     const LAS float* o = cur + (st + 1) * 384;
;                     nr4 = *(const LAS f32x4*)(o + kq * 4); nd4 = *(const LAS f32x4*)(o + 64 + kq * 4); nk4 = *(const LAS f32x4*)(o + 128 + kq * 4);
;                     nkk4 = *(const LAS f32x4*)(o + 192 + kq * 4); nb4 = *(const LAS f32x4*)(o + 256 + kq * 4); nv2 = *(const LAS f32x2*)(o + 320 + row0);
;                 }
;                 f32x2 sa = S[0] * kk4[0]; sa += S[1] * kk4[1]; f32x2 sb = S[2] * kk4[2]; sb += S[3] * kk4[3]; sa += sb;
;                 sa = red16p(sa); sa = -sa;
; #pragma unroll
;                 for (int j = 0; j < 4; ++j) S[j] = S[j] * d4[j] + sa * b4[j] + v2 * k4[j];
;                 f32x2 y = S[0] * r4[0]; y += S[1] * r4[1]; f32x2 yc = S[2] * r4[2]; yc += S[3] * r4[3]; y += yc;
;                 y = red16p(y);
;                 *(LAS unsigned*)(yb + st * 128 + row0 * 2) = pk2(y.x, y.y);
;                 if (st < T - 1) { r4 = nr4; d4 = nd4; k4 = nk4; kk4 = nkk4; b4 = nb4; v2 = nv2; }
;             }
.LBB0_497:
	s_and_b32 s2, s4, 1
	s_mul_i32 s3, s2, 0xc000
	s_add_i32 s3, s3, 0
	v_lshl_add_u32 v15, v11, 2, s3
	ds_read_b128 v[18:21], v15
	ds_read_b128 v[22:25], v15 offset:256
	ds_read_b128 v[26:29], v15 offset:512
	ds_read_b128 v[30:33], v15 offset:768
	v_lshl_add_u32 v16, v10, 2, s3
	v_add_u32_e32 v14, 0x100, v16
	ds_read2st64_b64 v[34:37], v14 offset0:2 offset1:5
	ds_read_b128 v[38:41], v15 offset:1024
	ds_read_b128 v[42:45], v15 offset:1536
	ds_read_b128 v[46:49], v15 offset:1792
	ds_read_b128 v[50:53], v15 offset:2048
	ds_read_b128 v[54:57], v15 offset:2304
	ds_read_b128 v[58:61], v15 offset:2560
	s_waitcnt lgkmcnt(7)
	v_pk_mul_f32 v[62:63], v[4:5], v[30:31] op_sel:[0,1]
	s_lshl_b32 s2, s2, 12
	v_pk_fma_f32 v[30:31], v[2:3], v[30:31], v[62:63] op_sel_hi:[1,0,1]
	v_mov_b32_e32 v62, v33
	v_pk_mul_f32 v[62:63], v[8:9], v[62:63] op_sel_hi:[1,0]
	s_add_i32 s5, s2, 0
	v_pk_fma_f32 v[32:33], v[6:7], v[32:33], v[62:63] op_sel_hi:[1,0,1]
	s_add_i32 s5, s5, 0x18000
	v_pk_add_f32 v[30:31], v[30:31], v[32:33]
	v_add_u32_e32 v14, s5, v12
	s_nop 0
	v_add_f32_dpp v30, v30, v30 quad_perm:[1,0,3,2] row_mask:0xf bank_mask:0xf bound_ctrl:1
	v_add_f32_dpp v31, v31, v31 quad_perm:[1,0,3,2] row_mask:0xf bank_mask:0xf bound_ctrl:1
	s_nop 0
	v_add_f32_dpp v30, v30, v30 quad_perm:[2,3,0,1] row_mask:0xf bank_mask:0xf bound_ctrl:1
	v_add_f32_dpp v31, v31, v31 quad_perm:[2,3,0,1] row_mask:0xf bank_mask:0xf bound_ctrl:1
	s_nop 0
	v_add_f32_dpp v30, v30, v30 row_half_mirror row_mask:0xf bank_mask:0xf bound_ctrl:1
	v_add_f32_dpp v31, v31, v31 row_half_mirror row_mask:0xf bank_mask:0xf bound_ctrl:1
	s_nop 0
	v_add_f32_dpp v30, v30, v30 row_mirror row_mask:0xf bank_mask:0xf bound_ctrl:1
	v_add_f32_dpp v31, v31, v31 row_mirror row_mask:0xf bank_mask:0xf bound_ctrl:1
	s_waitcnt lgkmcnt(5)
	v_pk_mul_f32 v[32:33], v[38:39], v[30:31] op_sel_hi:[0,1]
	v_pk_fma_f32 v[2:3], v[2:3], v[22:23], v[32:33] op_sel_hi:[1,0,1] neg_lo:[0,0,1] neg_hi:[0,0,1]
	s_nop 0
	v_pk_fma_f32 v[32:33], v[26:27], v[34:35], v[2:3] op_sel_hi:[0,1,1]
	v_pk_mul_f32 v[2:3], v[38:39], v[30:31] op_sel:[1,0]
	s_nop 0
	v_pk_fma_f32 v[2:3], v[4:5], v[22:23], v[2:3] op_sel:[0,1,0] neg_lo:[0,0,1] neg_hi:[0,0,1]
	v_mov_b32_e32 v4, v41
	v_pk_fma_f32 v[38:39], v[26:27], v[34:35], v[2:3] op_sel:[1,0,0]
	v_pk_mul_f32 v[2:3], v[40:41], v[30:31] op_sel_hi:[0,1]
	v_pk_fma_f32 v[2:3], v[6:7], v[24:25], v[2:3] op_sel_hi:[1,0,1] neg_lo:[0,0,1] neg_hi:[0,0,1]
	v_pk_mul_f32 v[4:5], v[4:5], v[30:31] op_sel_hi:[0,1]
	v_pk_fma_f32 v[62:63], v[28:29], v[34:35], v[2:3] op_sel_hi:[0,1,1]
	v_mov_b32_e32 v2, v25
	v_pk_fma_f32 v[2:3], v[8:9], v[2:3], v[4:5] op_sel_hi:[1,0,1] neg_lo:[0,0,1] neg_hi:[0,0,1]
	v_mov_b32_e32 v4, v29
	v_pk_fma_f32 v[30:31], v[4:5], v[34:35], v[2:3] op_sel_hi:[0,1,1]
	s_waitcnt lgkmcnt(1)
	v_mov_b32_e32 v40, v57
	v_mov_b32_e32 v4, v21
	v_pk_mul_f32 v[34:35], v[54:55], v[38:39] op_sel:[1,0]
	v_pk_mul_f32 v[40:41], v[40:41], v[30:31] op_sel_hi:[0,1]
	v_pk_mul_f32 v[2:3], v[18:19], v[38:39] op_sel:[1,0]
	v_pk_mul_f32 v[4:5], v[4:5], v[30:31] op_sel_hi:[0,1]
	v_pk_fma_f32 v[34:35], v[54:55], v[32:33], v[34:35] op_sel_hi:[0,1,1]
	v_pk_fma_f32 v[40:41], v[56:57], v[62:63], v[40:41] op_sel_hi:[0,1,1]
	v_pk_fma_f32 v[2:3], v[18:19], v[32:33], v[2:3] op_sel_hi:[0,1,1]
	v_pk_fma_f32 v[4:5], v[20:21], v[62:63], v[4:5] op_sel_hi:[0,1,1]
	v_pk_add_f32 v[34:35], v[34:35], v[40:41]
	v_pk_add_f32 v[2:3], v[2:3], v[4:5]
	s_nop 0
	v_add_f32_dpp v34, v34, v34 quad_perm:[1,0,3,2] row_mask:0xf bank_mask:0xf bound_ctrl:1
	v_add_f32_dpp v35, v35, v35 quad_perm:[1,0,3,2] row_mask:0xf bank_mask:0xf bound_ctrl:1
	v_add_f32_dpp v2, v2, v2 quad_perm:[1,0,3,2] row_mask:0xf bank_mask:0xf bound_ctrl:1
	v_add_f32_dpp v3, v3, v3 quad_perm:[1,0,3,2] row_mask:0xf bank_mask:0xf bound_ctrl:1
	v_add_f32_dpp v34, v34, v34 quad_perm:[2,3,0,1] row_mask:0xf bank_mask:0xf bound_ctrl:1
	v_add_f32_dpp v35, v35, v35 quad_perm:[2,3,0,1] row_mask:0xf bank_mask:0xf bound_ctrl:1
	v_add_f32_dpp v2, v2, v2 quad_perm:[2,3,0,1] row_mask:0xf bank_mask:0xf bound_ctrl:1
	v_add_f32_dpp v3, v3, v3 quad_perm:[2,3,0,1] row_mask:0xf bank_mask:0xf bound_ctrl:1
	v_add_f32_dpp v34, v34, v34 row_half_mirror row_mask:0xf bank_mask:0xf bound_ctrl:1
	v_add_f32_dpp v35, v35, v35 row_half_mirror row_mask:0xf bank_mask:0xf bound_ctrl:1
	v_add_f32_dpp v2, v2, v2 row_half_mirror row_mask:0xf bank_mask:0xf bound_ctrl:1
	v_add_f32_dpp v3, v3, v3 row_half_mirror row_mask:0xf bank_mask:0xf bound_ctrl:1
	v_add_f32_dpp v34, v34, v34 row_mirror row_mask:0xf bank_mask:0xf bound_ctrl:1
	v_add_f32_dpp v35, v35, v35 row_mirror row_mask:0xf bank_mask:0xf bound_ctrl:1
	s_waitcnt lgkmcnt(0)
	v_pk_mul_f32 v[40:41], v[58:59], v[34:35] op_sel_hi:[0,1]
	v_add_f32_dpp v2, v2, v2 row_mirror row_mask:0xf bank_mask:0xf bound_ctrl:1
	v_add_f32_dpp v3, v3, v3 row_mirror row_mask:0xf bank_mask:0xf bound_ctrl:1
	v_pk_fma_f32 v[32:33], v[46:47], v[32:33], v[40:41] op_sel_hi:[0,1,1] neg_lo:[0,0,1] neg_hi:[0,0,1]
	v_cvt_pk_bf16_f32 v2, v2, v3
	v_pk_fma_f32 v[54:55], v[50:51], v[36:37], v[32:33] op_sel_hi:[0,1,1]
	v_pk_mul_f32 v[32:33], v[58:59], v[34:35] op_sel:[1,0]
	ds_write_b32 v14, v2
	v_pk_fma_f32 v[32:33], v[46:47], v[38:39], v[32:33] op_sel:[1,0,0] neg_lo:[0,0,1] neg_hi:[0,0,1]
	ds_read_b128 v[2:5], v15 offset:3072
	ds_read_b128 v[6:9], v15 offset:3328
	ds_read_b128 v[18:21], v15 offset:3584
	ds_read_b128 v[22:25], v15 offset:3840
	ds_read_b128 v[26:29], v15 offset:4096
	ds_read_b64 v[64:65], v16 offset:4352
	v_pk_fma_f32 v[50:51], v[50:51], v[36:37], v[32:33] op_sel:[1,0,0]
	v_pk_mul_f32 v[32:33], v[60:61], v[34:35] op_sel_hi:[0,1]
	v_pk_fma_f32 v[32:33], v[48:49], v[62:63], v[32:33] op_sel_hi:[0,1,1] neg_lo:[0,0,1] neg_hi:[0,0,1]
	v_mov_b32_e32 v38, v61
	v_pk_fma_f32 v[56:57], v[52:53], v[36:37], v[32:33] op_sel_hi:[0,1,1]
	v_mov_b32_e32 v32, v49
	v_pk_mul_f32 v[34:35], v[38:39], v[34:35] op_sel_hi:[0,1]
	v_pk_fma_f32 v[30:31], v[32:33], v[30:31], v[34:35] op_sel_hi:[0,1,1] neg_lo:[0,0,1] neg_hi:[0,0,1]
	v_mov_b32_e32 v32, v53
	s_waitcnt lgkmcnt(2)
; #define LAS __attribute__((address_space(3)))
; DI unsigned pk2(float a, float b) { f32x2 v = {a, b}; bf2_t r = __builtin_convertvector(v, bf2_t); return __builtin_bit_cast(unsigned, r); }
; DI f32x2 red16p(f32x2 x) { float a = x.x, b = x.y; red16x2(a, b); return (f32x2){a, b}; }
; DI void scan_bh2(const Args& a, int l, int bh, int halfsel, LAS unsigned char* lds) {
;     ...
;             for (int st = 0; st < T; ++st) {
;                 f32x4 nr4, nd4, nk4, nkk4, nb4; f32x2 nv2;
;                 if (st < T - 1) {
;                     const LAS float* o = cur + (st + 1) * 384;
;                     nr4 = *(const LAS f32x4*)(o + kq * 4); nd4 = *(const LAS f32x4*)(o + 64 + kq * 4); nk4 = *(const LAS f32x4*)(o + 128 + kq * 4);
;                     nkk4 = *(const LAS f32x4*)(o + 192 + kq * 4); nb4 = *(const LAS f32x4*)(o + 256 + kq * 4); nv2 = *(const LAS f32x2*)(o + 320 + row0);
;                 }
;                 f32x2 sa = S[0] * kk4[0]; sa += S[1] * kk4[1]; f32x2 sb = S[2] * kk4[2]; sb += S[3] * kk4[3]; sa += sb;
;                 sa = red16p(sa); sa = -sa;
; #pragma unroll
;                 for (int j = 0; j < 4; ++j) S[j] = S[j] * d4[j] + sa * b4[j] + v2 * k4[j];
;                 f32x2 y = S[0] * r4[0]; y += S[1] * r4[1]; f32x2 yc = S[2] * r4[2]; yc += S[3] * r4[3]; y += yc;
;                 y = red16p(y);
;                 *(LAS unsigned*)(yb + st * 128 + row0 * 2) = pk2(y.x, y.y);
;                 if (st < T - 1) { r4 = nr4; d4 = nd4; k4 = nk4; kk4 = nkk4; b4 = nb4; v2 = nv2; }
;             }
	v_pk_mul_f32 v[60:61], v[22:23], v[50:51] op_sel:[1,0]
	v_pk_fma_f32 v[52:53], v[32:33], v[36:37], v[30:31] op_sel_hi:[0,1,1]
	v_pk_fma_f32 v[22:23], v[22:23], v[54:55], v[60:61] op_sel_hi:[0,1,1]
	v_mov_b32_e32 v60, v25
	v_pk_mul_f32 v[60:61], v[60:61], v[52:53] op_sel_hi:[0,1]
	v_mov_b32_e32 v32, v45
	v_pk_fma_f32 v[24:25], v[24:25], v[56:57], v[60:61] op_sel_hi:[0,1,1]
	v_pk_mul_f32 v[30:31], v[42:43], v[50:51] op_sel:[1,0]
	v_pk_mul_f32 v[32:33], v[32:33], v[52:53] op_sel_hi:[0,1]
	v_pk_add_f32 v[22:23], v[22:23], v[24:25]
	v_pk_fma_f32 v[30:31], v[42:43], v[54:55], v[30:31] op_sel_hi:[0,1,1]
	v_pk_fma_f32 v[32:33], v[44:45], v[56:57], v[32:33] op_sel_hi:[0,1,1]
	v_add_f32_dpp v22, v22, v22 quad_perm:[1,0,3,2] row_mask:0xf bank_mask:0xf bound_ctrl:1
	v_add_f32_dpp v23, v23, v23 quad_perm:[1,0,3,2] row_mask:0xf bank_mask:0xf bound_ctrl:1
	v_pk_add_f32 v[30:31], v[30:31], v[32:33]
	v_add_f32_dpp v22, v22, v22 quad_perm:[2,3,0,1] row_mask:0xf bank_mask:0xf bound_ctrl:1
	v_add_f32_dpp v23, v23, v23 quad_perm:[2,3,0,1] row_mask:0xf bank_mask:0xf bound_ctrl:1
	v_add_f32_dpp v30, v30, v30 quad_perm:[1,0,3,2] row_mask:0xf bank_mask:0xf bound_ctrl:1
	v_add_f32_dpp v31, v31, v31 quad_perm:[1,0,3,2] row_mask:0xf bank_mask:0xf bound_ctrl:1
	v_add_f32_dpp v22, v22, v22 row_half_mirror row_mask:0xf bank_mask:0xf bound_ctrl:1
	v_add_f32_dpp v23, v23, v23 row_half_mirror row_mask:0xf bank_mask:0xf bound_ctrl:1
	v_add_f32_dpp v30, v30, v30 quad_perm:[2,3,0,1] row_mask:0xf bank_mask:0xf bound_ctrl:1
	v_add_f32_dpp v31, v31, v31 quad_perm:[2,3,0,1] row_mask:0xf bank_mask:0xf bound_ctrl:1
	v_add_f32_dpp v22, v22, v22 row_mirror row_mask:0xf bank_mask:0xf bound_ctrl:1
	v_add_f32_dpp v23, v23, v23 row_mirror row_mask:0xf bank_mask:0xf bound_ctrl:1
	s_waitcnt lgkmcnt(1)
	v_pk_mul_f32 v[24:25], v[26:27], v[22:23] op_sel_hi:[0,1]
	v_add_f32_dpp v30, v30, v30 row_half_mirror row_mask:0xf bank_mask:0xf bound_ctrl:1
	v_add_f32_dpp v31, v31, v31 row_half_mirror row_mask:0xf bank_mask:0xf bound_ctrl:1
	v_pk_fma_f32 v[24:25], v[6:7], v[54:55], v[24:25] op_sel_hi:[0,1,1] neg_lo:[0,0,1] neg_hi:[0,0,1]
	v_add_f32_dpp v30, v30, v30 row_mirror row_mask:0xf bank_mask:0xf bound_ctrl:1
	v_add_f32_dpp v31, v31, v31 row_mirror row_mask:0xf bank_mask:0xf bound_ctrl:1
	s_waitcnt lgkmcnt(0)
	v_pk_fma_f32 v[54:55], v[18:19], v[64:65], v[24:25] op_sel_hi:[0,1,1]
	v_cvt_pk_bf16_f32 v17, v30, v31
	v_pk_mul_f32 v[24:25], v[26:27], v[22:23] op_sel:[1,0]
	ds_write_b32 v14, v17 offset:128
	v_pk_fma_f32 v[6:7], v[6:7], v[50:51], v[24:25] op_sel:[1,0,0] neg_lo:[0,0,1] neg_hi:[0,0,1]
	ds_read_b128 v[30:33], v15 offset:4608
	ds_read_b128 v[34:37], v15 offset:4864
	ds_read_b128 v[38:41], v15 offset:5120
	ds_read_b128 v[42:45], v15 offset:5376
	ds_read_b128 v[46:49], v15 offset:5632
	ds_read_b64 v[58:59], v16 offset:5888
	v_pk_fma_f32 v[50:51], v[18:19], v[64:65], v[6:7] op_sel:[1,0,0]
	v_pk_mul_f32 v[6:7], v[28:29], v[22:23] op_sel_hi:[0,1]
	v_pk_fma_f32 v[6:7], v[8:9], v[56:57], v[6:7] op_sel_hi:[0,1,1] neg_lo:[0,0,1] neg_hi:[0,0,1]
	v_mov_b32_e32 v8, v29
	v_pk_fma_f32 v[56:57], v[20:21], v[64:65], v[6:7] op_sel_hi:[0,1,1]
	v_mov_b32_e32 v6, v9
	v_pk_mul_f32 v[8:9], v[8:9], v[22:23] op_sel_hi:[0,1]
	v_pk_fma_f32 v[6:7], v[6:7], v[52:53], v[8:9] op_sel_hi:[0,1,1] neg_lo:[0,0,1] neg_hi:[0,0,1]
	v_mov_b32_e32 v8, v21
	s_waitcnt lgkmcnt(2)
	v_pk_mul_f32 v[62:63], v[42:43], v[50:51] op_sel:[1,0]
	v_pk_fma_f32 v[52:53], v[8:9], v[64:65], v[6:7] op_sel_hi:[0,1,1]
	v_pk_mul_f32 v[6:7], v[2:3], v[50:51] op_sel:[1,0]
	v_pk_fma_f32 v[42:43], v[42:43], v[54:55], v[62:63] op_sel_hi:[0,1,1]
	v_mov_b32_e32 v62, v45
	v_pk_fma_f32 v[2:3], v[2:3], v[54:55], v[6:7] op_sel_hi:[0,1,1]
	v_mov_b32_e32 v6, v5
	v_pk_mul_f32 v[62:63], v[62:63], v[52:53] op_sel_hi:[0,1]
	v_pk_mul_f32 v[6:7], v[6:7], v[52:53] op_sel_hi:[0,1]
	v_pk_fma_f32 v[44:45], v[44:45], v[56:57], v[62:63] op_sel_hi:[0,1,1]
	v_pk_fma_f32 v[4:5], v[4:5], v[56:57], v[6:7] op_sel_hi:[0,1,1]
	v_pk_add_f32 v[42:43], v[42:43], v[44:45]
	v_pk_add_f32 v[2:3], v[2:3], v[4:5]
	s_nop 0
	v_add_f32_dpp v42, v42, v42 quad_perm:[1,0,3,2] row_mask:0xf bank_mask:0xf bound_ctrl:1
	v_add_f32_dpp v43, v43, v43 quad_perm:[1,0,3,2] row_mask:0xf bank_mask:0xf bound_ctrl:1
	v_add_f32_dpp v2, v2, v2 quad_perm:[1,0,3,2] row_mask:0xf bank_mask:0xf bound_ctrl:1
	v_add_f32_dpp v3, v3, v3 quad_perm:[1,0,3,2] row_mask:0xf bank_mask:0xf bound_ctrl:1
	v_add_f32_dpp v42, v42, v42 quad_perm:[2,3,0,1] row_mask:0xf bank_mask:0xf bound_ctrl:1
	v_add_f32_dpp v43, v43, v43 quad_perm:[2,3,0,1] row_mask:0xf bank_mask:0xf bound_ctrl:1
	v_add_f32_dpp v2, v2, v2 quad_perm:[2,3,0,1] row_mask:0xf bank_mask:0xf bound_ctrl:1
	v_add_f32_dpp v3, v3, v3 quad_perm:[2,3,0,1] row_mask:0xf bank_mask:0xf bound_ctrl:1
	v_add_f32_dpp v42, v42, v42 row_half_mirror row_mask:0xf bank_mask:0xf bound_ctrl:1
	v_add_f32_dpp v43, v43, v43 row_half_mirror row_mask:0xf bank_mask:0xf bound_ctrl:1
	v_add_f32_dpp v2, v2, v2 row_half_mirror row_mask:0xf bank_mask:0xf bound_ctrl:1
	v_add_f32_dpp v3, v3, v3 row_half_mirror row_mask:0xf bank_mask:0xf bound_ctrl:1
	v_add_f32_dpp v42, v42, v42 row_mirror row_mask:0xf bank_mask:0xf bound_ctrl:1
	v_add_f32_dpp v43, v43, v43 row_mirror row_mask:0xf bank_mask:0xf bound_ctrl:1
	s_waitcnt lgkmcnt(1)
	v_pk_mul_f32 v[44:45], v[46:47], v[42:43] op_sel_hi:[0,1]
	v_add_f32_dpp v2, v2, v2 row_mirror row_mask:0xf bank_mask:0xf bound_ctrl:1
	v_add_f32_dpp v3, v3, v3 row_mirror row_mask:0xf bank_mask:0xf bound_ctrl:1
	v_pk_fma_f32 v[44:45], v[34:35], v[54:55], v[44:45] op_sel_hi:[0,1,1] neg_lo:[0,0,1] neg_hi:[0,0,1]
	v_cvt_pk_bf16_f32 v2, v2, v3
	s_waitcnt lgkmcnt(0)
; #define LAS __attribute__((address_space(3)))
; DI unsigned pk2(float a, float b) { f32x2 v = {a, b}; bf2_t r = __builtin_convertvector(v, bf2_t); return __builtin_bit_cast(unsigned, r); }
; DI f32x2 red16p(f32x2 x) { float a = x.x, b = x.y; red16x2(a, b); return (f32x2){a, b}; }
; DI void scan_bh2(const Args& a, int l, int bh, int halfsel, LAS unsigned char* lds) {
;     ...
;             for (int st = 0; st < T; ++st) {
;                 f32x4 nr4, nd4, nk4, nkk4, nb4; f32x2 nv2;
;                 if (st < T - 1) {
;                     const LAS float* o = cur + (st + 1) * 384;
;                     nr4 = *(const LAS f32x4*)(o + kq * 4); nd4 = *(const LAS f32x4*)(o + 64 + kq * 4); nk4 = *(const LAS f32x4*)(o + 128 + kq * 4);
;                     nkk4 = *(const LAS f32x4*)(o + 192 + kq * 4); nb4 = *(const LAS f32x4*)(o + 256 + kq * 4); nv2 = *(const LAS f32x2*)(o + 320 + row0);
;                 }
;                 f32x2 sa = S[0] * kk4[0]; sa += S[1] * kk4[1]; f32x2 sb = S[2] * kk4[2]; sb += S[3] * kk4[3]; sa += sb;
;                 sa = red16p(sa); sa = -sa;
; #pragma unroll
;                 for (int j = 0; j < 4; ++j) S[j] = S[j] * d4[j] + sa * b4[j] + v2 * k4[j];
;                 f32x2 y = S[0] * r4[0]; y += S[1] * r4[1]; f32x2 yc = S[2] * r4[2]; yc += S[3] * r4[3]; y += yc;
;                 y = red16p(y);
;                 *(LAS unsigned*)(yb + st * 128 + row0 * 2) = pk2(y.x, y.y);
;                 if (st < T - 1) { r4 = nr4; d4 = nd4; k4 = nk4; kk4 = nkk4; b4 = nb4; v2 = nv2; }
;             }
	v_pk_fma_f32 v[54:55], v[38:39], v[58:59], v[44:45] op_sel_hi:[0,1,1]
	v_pk_mul_f32 v[44:45], v[46:47], v[42:43] op_sel:[1,0]
	ds_write_b32 v14, v2 offset:256
	v_pk_fma_f32 v[34:35], v[34:35], v[50:51], v[44:45] op_sel:[1,0,0] neg_lo:[0,0,1] neg_hi:[0,0,1]
	ds_read_b128 v[2:5], v15 offset:6144
	ds_read_b128 v[6:9], v15 offset:6400
	ds_read_b128 v[18:21], v15 offset:6656
	ds_read_b128 v[22:25], v15 offset:6912
	ds_read_b128 v[26:29], v15 offset:7168
	ds_read_b64 v[60:61], v16 offset:7424
	v_pk_fma_f32 v[50:51], v[38:39], v[58:59], v[34:35] op_sel:[1,0,0]
	v_pk_mul_f32 v[34:35], v[48:49], v[42:43] op_sel_hi:[0,1]
	v_pk_fma_f32 v[34:35], v[36:37], v[56:57], v[34:35] op_sel_hi:[0,1,1] neg_lo:[0,0,1] neg_hi:[0,0,1]
	v_mov_b32_e32 v36, v49
	v_pk_fma_f32 v[56:57], v[40:41], v[58:59], v[34:35] op_sel_hi:[0,1,1]
	v_mov_b32_e32 v34, v37
	v_pk_mul_f32 v[36:37], v[36:37], v[42:43] op_sel_hi:[0,1]
	v_pk_fma_f32 v[34:35], v[34:35], v[52:53], v[36:37] op_sel_hi:[0,1,1] neg_lo:[0,0,1] neg_hi:[0,0,1]
	v_mov_b32_e32 v36, v41
	s_waitcnt lgkmcnt(2)
	v_pk_mul_f32 v[62:63], v[22:23], v[50:51] op_sel:[1,0]
	v_pk_fma_f32 v[52:53], v[36:37], v[58:59], v[34:35] op_sel_hi:[0,1,1]
	v_pk_fma_f32 v[22:23], v[22:23], v[54:55], v[62:63] op_sel_hi:[0,1,1]
	v_mov_b32_e32 v62, v25
	v_pk_mul_f32 v[34:35], v[30:31], v[50:51] op_sel:[1,0]
	v_pk_mul_f32 v[62:63], v[62:63], v[52:53] op_sel_hi:[0,1]
	v_pk_fma_f32 v[30:31], v[30:31], v[54:55], v[34:35] op_sel_hi:[0,1,1]
	v_mov_b32_e32 v34, v33
	v_pk_fma_f32 v[24:25], v[24:25], v[56:57], v[62:63] op_sel_hi:[0,1,1]
	v_pk_mul_f32 v[34:35], v[34:35], v[52:53] op_sel_hi:[0,1]
	v_pk_add_f32 v[22:23], v[22:23], v[24:25]
	v_pk_fma_f32 v[32:33], v[32:33], v[56:57], v[34:35] op_sel_hi:[0,1,1]
	s_nop 0
	v_add_f32_dpp v22, v22, v22 quad_perm:[1,0,3,2] row_mask:0xf bank_mask:0xf bound_ctrl:1
	v_add_f32_dpp v23, v23, v23 quad_perm:[1,0,3,2] row_mask:0xf bank_mask:0xf bound_ctrl:1
	v_pk_add_f32 v[30:31], v[30:31], v[32:33]
	v_add_f32_dpp v22, v22, v22 quad_perm:[2,3,0,1] row_mask:0xf bank_mask:0xf bound_ctrl:1
	v_add_f32_dpp v23, v23, v23 quad_perm:[2,3,0,1] row_mask:0xf bank_mask:0xf bound_ctrl:1
	v_add_f32_dpp v30, v30, v30 quad_perm:[1,0,3,2] row_mask:0xf bank_mask:0xf bound_ctrl:1
	v_add_f32_dpp v31, v31, v31 quad_perm:[1,0,3,2] row_mask:0xf bank_mask:0xf bound_ctrl:1
	v_add_f32_dpp v22, v22, v22 row_half_mirror row_mask:0xf bank_mask:0xf bound_ctrl:1
	v_add_f32_dpp v23, v23, v23 row_half_mirror row_mask:0xf bank_mask:0xf bound_ctrl:1
	v_add_f32_dpp v30, v30, v30 quad_perm:[2,3,0,1] row_mask:0xf bank_mask:0xf bound_ctrl:1
	v_add_f32_dpp v31, v31, v31 quad_perm:[2,3,0,1] row_mask:0xf bank_mask:0xf bound_ctrl:1
	v_add_f32_dpp v22, v22, v22 row_mirror row_mask:0xf bank_mask:0xf bound_ctrl:1
	v_add_f32_dpp v23, v23, v23 row_mirror row_mask:0xf bank_mask:0xf bound_ctrl:1
	s_waitcnt lgkmcnt(1)
	v_pk_mul_f32 v[24:25], v[26:27], v[22:23] op_sel_hi:[0,1]
	v_add_f32_dpp v30, v30, v30 row_half_mirror row_mask:0xf bank_mask:0xf bound_ctrl:1
	v_add_f32_dpp v31, v31, v31 row_half_mirror row_mask:0xf bank_mask:0xf bound_ctrl:1
	v_pk_fma_f32 v[24:25], v[6:7], v[54:55], v[24:25] op_sel_hi:[0,1,1] neg_lo:[0,0,1] neg_hi:[0,0,1]
	v_add_f32_dpp v30, v30, v30 row_mirror row_mask:0xf bank_mask:0xf bound_ctrl:1
	v_add_f32_dpp v31, v31, v31 row_mirror row_mask:0xf bank_mask:0xf bound_ctrl:1
	s_waitcnt lgkmcnt(0)
	v_pk_fma_f32 v[54:55], v[18:19], v[60:61], v[24:25] op_sel_hi:[0,1,1]
	v_cvt_pk_bf16_f32 v17, v30, v31
	v_pk_mul_f32 v[24:25], v[26:27], v[22:23] op_sel:[1,0]
	ds_write_b32 v14, v17 offset:384
	v_pk_fma_f32 v[6:7], v[6:7], v[50:51], v[24:25] op_sel:[1,0,0] neg_lo:[0,0,1] neg_hi:[0,0,1]
	ds_read_b128 v[30:33], v15 offset:7680
	ds_read_b128 v[34:37], v15 offset:7936
	ds_read_b128 v[38:41], v15 offset:8192
	ds_read_b128 v[42:45], v15 offset:8448
	ds_read_b128 v[46:49], v15 offset:8704
	ds_read_b64 v[58:59], v16 offset:8960
	v_pk_fma_f32 v[50:51], v[18:19], v[60:61], v[6:7] op_sel:[1,0,0]
	v_pk_mul_f32 v[6:7], v[28:29], v[22:23] op_sel_hi:[0,1]
	v_pk_fma_f32 v[6:7], v[8:9], v[56:57], v[6:7] op_sel_hi:[0,1,1] neg_lo:[0,0,1] neg_hi:[0,0,1]
	v_mov_b32_e32 v8, v29
	v_pk_fma_f32 v[56:57], v[20:21], v[60:61], v[6:7] op_sel_hi:[0,1,1]
	v_mov_b32_e32 v6, v9
	v_pk_mul_f32 v[8:9], v[8:9], v[22:23] op_sel_hi:[0,1]
	v_pk_fma_f32 v[6:7], v[6:7], v[52:53], v[8:9] op_sel_hi:[0,1,1] neg_lo:[0,0,1] neg_hi:[0,0,1]
	v_mov_b32_e32 v8, v21
	s_waitcnt lgkmcnt(2)
	v_pk_mul_f32 v[62:63], v[42:43], v[50:51] op_sel:[1,0]
	v_pk_fma_f32 v[52:53], v[8:9], v[60:61], v[6:7] op_sel_hi:[0,1,1]
	v_pk_mul_f32 v[6:7], v[2:3], v[50:51] op_sel:[1,0]
	v_pk_fma_f32 v[42:43], v[42:43], v[54:55], v[62:63] op_sel_hi:[0,1,1]
	v_mov_b32_e32 v62, v45
	v_pk_fma_f32 v[2:3], v[2:3], v[54:55], v[6:7] op_sel_hi:[0,1,1]
	v_mov_b32_e32 v6, v5
	v_pk_mul_f32 v[62:63], v[62:63], v[52:53] op_sel_hi:[0,1]
	v_pk_mul_f32 v[6:7], v[6:7], v[52:53] op_sel_hi:[0,1]
	v_pk_fma_f32 v[44:45], v[44:45], v[56:57], v[62:63] op_sel_hi:[0,1,1]
	v_pk_fma_f32 v[4:5], v[4:5], v[56:57], v[6:7] op_sel_hi:[0,1,1]
	v_pk_add_f32 v[42:43], v[42:43], v[44:45]
	v_pk_add_f32 v[2:3], v[2:3], v[4:5]
	s_nop 0
	v_add_f32_dpp v42, v42, v42 quad_perm:[1,0,3,2] row_mask:0xf bank_mask:0xf bound_ctrl:1
	v_add_f32_dpp v43, v43, v43 quad_perm:[1,0,3,2] row_mask:0xf bank_mask:0xf bound_ctrl:1
	v_add_f32_dpp v2, v2, v2 quad_perm:[1,0,3,2] row_mask:0xf bank_mask:0xf bound_ctrl:1
	v_add_f32_dpp v3, v3, v3 quad_perm:[1,0,3,2] row_mask:0xf bank_mask:0xf bound_ctrl:1
	v_add_f32_dpp v42, v42, v42 quad_perm:[2,3,0,1] row_mask:0xf bank_mask:0xf bound_ctrl:1
	v_add_f32_dpp v43, v43, v43 quad_perm:[2,3,0,1] row_mask:0xf bank_mask:0xf bound_ctrl:1
	v_add_f32_dpp v2, v2, v2 quad_perm:[2,3,0,1] row_mask:0xf bank_mask:0xf bound_ctrl:1
	v_add_f32_dpp v3, v3, v3 quad_perm:[2,3,0,1] row_mask:0xf bank_mask:0xf bound_ctrl:1
	v_add_f32_dpp v42, v42, v42 row_half_mirror row_mask:0xf bank_mask:0xf bound_ctrl:1
	v_add_f32_dpp v43, v43, v43 row_half_mirror row_mask:0xf bank_mask:0xf bound_ctrl:1
	v_add_f32_dpp v2, v2, v2 row_half_mirror row_mask:0xf bank_mask:0xf bound_ctrl:1
	v_add_f32_dpp v3, v3, v3 row_half_mirror row_mask:0xf bank_mask:0xf bound_ctrl:1
	v_add_f32_dpp v42, v42, v42 row_mirror row_mask:0xf bank_mask:0xf bound_ctrl:1
	v_add_f32_dpp v43, v43, v43 row_mirror row_mask:0xf bank_mask:0xf bound_ctrl:1
	s_waitcnt lgkmcnt(1)
; #define LAS __attribute__((address_space(3)))
; DI unsigned pk2(float a, float b) { f32x2 v = {a, b}; bf2_t r = __builtin_convertvector(v, bf2_t); return __builtin_bit_cast(unsigned, r); }
; DI f32x2 red16p(f32x2 x) { float a = x.x, b = x.y; red16x2(a, b); return (f32x2){a, b}; }
; DI void scan_bh2(const Args& a, int l, int bh, int halfsel, LAS unsigned char* lds) {
;     ...
;             for (int st = 0; st < T; ++st) {
;                 f32x4 nr4, nd4, nk4, nkk4, nb4; f32x2 nv2;
;                 if (st < T - 1) {
;                     const LAS float* o = cur + (st + 1) * 384;
;                     nr4 = *(const LAS f32x4*)(o + kq * 4); nd4 = *(const LAS f32x4*)(o + 64 + kq * 4); nk4 = *(const LAS f32x4*)(o + 128 + kq * 4);
;                     nkk4 = *(const LAS f32x4*)(o + 192 + kq * 4); nb4 = *(const LAS f32x4*)(o + 256 + kq * 4); nv2 = *(const LAS f32x2*)(o + 320 + row0);
;                 }
;                 f32x2 sa = S[0] * kk4[0]; sa += S[1] * kk4[1]; f32x2 sb = S[2] * kk4[2]; sb += S[3] * kk4[3]; sa += sb;
;                 sa = red16p(sa); sa = -sa;
; #pragma unroll
;                 for (int j = 0; j < 4; ++j) S[j] = S[j] * d4[j] + sa * b4[j] + v2 * k4[j];
;                 f32x2 y = S[0] * r4[0]; y += S[1] * r4[1]; f32x2 yc = S[2] * r4[2]; yc += S[3] * r4[3]; y += yc;
;                 y = red16p(y);
;                 *(LAS unsigned*)(yb + st * 128 + row0 * 2) = pk2(y.x, y.y);
;                 if (st < T - 1) { r4 = nr4; d4 = nd4; k4 = nk4; kk4 = nkk4; b4 = nb4; v2 = nv2; }
;             }
	v_pk_mul_f32 v[44:45], v[46:47], v[42:43] op_sel_hi:[0,1]
	v_add_f32_dpp v2, v2, v2 row_mirror row_mask:0xf bank_mask:0xf bound_ctrl:1
	v_add_f32_dpp v3, v3, v3 row_mirror row_mask:0xf bank_mask:0xf bound_ctrl:1
	v_pk_fma_f32 v[44:45], v[34:35], v[54:55], v[44:45] op_sel_hi:[0,1,1] neg_lo:[0,0,1] neg_hi:[0,0,1]
	v_cvt_pk_bf16_f32 v2, v2, v3
	s_waitcnt lgkmcnt(0)
	v_pk_fma_f32 v[54:55], v[38:39], v[58:59], v[44:45] op_sel_hi:[0,1,1]
	v_pk_mul_f32 v[44:45], v[46:47], v[42:43] op_sel:[1,0]
	ds_write_b32 v14, v2 offset:512
	v_pk_fma_f32 v[34:35], v[34:35], v[50:51], v[44:45] op_sel:[1,0,0] neg_lo:[0,0,1] neg_hi:[0,0,1]
	ds_read_b128 v[2:5], v15 offset:9216
	ds_read_b128 v[6:9], v15 offset:9472
	ds_read_b128 v[18:21], v15 offset:9728
	ds_read_b128 v[22:25], v15 offset:9984
	ds_read_b128 v[26:29], v15 offset:10240
	ds_read_b64 v[60:61], v16 offset:10496
	v_pk_fma_f32 v[50:51], v[38:39], v[58:59], v[34:35] op_sel:[1,0,0]
	v_pk_mul_f32 v[34:35], v[48:49], v[42:43] op_sel_hi:[0,1]
	v_pk_fma_f32 v[34:35], v[36:37], v[56:57], v[34:35] op_sel_hi:[0,1,1] neg_lo:[0,0,1] neg_hi:[0,0,1]
	v_mov_b32_e32 v36, v49
	v_pk_fma_f32 v[56:57], v[40:41], v[58:59], v[34:35] op_sel_hi:[0,1,1]
	v_mov_b32_e32 v34, v37
	v_pk_mul_f32 v[36:37], v[36:37], v[42:43] op_sel_hi:[0,1]
	v_pk_fma_f32 v[34:35], v[34:35], v[52:53], v[36:37] op_sel_hi:[0,1,1] neg_lo:[0,0,1] neg_hi:[0,0,1]
	v_mov_b32_e32 v36, v41
	s_waitcnt lgkmcnt(2)
	v_pk_mul_f32 v[62:63], v[22:23], v[50:51] op_sel:[1,0]
	v_pk_fma_f32 v[52:53], v[36:37], v[58:59], v[34:35] op_sel_hi:[0,1,1]
	v_pk_fma_f32 v[22:23], v[22:23], v[54:55], v[62:63] op_sel_hi:[0,1,1]
	v_mov_b32_e32 v62, v25
	v_pk_mul_f32 v[34:35], v[30:31], v[50:51] op_sel:[1,0]
	v_pk_mul_f32 v[62:63], v[62:63], v[52:53] op_sel_hi:[0,1]
	v_pk_fma_f32 v[30:31], v[30:31], v[54:55], v[34:35] op_sel_hi:[0,1,1]
	v_mov_b32_e32 v34, v33
	v_pk_fma_f32 v[24:25], v[24:25], v[56:57], v[62:63] op_sel_hi:[0,1,1]
	v_pk_mul_f32 v[34:35], v[34:35], v[52:53] op_sel_hi:[0,1]
	v_pk_add_f32 v[22:23], v[22:23], v[24:25]
	v_pk_fma_f32 v[32:33], v[32:33], v[56:57], v[34:35] op_sel_hi:[0,1,1]
	s_nop 0
	v_add_f32_dpp v22, v22, v22 quad_perm:[1,0,3,2] row_mask:0xf bank_mask:0xf bound_ctrl:1
	v_add_f32_dpp v23, v23, v23 quad_perm:[1,0,3,2] row_mask:0xf bank_mask:0xf bound_ctrl:1
	v_pk_add_f32 v[30:31], v[30:31], v[32:33]
	v_add_f32_dpp v22, v22, v22 quad_perm:[2,3,0,1] row_mask:0xf bank_mask:0xf bound_ctrl:1
	v_add_f32_dpp v23, v23, v23 quad_perm:[2,3,0,1] row_mask:0xf bank_mask:0xf bound_ctrl:1
	v_add_f32_dpp v30, v30, v30 quad_perm:[1,0,3,2] row_mask:0xf bank_mask:0xf bound_ctrl:1
	v_add_f32_dpp v31, v31, v31 quad_perm:[1,0,3,2] row_mask:0xf bank_mask:0xf bound_ctrl:1
	v_add_f32_dpp v22, v22, v22 row_half_mirror row_mask:0xf bank_mask:0xf bound_ctrl:1
	v_add_f32_dpp v23, v23, v23 row_half_mirror row_mask:0xf bank_mask:0xf bound_ctrl:1
	v_add_f32_dpp v30, v30, v30 quad_perm:[2,3,0,1] row_mask:0xf bank_mask:0xf bound_ctrl:1
	v_add_f32_dpp v31, v31, v31 quad_perm:[2,3,0,1] row_mask:0xf bank_mask:0xf bound_ctrl:1
	v_add_f32_dpp v22, v22, v22 row_mirror row_mask:0xf bank_mask:0xf bound_ctrl:1
	v_add_f32_dpp v23, v23, v23 row_mirror row_mask:0xf bank_mask:0xf bound_ctrl:1
	s_waitcnt lgkmcnt(1)
	v_pk_mul_f32 v[24:25], v[26:27], v[22:23] op_sel_hi:[0,1]
	v_add_f32_dpp v30, v30, v30 row_half_mirror row_mask:0xf bank_mask:0xf bound_ctrl:1
	v_add_f32_dpp v31, v31, v31 row_half_mirror row_mask:0xf bank_mask:0xf bound_ctrl:1
	v_pk_fma_f32 v[24:25], v[6:7], v[54:55], v[24:25] op_sel_hi:[0,1,1] neg_lo:[0,0,1] neg_hi:[0,0,1]
	v_add_f32_dpp v30, v30, v30 row_mirror row_mask:0xf bank_mask:0xf bound_ctrl:1
	v_add_f32_dpp v31, v31, v31 row_mirror row_mask:0xf bank_mask:0xf bound_ctrl:1
	s_waitcnt lgkmcnt(0)
	v_pk_fma_f32 v[54:55], v[18:19], v[60:61], v[24:25] op_sel_hi:[0,1,1]
	v_cvt_pk_bf16_f32 v17, v30, v31
	v_pk_mul_f32 v[24:25], v[26:27], v[22:23] op_sel:[1,0]
	ds_write_b32 v14, v17 offset:640
	v_pk_fma_f32 v[6:7], v[6:7], v[50:51], v[24:25] op_sel:[1,0,0] neg_lo:[0,0,1] neg_hi:[0,0,1]
	ds_read_b128 v[30:33], v15 offset:10752
	ds_read_b128 v[34:37], v15 offset:11008
	ds_read_b128 v[38:41], v15 offset:11264
	ds_read_b128 v[42:45], v15 offset:11520
	ds_read_b128 v[46:49], v15 offset:11776
	ds_read_b64 v[58:59], v16 offset:12032
	v_pk_fma_f32 v[50:51], v[18:19], v[60:61], v[6:7] op_sel:[1,0,0]
	v_pk_mul_f32 v[6:7], v[28:29], v[22:23] op_sel_hi:[0,1]
	v_pk_fma_f32 v[6:7], v[8:9], v[56:57], v[6:7] op_sel_hi:[0,1,1] neg_lo:[0,0,1] neg_hi:[0,0,1]
	v_mov_b32_e32 v8, v29
	v_pk_fma_f32 v[56:57], v[20:21], v[60:61], v[6:7] op_sel_hi:[0,1,1]
	v_mov_b32_e32 v6, v9
	v_pk_mul_f32 v[8:9], v[8:9], v[22:23] op_sel_hi:[0,1]
	v_pk_fma_f32 v[6:7], v[6:7], v[52:53], v[8:9] op_sel_hi:[0,1,1] neg_lo:[0,0,1] neg_hi:[0,0,1]
	v_mov_b32_e32 v8, v21
	s_waitcnt lgkmcnt(2)
; #define LAS __attribute__((address_space(3)))
; DI unsigned pk2(float a, float b) { f32x2 v = {a, b}; bf2_t r = __builtin_convertvector(v, bf2_t); return __builtin_bit_cast(unsigned, r); }
; DI f32x2 red16p(f32x2 x) { float a = x.x, b = x.y; red16x2(a, b); return (f32x2){a, b}; }
; DI void scan_bh2(const Args& a, int l, int bh, int halfsel, LAS unsigned char* lds) {
;     ...
;             for (int st = 0; st < T; ++st) {
;                 f32x4 nr4, nd4, nk4, nkk4, nb4; f32x2 nv2;
;                 if (st < T - 1) {
;                     const LAS float* o = cur + (st + 1) * 384;
;                     nr4 = *(const LAS f32x4*)(o + kq * 4); nd4 = *(const LAS f32x4*)(o + 64 + kq * 4); nk4 = *(const LAS f32x4*)(o + 128 + kq * 4);
;                     nkk4 = *(const LAS f32x4*)(o + 192 + kq * 4); nb4 = *(const LAS f32x4*)(o + 256 + kq * 4); nv2 = *(const LAS f32x2*)(o + 320 + row0);
;                 }
;                 f32x2 sa = S[0] * kk4[0]; sa += S[1] * kk4[1]; f32x2 sb = S[2] * kk4[2]; sb += S[3] * kk4[3]; sa += sb;
;                 sa = red16p(sa); sa = -sa;
; #pragma unroll
;                 for (int j = 0; j < 4; ++j) S[j] = S[j] * d4[j] + sa * b4[j] + v2 * k4[j];
;                 f32x2 y = S[0] * r4[0]; y += S[1] * r4[1]; f32x2 yc = S[2] * r4[2]; yc += S[3] * r4[3]; y += yc;
;                 y = red16p(y);
;                 *(LAS unsigned*)(yb + st * 128 + row0 * 2) = pk2(y.x, y.y);
;                 if (st < T - 1) { r4 = nr4; d4 = nd4; k4 = nk4; kk4 = nkk4; b4 = nb4; v2 = nv2; }
;             }
	v_pk_mul_f32 v[62:63], v[42:43], v[50:51] op_sel:[1,0]
	v_pk_fma_f32 v[52:53], v[8:9], v[60:61], v[6:7] op_sel_hi:[0,1,1]
	v_pk_mul_f32 v[6:7], v[2:3], v[50:51] op_sel:[1,0]
	v_pk_fma_f32 v[42:43], v[42:43], v[54:55], v[62:63] op_sel_hi:[0,1,1]
	v_mov_b32_e32 v62, v45
	v_pk_fma_f32 v[2:3], v[2:3], v[54:55], v[6:7] op_sel_hi:[0,1,1]
	v_mov_b32_e32 v6, v5
	v_pk_mul_f32 v[62:63], v[62:63], v[52:53] op_sel_hi:[0,1]
	v_pk_mul_f32 v[6:7], v[6:7], v[52:53] op_sel_hi:[0,1]
	v_pk_fma_f32 v[44:45], v[44:45], v[56:57], v[62:63] op_sel_hi:[0,1,1]
	v_pk_fma_f32 v[4:5], v[4:5], v[56:57], v[6:7] op_sel_hi:[0,1,1]
	v_pk_add_f32 v[42:43], v[42:43], v[44:45]
	v_pk_add_f32 v[2:3], v[2:3], v[4:5]
	s_nop 0
	v_add_f32_dpp v42, v42, v42 quad_perm:[1,0,3,2] row_mask:0xf bank_mask:0xf bound_ctrl:1
	v_add_f32_dpp v43, v43, v43 quad_perm:[1,0,3,2] row_mask:0xf bank_mask:0xf bound_ctrl:1
	v_add_f32_dpp v2, v2, v2 quad_perm:[1,0,3,2] row_mask:0xf bank_mask:0xf bound_ctrl:1
	v_add_f32_dpp v3, v3, v3 quad_perm:[1,0,3,2] row_mask:0xf bank_mask:0xf bound_ctrl:1
	v_add_f32_dpp v42, v42, v42 quad_perm:[2,3,0,1] row_mask:0xf bank_mask:0xf bound_ctrl:1
	v_add_f32_dpp v43, v43, v43 quad_perm:[2,3,0,1] row_mask:0xf bank_mask:0xf bound_ctrl:1
	v_add_f32_dpp v2, v2, v2 quad_perm:[2,3,0,1] row_mask:0xf bank_mask:0xf bound_ctrl:1
	v_add_f32_dpp v3, v3, v3 quad_perm:[2,3,0,1] row_mask:0xf bank_mask:0xf bound_ctrl:1
	v_add_f32_dpp v42, v42, v42 row_half_mirror row_mask:0xf bank_mask:0xf bound_ctrl:1
	v_add_f32_dpp v43, v43, v43 row_half_mirror row_mask:0xf bank_mask:0xf bound_ctrl:1
	v_add_f32_dpp v2, v2, v2 row_half_mirror row_mask:0xf bank_mask:0xf bound_ctrl:1
	v_add_f32_dpp v3, v3, v3 row_half_mirror row_mask:0xf bank_mask:0xf bound_ctrl:1
	v_add_f32_dpp v42, v42, v42 row_mirror row_mask:0xf bank_mask:0xf bound_ctrl:1
	v_add_f32_dpp v43, v43, v43 row_mirror row_mask:0xf bank_mask:0xf bound_ctrl:1
	s_waitcnt lgkmcnt(1)
	v_pk_mul_f32 v[44:45], v[46:47], v[42:43] op_sel_hi:[0,1]
	v_add_f32_dpp v2, v2, v2 row_mirror row_mask:0xf bank_mask:0xf bound_ctrl:1
	v_add_f32_dpp v3, v3, v3 row_mirror row_mask:0xf bank_mask:0xf bound_ctrl:1
	v_pk_fma_f32 v[44:45], v[34:35], v[54:55], v[44:45] op_sel_hi:[0,1,1] neg_lo:[0,0,1] neg_hi:[0,0,1]
	v_cvt_pk_bf16_f32 v2, v2, v3
	s_waitcnt lgkmcnt(0)
	v_pk_fma_f32 v[54:55], v[38:39], v[58:59], v[44:45] op_sel_hi:[0,1,1]
	v_pk_mul_f32 v[44:45], v[46:47], v[42:43] op_sel:[1,0]
	ds_write_b32 v14, v2 offset:768
	v_pk_fma_f32 v[34:35], v[34:35], v[50:51], v[44:45] op_sel:[1,0,0] neg_lo:[0,0,1] neg_hi:[0,0,1]
	ds_read_b128 v[2:5], v15 offset:12288
	ds_read_b128 v[6:9], v15 offset:12544
	ds_read_b128 v[18:21], v15 offset:12800
	ds_read_b128 v[22:25], v15 offset:13056
	ds_read_b128 v[26:29], v15 offset:13312
	ds_read_b64 v[60:61], v16 offset:13568
	v_pk_fma_f32 v[50:51], v[38:39], v[58:59], v[34:35] op_sel:[1,0,0]
	v_pk_mul_f32 v[34:35], v[48:49], v[42:43] op_sel_hi:[0,1]
	v_pk_fma_f32 v[34:35], v[36:37], v[56:57], v[34:35] op_sel_hi:[0,1,1] neg_lo:[0,0,1] neg_hi:[0,0,1]
	v_mov_b32_e32 v36, v49
	v_pk_fma_f32 v[56:57], v[40:41], v[58:59], v[34:35] op_sel_hi:[0,1,1]
	v_mov_b32_e32 v34, v37
	v_pk_mul_f32 v[36:37], v[36:37], v[42:43] op_sel_hi:[0,1]
	v_pk_fma_f32 v[34:35], v[34:35], v[52:53], v[36:37] op_sel_hi:[0,1,1] neg_lo:[0,0,1] neg_hi:[0,0,1]
	v_mov_b32_e32 v36, v41
	s_waitcnt lgkmcnt(2)
	v_pk_mul_f32 v[62:63], v[22:23], v[50:51] op_sel:[1,0]
	v_pk_fma_f32 v[52:53], v[36:37], v[58:59], v[34:35] op_sel_hi:[0,1,1]
	v_pk_fma_f32 v[22:23], v[22:23], v[54:55], v[62:63] op_sel_hi:[0,1,1]
	v_mov_b32_e32 v62, v25
	v_pk_mul_f32 v[34:35], v[30:31], v[50:51] op_sel:[1,0]
	v_pk_mul_f32 v[62:63], v[62:63], v[52:53] op_sel_hi:[0,1]
	v_pk_fma_f32 v[30:31], v[30:31], v[54:55], v[34:35] op_sel_hi:[0,1,1]
	v_mov_b32_e32 v34, v33
	v_pk_fma_f32 v[24:25], v[24:25], v[56:57], v[62:63] op_sel_hi:[0,1,1]
	v_pk_mul_f32 v[34:35], v[34:35], v[52:53] op_sel_hi:[0,1]
	v_pk_add_f32 v[22:23], v[22:23], v[24:25]
	v_pk_fma_f32 v[32:33], v[32:33], v[56:57], v[34:35] op_sel_hi:[0,1,1]
	s_nop 0
	v_add_f32_dpp v22, v22, v22 quad_perm:[1,0,3,2] row_mask:0xf bank_mask:0xf bound_ctrl:1
	v_add_f32_dpp v23, v23, v23 quad_perm:[1,0,3,2] row_mask:0xf bank_mask:0xf bound_ctrl:1
	v_pk_add_f32 v[30:31], v[30:31], v[32:33]
	v_add_f32_dpp v22, v22, v22 quad_perm:[2,3,0,1] row_mask:0xf bank_mask:0xf bound_ctrl:1
	v_add_f32_dpp v23, v23, v23 quad_perm:[2,3,0,1] row_mask:0xf bank_mask:0xf bound_ctrl:1
	v_add_f32_dpp v30, v30, v30 quad_perm:[1,0,3,2] row_mask:0xf bank_mask:0xf bound_ctrl:1
	v_add_f32_dpp v31, v31, v31 quad_perm:[1,0,3,2] row_mask:0xf bank_mask:0xf bound_ctrl:1
	v_add_f32_dpp v22, v22, v22 row_half_mirror row_mask:0xf bank_mask:0xf bound_ctrl:1
	v_add_f32_dpp v23, v23, v23 row_half_mirror row_mask:0xf bank_mask:0xf bound_ctrl:1
	v_add_f32_dpp v30, v30, v30 quad_perm:[2,3,0,1] row_mask:0xf bank_mask:0xf bound_ctrl:1
	v_add_f32_dpp v31, v31, v31 quad_perm:[2,3,0,1] row_mask:0xf bank_mask:0xf bound_ctrl:1
	v_add_f32_dpp v22, v22, v22 row_mirror row_mask:0xf bank_mask:0xf bound_ctrl:1
	v_add_f32_dpp v23, v23, v23 row_mirror row_mask:0xf bank_mask:0xf bound_ctrl:1
	s_waitcnt lgkmcnt(1)
	v_pk_mul_f32 v[24:25], v[26:27], v[22:23] op_sel_hi:[0,1]
	v_add_f32_dpp v30, v30, v30 row_half_mirror row_mask:0xf bank_mask:0xf bound_ctrl:1
	v_add_f32_dpp v31, v31, v31 row_half_mirror row_mask:0xf bank_mask:0xf bound_ctrl:1
	v_pk_fma_f32 v[24:25], v[6:7], v[54:55], v[24:25] op_sel_hi:[0,1,1] neg_lo:[0,0,1] neg_hi:[0,0,1]
	v_add_f32_dpp v30, v30, v30 row_mirror row_mask:0xf bank_mask:0xf bound_ctrl:1
	v_add_f32_dpp v31, v31, v31 row_mirror row_mask:0xf bank_mask:0xf bound_ctrl:1
	s_waitcnt lgkmcnt(0)
; #define LAS __attribute__((address_space(3)))
; DI unsigned pk2(float a, float b) { f32x2 v = {a, b}; bf2_t r = __builtin_convertvector(v, bf2_t); return __builtin_bit_cast(unsigned, r); }
; DI f32x2 red16p(f32x2 x) { float a = x.x, b = x.y; red16x2(a, b); return (f32x2){a, b}; }
; DI void scan_bh2(const Args& a, int l, int bh, int halfsel, LAS unsigned char* lds) {
;     ...
;             for (int st = 0; st < T; ++st) {
;                 f32x4 nr4, nd4, nk4, nkk4, nb4; f32x2 nv2;
;                 if (st < T - 1) {
;                     const LAS float* o = cur + (st + 1) * 384;
;                     nr4 = *(const LAS f32x4*)(o + kq * 4); nd4 = *(const LAS f32x4*)(o + 64 + kq * 4); nk4 = *(const LAS f32x4*)(o + 128 + kq * 4);
;                     nkk4 = *(const LAS f32x4*)(o + 192 + kq * 4); nb4 = *(const LAS f32x4*)(o + 256 + kq * 4); nv2 = *(const LAS f32x2*)(o + 320 + row0);
;                 }
;                 f32x2 sa = S[0] * kk4[0]; sa += S[1] * kk4[1]; f32x2 sb = S[2] * kk4[2]; sb += S[3] * kk4[3]; sa += sb;
;                 sa = red16p(sa); sa = -sa;
; #pragma unroll
;                 for (int j = 0; j < 4; ++j) S[j] = S[j] * d4[j] + sa * b4[j] + v2 * k4[j];
;                 f32x2 y = S[0] * r4[0]; y += S[1] * r4[1]; f32x2 yc = S[2] * r4[2]; yc += S[3] * r4[3]; y += yc;
;                 y = red16p(y);
;                 *(LAS unsigned*)(yb + st * 128 + row0 * 2) = pk2(y.x, y.y);
;                 if (st < T - 1) { r4 = nr4; d4 = nd4; k4 = nk4; kk4 = nkk4; b4 = nb4; v2 = nv2; }
;             }
	v_pk_fma_f32 v[54:55], v[18:19], v[60:61], v[24:25] op_sel_hi:[0,1,1]
	v_cvt_pk_bf16_f32 v17, v30, v31
	v_pk_mul_f32 v[24:25], v[26:27], v[22:23] op_sel:[1,0]
	ds_write_b32 v14, v17 offset:896
	v_pk_fma_f32 v[6:7], v[6:7], v[50:51], v[24:25] op_sel:[1,0,0] neg_lo:[0,0,1] neg_hi:[0,0,1]
	ds_read_b128 v[30:33], v15 offset:13824
	ds_read_b128 v[34:37], v15 offset:14080
	ds_read_b128 v[38:41], v15 offset:14336
	ds_read_b128 v[42:45], v15 offset:14592
	ds_read_b128 v[46:49], v15 offset:14848
	ds_read_b64 v[58:59], v16 offset:15104
	v_pk_fma_f32 v[50:51], v[18:19], v[60:61], v[6:7] op_sel:[1,0,0]
	v_pk_mul_f32 v[6:7], v[28:29], v[22:23] op_sel_hi:[0,1]
	v_pk_fma_f32 v[6:7], v[8:9], v[56:57], v[6:7] op_sel_hi:[0,1,1] neg_lo:[0,0,1] neg_hi:[0,0,1]
	v_mov_b32_e32 v8, v29
	v_pk_fma_f32 v[56:57], v[20:21], v[60:61], v[6:7] op_sel_hi:[0,1,1]
	v_mov_b32_e32 v6, v9
	v_pk_mul_f32 v[8:9], v[8:9], v[22:23] op_sel_hi:[0,1]
	v_pk_fma_f32 v[6:7], v[6:7], v[52:53], v[8:9] op_sel_hi:[0,1,1] neg_lo:[0,0,1] neg_hi:[0,0,1]
	v_mov_b32_e32 v8, v21
	s_waitcnt lgkmcnt(2)
	v_pk_mul_f32 v[62:63], v[42:43], v[50:51] op_sel:[1,0]
	v_pk_fma_f32 v[52:53], v[8:9], v[60:61], v[6:7] op_sel_hi:[0,1,1]
	v_pk_mul_f32 v[6:7], v[2:3], v[50:51] op_sel:[1,0]
	v_pk_fma_f32 v[42:43], v[42:43], v[54:55], v[62:63] op_sel_hi:[0,1,1]
	v_mov_b32_e32 v62, v45
	v_pk_fma_f32 v[2:3], v[2:3], v[54:55], v[6:7] op_sel_hi:[0,1,1]
	v_mov_b32_e32 v6, v5
	v_pk_mul_f32 v[62:63], v[62:63], v[52:53] op_sel_hi:[0,1]
	v_pk_mul_f32 v[6:7], v[6:7], v[52:53] op_sel_hi:[0,1]
	v_pk_fma_f32 v[44:45], v[44:45], v[56:57], v[62:63] op_sel_hi:[0,1,1]
	v_pk_fma_f32 v[4:5], v[4:5], v[56:57], v[6:7] op_sel_hi:[0,1,1]
	v_pk_add_f32 v[42:43], v[42:43], v[44:45]
	v_pk_add_f32 v[2:3], v[2:3], v[4:5]
	s_nop 0
	v_add_f32_dpp v42, v42, v42 quad_perm:[1,0,3,2] row_mask:0xf bank_mask:0xf bound_ctrl:1
	v_add_f32_dpp v43, v43, v43 quad_perm:[1,0,3,2] row_mask:0xf bank_mask:0xf bound_ctrl:1
	v_add_f32_dpp v2, v2, v2 quad_perm:[1,0,3,2] row_mask:0xf bank_mask:0xf bound_ctrl:1
	v_add_f32_dpp v3, v3, v3 quad_perm:[1,0,3,2] row_mask:0xf bank_mask:0xf bound_ctrl:1
	v_add_f32_dpp v42, v42, v42 quad_perm:[2,3,0,1] row_mask:0xf bank_mask:0xf bound_ctrl:1
	v_add_f32_dpp v43, v43, v43 quad_perm:[2,3,0,1] row_mask:0xf bank_mask:0xf bound_ctrl:1
	v_add_f32_dpp v2, v2, v2 quad_perm:[2,3,0,1] row_mask:0xf bank_mask:0xf bound_ctrl:1
	v_add_f32_dpp v3, v3, v3 quad_perm:[2,3,0,1] row_mask:0xf bank_mask:0xf bound_ctrl:1
	v_add_f32_dpp v42, v42, v42 row_half_mirror row_mask:0xf bank_mask:0xf bound_ctrl:1
	v_add_f32_dpp v43, v43, v43 row_half_mirror row_mask:0xf bank_mask:0xf bound_ctrl:1
	v_add_f32_dpp v2, v2, v2 row_half_mirror row_mask:0xf bank_mask:0xf bound_ctrl:1
	v_add_f32_dpp v3, v3, v3 row_half_mirror row_mask:0xf bank_mask:0xf bound_ctrl:1
	v_add_f32_dpp v42, v42, v42 row_mirror row_mask:0xf bank_mask:0xf bound_ctrl:1
	v_add_f32_dpp v43, v43, v43 row_mirror row_mask:0xf bank_mask:0xf bound_ctrl:1
	s_waitcnt lgkmcnt(1)
	v_pk_mul_f32 v[44:45], v[46:47], v[42:43] op_sel_hi:[0,1]
	v_add_f32_dpp v2, v2, v2 row_mirror row_mask:0xf bank_mask:0xf bound_ctrl:1
	v_add_f32_dpp v3, v3, v3 row_mirror row_mask:0xf bank_mask:0xf bound_ctrl:1
	v_pk_fma_f32 v[44:45], v[34:35], v[54:55], v[44:45] op_sel_hi:[0,1,1] neg_lo:[0,0,1] neg_hi:[0,0,1]
	v_cvt_pk_bf16_f32 v2, v2, v3
	s_waitcnt lgkmcnt(0)
	v_pk_fma_f32 v[54:55], v[38:39], v[58:59], v[44:45] op_sel_hi:[0,1,1]
	v_pk_mul_f32 v[44:45], v[46:47], v[42:43] op_sel:[1,0]
	ds_write_b32 v14, v2 offset:1024
	v_pk_fma_f32 v[34:35], v[34:35], v[50:51], v[44:45] op_sel:[1,0,0] neg_lo:[0,0,1] neg_hi:[0,0,1]
	ds_read_b128 v[2:5], v15 offset:15360
	ds_read_b128 v[6:9], v15 offset:15616
	ds_read_b128 v[18:21], v15 offset:15872
	ds_read_b128 v[22:25], v15 offset:16128
	ds_read_b128 v[26:29], v15 offset:16384
	ds_read_b64 v[60:61], v16 offset:16640
	v_pk_fma_f32 v[50:51], v[38:39], v[58:59], v[34:35] op_sel:[1,0,0]
	v_pk_mul_f32 v[34:35], v[48:49], v[42:43] op_sel_hi:[0,1]
	v_pk_fma_f32 v[34:35], v[36:37], v[56:57], v[34:35] op_sel_hi:[0,1,1] neg_lo:[0,0,1] neg_hi:[0,0,1]
	v_mov_b32_e32 v36, v49
	v_pk_fma_f32 v[56:57], v[40:41], v[58:59], v[34:35] op_sel_hi:[0,1,1]
	v_mov_b32_e32 v34, v37
	v_pk_mul_f32 v[36:37], v[36:37], v[42:43] op_sel_hi:[0,1]
	v_pk_fma_f32 v[34:35], v[34:35], v[52:53], v[36:37] op_sel_hi:[0,1,1] neg_lo:[0,0,1] neg_hi:[0,0,1]
	v_mov_b32_e32 v36, v41
	s_waitcnt lgkmcnt(2)
	v_pk_mul_f32 v[62:63], v[22:23], v[50:51] op_sel:[1,0]
	v_pk_fma_f32 v[52:53], v[36:37], v[58:59], v[34:35] op_sel_hi:[0,1,1]
	v_pk_fma_f32 v[22:23], v[22:23], v[54:55], v[62:63] op_sel_hi:[0,1,1]
	v_mov_b32_e32 v62, v25
	v_pk_mul_f32 v[34:35], v[30:31], v[50:51] op_sel:[1,0]
	v_pk_mul_f32 v[62:63], v[62:63], v[52:53] op_sel_hi:[0,1]
	v_pk_fma_f32 v[30:31], v[30:31], v[54:55], v[34:35] op_sel_hi:[0,1,1]
	v_mov_b32_e32 v34, v33
	v_pk_fma_f32 v[24:25], v[24:25], v[56:57], v[62:63] op_sel_hi:[0,1,1]
	v_pk_mul_f32 v[34:35], v[34:35], v[52:53] op_sel_hi:[0,1]
	v_pk_add_f32 v[22:23], v[22:23], v[24:25]
	v_pk_fma_f32 v[32:33], v[32:33], v[56:57], v[34:35] op_sel_hi:[0,1,1]
	s_nop 0
	v_add_f32_dpp v22, v22, v22 quad_perm:[1,0,3,2] row_mask:0xf bank_mask:0xf bound_ctrl:1
	v_add_f32_dpp v23, v23, v23 quad_perm:[1,0,3,2] row_mask:0xf bank_mask:0xf bound_ctrl:1
	v_pk_add_f32 v[30:31], v[30:31], v[32:33]
	v_add_f32_dpp v22, v22, v22 quad_perm:[2,3,0,1] row_mask:0xf bank_mask:0xf bound_ctrl:1
	v_add_f32_dpp v23, v23, v23 quad_perm:[2,3,0,1] row_mask:0xf bank_mask:0xf bound_ctrl:1
	v_add_f32_dpp v30, v30, v30 quad_perm:[1,0,3,2] row_mask:0xf bank_mask:0xf bound_ctrl:1
	v_add_f32_dpp v31, v31, v31 quad_perm:[1,0,3,2] row_mask:0xf bank_mask:0xf bound_ctrl:1
	v_add_f32_dpp v22, v22, v22 row_half_mirror row_mask:0xf bank_mask:0xf bound_ctrl:1
	v_add_f32_dpp v23, v23, v23 row_half_mirror row_mask:0xf bank_mask:0xf bound_ctrl:1
	v_add_f32_dpp v30, v30, v30 quad_perm:[2,3,0,1] row_mask:0xf bank_mask:0xf bound_ctrl:1
	v_add_f32_dpp v31, v31, v31 quad_perm:[2,3,0,1] row_mask:0xf bank_mask:0xf bound_ctrl:1
	v_add_f32_dpp v22, v22, v22 row_mirror row_mask:0xf bank_mask:0xf bound_ctrl:1
	v_add_f32_dpp v23, v23, v23 row_mirror row_mask:0xf bank_mask:0xf bound_ctrl:1
	s_waitcnt lgkmcnt(1)
; #define LAS __attribute__((address_space(3)))
; DI unsigned pk2(float a, float b) { f32x2 v = {a, b}; bf2_t r = __builtin_convertvector(v, bf2_t); return __builtin_bit_cast(unsigned, r); }
; DI f32x2 red16p(f32x2 x) { float a = x.x, b = x.y; red16x2(a, b); return (f32x2){a, b}; }
; DI void scan_bh2(const Args& a, int l, int bh, int halfsel, LAS unsigned char* lds) {
;     ...
;             for (int st = 0; st < T; ++st) {
;                 f32x4 nr4, nd4, nk4, nkk4, nb4; f32x2 nv2;
;                 if (st < T - 1) {
;                     const LAS float* o = cur + (st + 1) * 384;
;                     nr4 = *(const LAS f32x4*)(o + kq * 4); nd4 = *(const LAS f32x4*)(o + 64 + kq * 4); nk4 = *(const LAS f32x4*)(o + 128 + kq * 4);
;                     nkk4 = *(const LAS f32x4*)(o + 192 + kq * 4); nb4 = *(const LAS f32x4*)(o + 256 + kq * 4); nv2 = *(const LAS f32x2*)(o + 320 + row0);
;                 }
;                 f32x2 sa = S[0] * kk4[0]; sa += S[1] * kk4[1]; f32x2 sb = S[2] * kk4[2]; sb += S[3] * kk4[3]; sa += sb;
;                 sa = red16p(sa); sa = -sa;
; #pragma unroll
;                 for (int j = 0; j < 4; ++j) S[j] = S[j] * d4[j] + sa * b4[j] + v2 * k4[j];
;                 f32x2 y = S[0] * r4[0]; y += S[1] * r4[1]; f32x2 yc = S[2] * r4[2]; yc += S[3] * r4[3]; y += yc;
;                 y = red16p(y);
;                 *(LAS unsigned*)(yb + st * 128 + row0 * 2) = pk2(y.x, y.y);
;                 if (st < T - 1) { r4 = nr4; d4 = nd4; k4 = nk4; kk4 = nkk4; b4 = nb4; v2 = nv2; }
;             }
	v_pk_mul_f32 v[24:25], v[26:27], v[22:23] op_sel_hi:[0,1]
	v_add_f32_dpp v30, v30, v30 row_half_mirror row_mask:0xf bank_mask:0xf bound_ctrl:1
	v_add_f32_dpp v31, v31, v31 row_half_mirror row_mask:0xf bank_mask:0xf bound_ctrl:1
	v_pk_fma_f32 v[24:25], v[6:7], v[54:55], v[24:25] op_sel_hi:[0,1,1] neg_lo:[0,0,1] neg_hi:[0,0,1]
	v_add_f32_dpp v30, v30, v30 row_mirror row_mask:0xf bank_mask:0xf bound_ctrl:1
	v_add_f32_dpp v31, v31, v31 row_mirror row_mask:0xf bank_mask:0xf bound_ctrl:1
	s_waitcnt lgkmcnt(0)
	v_pk_fma_f32 v[54:55], v[18:19], v[60:61], v[24:25] op_sel_hi:[0,1,1]
	v_cvt_pk_bf16_f32 v17, v30, v31
	v_pk_mul_f32 v[24:25], v[26:27], v[22:23] op_sel:[1,0]
	ds_write_b32 v14, v17 offset:1152
	v_pk_fma_f32 v[6:7], v[6:7], v[50:51], v[24:25] op_sel:[1,0,0] neg_lo:[0,0,1] neg_hi:[0,0,1]
	ds_read_b128 v[30:33], v15 offset:16896
	ds_read_b128 v[34:37], v15 offset:17152
	ds_read_b128 v[38:41], v15 offset:17408
	ds_read_b128 v[42:45], v15 offset:17664
	ds_read_b128 v[46:49], v15 offset:17920
	ds_read_b64 v[58:59], v16 offset:18176
	v_pk_fma_f32 v[50:51], v[18:19], v[60:61], v[6:7] op_sel:[1,0,0]
	v_pk_mul_f32 v[6:7], v[28:29], v[22:23] op_sel_hi:[0,1]
	v_pk_fma_f32 v[6:7], v[8:9], v[56:57], v[6:7] op_sel_hi:[0,1,1] neg_lo:[0,0,1] neg_hi:[0,0,1]
	v_mov_b32_e32 v8, v29
	v_pk_fma_f32 v[56:57], v[20:21], v[60:61], v[6:7] op_sel_hi:[0,1,1]
	v_mov_b32_e32 v6, v9
	v_pk_mul_f32 v[8:9], v[8:9], v[22:23] op_sel_hi:[0,1]
	v_pk_fma_f32 v[6:7], v[6:7], v[52:53], v[8:9] op_sel_hi:[0,1,1] neg_lo:[0,0,1] neg_hi:[0,0,1]
	v_mov_b32_e32 v8, v21
	s_waitcnt lgkmcnt(2)
	v_pk_mul_f32 v[62:63], v[42:43], v[50:51] op_sel:[1,0]
	v_pk_fma_f32 v[52:53], v[8:9], v[60:61], v[6:7] op_sel_hi:[0,1,1]
	v_pk_mul_f32 v[6:7], v[2:3], v[50:51] op_sel:[1,0]
	v_pk_fma_f32 v[42:43], v[42:43], v[54:55], v[62:63] op_sel_hi:[0,1,1]
	v_mov_b32_e32 v62, v45
	v_pk_fma_f32 v[2:3], v[2:3], v[54:55], v[6:7] op_sel_hi:[0,1,1]
	v_mov_b32_e32 v6, v5
	v_pk_mul_f32 v[62:63], v[62:63], v[52:53] op_sel_hi:[0,1]
	v_pk_mul_f32 v[6:7], v[6:7], v[52:53] op_sel_hi:[0,1]
	v_pk_fma_f32 v[44:45], v[44:45], v[56:57], v[62:63] op_sel_hi:[0,1,1]
	v_pk_fma_f32 v[4:5], v[4:5], v[56:57], v[6:7] op_sel_hi:[0,1,1]
	v_pk_add_f32 v[42:43], v[42:43], v[44:45]
	v_pk_add_f32 v[2:3], v[2:3], v[4:5]
	s_nop 0
	v_add_f32_dpp v42, v42, v42 quad_perm:[1,0,3,2] row_mask:0xf bank_mask:0xf bound_ctrl:1
	v_add_f32_dpp v43, v43, v43 quad_perm:[1,0,3,2] row_mask:0xf bank_mask:0xf bound_ctrl:1
	v_add_f32_dpp v2, v2, v2 quad_perm:[1,0,3,2] row_mask:0xf bank_mask:0xf bound_ctrl:1
	v_add_f32_dpp v3, v3, v3 quad_perm:[1,0,3,2] row_mask:0xf bank_mask:0xf bound_ctrl:1
	v_add_f32_dpp v42, v42, v42 quad_perm:[2,3,0,1] row_mask:0xf bank_mask:0xf bound_ctrl:1
	v_add_f32_dpp v43, v43, v43 quad_perm:[2,3,0,1] row_mask:0xf bank_mask:0xf bound_ctrl:1
	v_add_f32_dpp v2, v2, v2 quad_perm:[2,3,0,1] row_mask:0xf bank_mask:0xf bound_ctrl:1
	v_add_f32_dpp v3, v3, v3 quad_perm:[2,3,0,1] row_mask:0xf bank_mask:0xf bound_ctrl:1
	v_add_f32_dpp v42, v42, v42 row_half_mirror row_mask:0xf bank_mask:0xf bound_ctrl:1
	v_add_f32_dpp v43, v43, v43 row_half_mirror row_mask:0xf bank_mask:0xf bound_ctrl:1
	v_add_f32_dpp v2, v2, v2 row_half_mirror row_mask:0xf bank_mask:0xf bound_ctrl:1
	v_add_f32_dpp v3, v3, v3 row_half_mirror row_mask:0xf bank_mask:0xf bound_ctrl:1
	v_add_f32_dpp v42, v42, v42 row_mirror row_mask:0xf bank_mask:0xf bound_ctrl:1
	v_add_f32_dpp v43, v43, v43 row_mirror row_mask:0xf bank_mask:0xf bound_ctrl:1
	s_waitcnt lgkmcnt(1)
	v_pk_mul_f32 v[44:45], v[46:47], v[42:43] op_sel_hi:[0,1]
	v_add_f32_dpp v2, v2, v2 row_mirror row_mask:0xf bank_mask:0xf bound_ctrl:1
	v_add_f32_dpp v3, v3, v3 row_mirror row_mask:0xf bank_mask:0xf bound_ctrl:1
	v_pk_fma_f32 v[44:45], v[34:35], v[54:55], v[44:45] op_sel_hi:[0,1,1] neg_lo:[0,0,1] neg_hi:[0,0,1]
	v_cvt_pk_bf16_f32 v2, v2, v3
	s_waitcnt lgkmcnt(0)
	v_pk_fma_f32 v[54:55], v[38:39], v[58:59], v[44:45] op_sel_hi:[0,1,1]
	v_pk_mul_f32 v[44:45], v[46:47], v[42:43] op_sel:[1,0]
	ds_write_b32 v14, v2 offset:1280
	v_pk_fma_f32 v[34:35], v[34:35], v[50:51], v[44:45] op_sel:[1,0,0] neg_lo:[0,0,1] neg_hi:[0,0,1]
	ds_read_b128 v[2:5], v15 offset:18432
	ds_read_b128 v[6:9], v15 offset:18688
	ds_read_b128 v[18:21], v15 offset:18944
	ds_read_b128 v[22:25], v15 offset:19200
	ds_read_b128 v[26:29], v15 offset:19456
	ds_read_b64 v[60:61], v16 offset:19712
	v_pk_fma_f32 v[50:51], v[38:39], v[58:59], v[34:35] op_sel:[1,0,0]
	v_pk_mul_f32 v[34:35], v[48:49], v[42:43] op_sel_hi:[0,1]
	v_pk_fma_f32 v[34:35], v[36:37], v[56:57], v[34:35] op_sel_hi:[0,1,1] neg_lo:[0,0,1] neg_hi:[0,0,1]
	v_mov_b32_e32 v36, v49
	v_pk_fma_f32 v[56:57], v[40:41], v[58:59], v[34:35] op_sel_hi:[0,1,1]
	v_mov_b32_e32 v34, v37
	v_pk_mul_f32 v[36:37], v[36:37], v[42:43] op_sel_hi:[0,1]
	v_pk_fma_f32 v[34:35], v[34:35], v[52:53], v[36:37] op_sel_hi:[0,1,1] neg_lo:[0,0,1] neg_hi:[0,0,1]
	v_mov_b32_e32 v36, v41
	s_waitcnt lgkmcnt(2)
; #define LAS __attribute__((address_space(3)))
; DI unsigned pk2(float a, float b) { f32x2 v = {a, b}; bf2_t r = __builtin_convertvector(v, bf2_t); return __builtin_bit_cast(unsigned, r); }
; DI f32x2 red16p(f32x2 x) { float a = x.x, b = x.y; red16x2(a, b); return (f32x2){a, b}; }
; DI void scan_bh2(const Args& a, int l, int bh, int halfsel, LAS unsigned char* lds) {
;     ...
;             for (int st = 0; st < T; ++st) {
;                 f32x4 nr4, nd4, nk4, nkk4, nb4; f32x2 nv2;
;                 if (st < T - 1) {
;                     const LAS float* o = cur + (st + 1) * 384;
;                     nr4 = *(const LAS f32x4*)(o + kq * 4); nd4 = *(const LAS f32x4*)(o + 64 + kq * 4); nk4 = *(const LAS f32x4*)(o + 128 + kq * 4);
;                     nkk4 = *(const LAS f32x4*)(o + 192 + kq * 4); nb4 = *(const LAS f32x4*)(o + 256 + kq * 4); nv2 = *(const LAS f32x2*)(o + 320 + row0);
;                 }
;                 f32x2 sa = S[0] * kk4[0]; sa += S[1] * kk4[1]; f32x2 sb = S[2] * kk4[2]; sb += S[3] * kk4[3]; sa += sb;
;                 sa = red16p(sa); sa = -sa;
; #pragma unroll
;                 for (int j = 0; j < 4; ++j) S[j] = S[j] * d4[j] + sa * b4[j] + v2 * k4[j];
;                 f32x2 y = S[0] * r4[0]; y += S[1] * r4[1]; f32x2 yc = S[2] * r4[2]; yc += S[3] * r4[3]; y += yc;
;                 y = red16p(y);
;                 *(LAS unsigned*)(yb + st * 128 + row0 * 2) = pk2(y.x, y.y);
;                 if (st < T - 1) { r4 = nr4; d4 = nd4; k4 = nk4; kk4 = nkk4; b4 = nb4; v2 = nv2; }
;             }
	v_pk_mul_f32 v[62:63], v[22:23], v[50:51] op_sel:[1,0]
	v_pk_fma_f32 v[52:53], v[36:37], v[58:59], v[34:35] op_sel_hi:[0,1,1]
	v_pk_fma_f32 v[22:23], v[22:23], v[54:55], v[62:63] op_sel_hi:[0,1,1]
	v_mov_b32_e32 v62, v25
	v_pk_mul_f32 v[34:35], v[30:31], v[50:51] op_sel:[1,0]
	v_pk_mul_f32 v[62:63], v[62:63], v[52:53] op_sel_hi:[0,1]
	v_pk_fma_f32 v[30:31], v[30:31], v[54:55], v[34:35] op_sel_hi:[0,1,1]
	v_mov_b32_e32 v34, v33
	v_pk_fma_f32 v[24:25], v[24:25], v[56:57], v[62:63] op_sel_hi:[0,1,1]
	v_pk_mul_f32 v[34:35], v[34:35], v[52:53] op_sel_hi:[0,1]
	v_pk_add_f32 v[22:23], v[22:23], v[24:25]
	v_pk_fma_f32 v[32:33], v[32:33], v[56:57], v[34:35] op_sel_hi:[0,1,1]
	s_nop 0
	v_add_f32_dpp v22, v22, v22 quad_perm:[1,0,3,2] row_mask:0xf bank_mask:0xf bound_ctrl:1
	v_add_f32_dpp v23, v23, v23 quad_perm:[1,0,3,2] row_mask:0xf bank_mask:0xf bound_ctrl:1
	v_pk_add_f32 v[30:31], v[30:31], v[32:33]
	v_add_f32_dpp v22, v22, v22 quad_perm:[2,3,0,1] row_mask:0xf bank_mask:0xf bound_ctrl:1
	v_add_f32_dpp v23, v23, v23 quad_perm:[2,3,0,1] row_mask:0xf bank_mask:0xf bound_ctrl:1
	v_add_f32_dpp v30, v30, v30 quad_perm:[1,0,3,2] row_mask:0xf bank_mask:0xf bound_ctrl:1
	v_add_f32_dpp v31, v31, v31 quad_perm:[1,0,3,2] row_mask:0xf bank_mask:0xf bound_ctrl:1
	v_add_f32_dpp v22, v22, v22 row_half_mirror row_mask:0xf bank_mask:0xf bound_ctrl:1
	v_add_f32_dpp v23, v23, v23 row_half_mirror row_mask:0xf bank_mask:0xf bound_ctrl:1
	v_add_f32_dpp v30, v30, v30 quad_perm:[2,3,0,1] row_mask:0xf bank_mask:0xf bound_ctrl:1
	v_add_f32_dpp v31, v31, v31 quad_perm:[2,3,0,1] row_mask:0xf bank_mask:0xf bound_ctrl:1
	v_add_f32_dpp v22, v22, v22 row_mirror row_mask:0xf bank_mask:0xf bound_ctrl:1
	v_add_f32_dpp v23, v23, v23 row_mirror row_mask:0xf bank_mask:0xf bound_ctrl:1
	s_waitcnt lgkmcnt(1)
	v_pk_mul_f32 v[24:25], v[26:27], v[22:23] op_sel_hi:[0,1]
	v_add_f32_dpp v30, v30, v30 row_half_mirror row_mask:0xf bank_mask:0xf bound_ctrl:1
	v_add_f32_dpp v31, v31, v31 row_half_mirror row_mask:0xf bank_mask:0xf bound_ctrl:1
	v_pk_fma_f32 v[24:25], v[6:7], v[54:55], v[24:25] op_sel_hi:[0,1,1] neg_lo:[0,0,1] neg_hi:[0,0,1]
	v_add_f32_dpp v30, v30, v30 row_mirror row_mask:0xf bank_mask:0xf bound_ctrl:1
	v_add_f32_dpp v31, v31, v31 row_mirror row_mask:0xf bank_mask:0xf bound_ctrl:1
	s_waitcnt lgkmcnt(0)
	v_pk_fma_f32 v[54:55], v[18:19], v[60:61], v[24:25] op_sel_hi:[0,1,1]
	v_cvt_pk_bf16_f32 v17, v30, v31
	v_pk_mul_f32 v[24:25], v[26:27], v[22:23] op_sel:[1,0]
	ds_write_b32 v14, v17 offset:1408
	v_pk_fma_f32 v[6:7], v[6:7], v[50:51], v[24:25] op_sel:[1,0,0] neg_lo:[0,0,1] neg_hi:[0,0,1]
	ds_read_b128 v[30:33], v15 offset:19968
	ds_read_b128 v[34:37], v15 offset:20224
	ds_read_b128 v[38:41], v15 offset:20480
	ds_read_b128 v[42:45], v15 offset:20736
	ds_read_b128 v[46:49], v15 offset:20992
	ds_read_b64 v[58:59], v16 offset:21248
	v_pk_fma_f32 v[50:51], v[18:19], v[60:61], v[6:7] op_sel:[1,0,0]
	v_pk_mul_f32 v[6:7], v[28:29], v[22:23] op_sel_hi:[0,1]
	v_pk_fma_f32 v[6:7], v[8:9], v[56:57], v[6:7] op_sel_hi:[0,1,1] neg_lo:[0,0,1] neg_hi:[0,0,1]
	v_mov_b32_e32 v8, v29
	v_pk_fma_f32 v[56:57], v[20:21], v[60:61], v[6:7] op_sel_hi:[0,1,1]
	v_mov_b32_e32 v6, v9
	v_pk_mul_f32 v[8:9], v[8:9], v[22:23] op_sel_hi:[0,1]
	v_pk_fma_f32 v[6:7], v[6:7], v[52:53], v[8:9] op_sel_hi:[0,1,1] neg_lo:[0,0,1] neg_hi:[0,0,1]
	v_mov_b32_e32 v8, v21
	s_waitcnt lgkmcnt(2)
	v_pk_mul_f32 v[62:63], v[42:43], v[50:51] op_sel:[1,0]
	v_pk_fma_f32 v[52:53], v[8:9], v[60:61], v[6:7] op_sel_hi:[0,1,1]
	v_pk_mul_f32 v[6:7], v[2:3], v[50:51] op_sel:[1,0]
	v_pk_fma_f32 v[42:43], v[42:43], v[54:55], v[62:63] op_sel_hi:[0,1,1]
	v_mov_b32_e32 v62, v45
	v_pk_fma_f32 v[2:3], v[2:3], v[54:55], v[6:7] op_sel_hi:[0,1,1]
	v_mov_b32_e32 v6, v5
	v_pk_mul_f32 v[62:63], v[62:63], v[52:53] op_sel_hi:[0,1]
	v_pk_mul_f32 v[6:7], v[6:7], v[52:53] op_sel_hi:[0,1]
	v_pk_fma_f32 v[44:45], v[44:45], v[56:57], v[62:63] op_sel_hi:[0,1,1]
	v_pk_fma_f32 v[4:5], v[4:5], v[56:57], v[6:7] op_sel_hi:[0,1,1]
	v_pk_add_f32 v[42:43], v[42:43], v[44:45]
	v_pk_add_f32 v[2:3], v[2:3], v[4:5]
	s_nop 0
	v_add_f32_dpp v42, v42, v42 quad_perm:[1,0,3,2] row_mask:0xf bank_mask:0xf bound_ctrl:1
	v_add_f32_dpp v43, v43, v43 quad_perm:[1,0,3,2] row_mask:0xf bank_mask:0xf bound_ctrl:1
	v_add_f32_dpp v2, v2, v2 quad_perm:[1,0,3,2] row_mask:0xf bank_mask:0xf bound_ctrl:1
	v_add_f32_dpp v3, v3, v3 quad_perm:[1,0,3,2] row_mask:0xf bank_mask:0xf bound_ctrl:1
	v_add_f32_dpp v42, v42, v42 quad_perm:[2,3,0,1] row_mask:0xf bank_mask:0xf bound_ctrl:1
	v_add_f32_dpp v43, v43, v43 quad_perm:[2,3,0,1] row_mask:0xf bank_mask:0xf bound_ctrl:1
	v_add_f32_dpp v2, v2, v2 quad_perm:[2,3,0,1] row_mask:0xf bank_mask:0xf bound_ctrl:1
	v_add_f32_dpp v3, v3, v3 quad_perm:[2,3,0,1] row_mask:0xf bank_mask:0xf bound_ctrl:1
	v_add_f32_dpp v42, v42, v42 row_half_mirror row_mask:0xf bank_mask:0xf bound_ctrl:1
	v_add_f32_dpp v43, v43, v43 row_half_mirror row_mask:0xf bank_mask:0xf bound_ctrl:1
	v_add_f32_dpp v2, v2, v2 row_half_mirror row_mask:0xf bank_mask:0xf bound_ctrl:1
	v_add_f32_dpp v3, v3, v3 row_half_mirror row_mask:0xf bank_mask:0xf bound_ctrl:1
	v_add_f32_dpp v42, v42, v42 row_mirror row_mask:0xf bank_mask:0xf bound_ctrl:1
	v_add_f32_dpp v43, v43, v43 row_mirror row_mask:0xf bank_mask:0xf bound_ctrl:1
	s_waitcnt lgkmcnt(1)
	v_pk_mul_f32 v[44:45], v[46:47], v[42:43] op_sel_hi:[0,1]
	v_add_f32_dpp v2, v2, v2 row_mirror row_mask:0xf bank_mask:0xf bound_ctrl:1
	v_add_f32_dpp v3, v3, v3 row_mirror row_mask:0xf bank_mask:0xf bound_ctrl:1
	v_pk_fma_f32 v[44:45], v[34:35], v[54:55], v[44:45] op_sel_hi:[0,1,1] neg_lo:[0,0,1] neg_hi:[0,0,1]
	v_cvt_pk_bf16_f32 v2, v2, v3
	s_waitcnt lgkmcnt(0)
; #define LAS __attribute__((address_space(3)))
; DI unsigned pk2(float a, float b) { f32x2 v = {a, b}; bf2_t r = __builtin_convertvector(v, bf2_t); return __builtin_bit_cast(unsigned, r); }
; DI f32x2 red16p(f32x2 x) { float a = x.x, b = x.y; red16x2(a, b); return (f32x2){a, b}; }
; DI void scan_bh2(const Args& a, int l, int bh, int halfsel, LAS unsigned char* lds) {
;     ...
;             for (int st = 0; st < T; ++st) {
;                 f32x4 nr4, nd4, nk4, nkk4, nb4; f32x2 nv2;
;                 if (st < T - 1) {
;                     const LAS float* o = cur + (st + 1) * 384;
;                     nr4 = *(const LAS f32x4*)(o + kq * 4); nd4 = *(const LAS f32x4*)(o + 64 + kq * 4); nk4 = *(const LAS f32x4*)(o + 128 + kq * 4);
;                     nkk4 = *(const LAS f32x4*)(o + 192 + kq * 4); nb4 = *(const LAS f32x4*)(o + 256 + kq * 4); nv2 = *(const LAS f32x2*)(o + 320 + row0);
;                 }
;                 f32x2 sa = S[0] * kk4[0]; sa += S[1] * kk4[1]; f32x2 sb = S[2] * kk4[2]; sb += S[3] * kk4[3]; sa += sb;
;                 sa = red16p(sa); sa = -sa;
; #pragma unroll
;                 for (int j = 0; j < 4; ++j) S[j] = S[j] * d4[j] + sa * b4[j] + v2 * k4[j];
;                 f32x2 y = S[0] * r4[0]; y += S[1] * r4[1]; f32x2 yc = S[2] * r4[2]; yc += S[3] * r4[3]; y += yc;
;                 y = red16p(y);
;                 *(LAS unsigned*)(yb + st * 128 + row0 * 2) = pk2(y.x, y.y);
;                 if (st < T - 1) { r4 = nr4; d4 = nd4; k4 = nk4; kk4 = nkk4; b4 = nb4; v2 = nv2; }
;             }
	v_pk_fma_f32 v[54:55], v[38:39], v[58:59], v[44:45] op_sel_hi:[0,1,1]
	v_pk_mul_f32 v[44:45], v[46:47], v[42:43] op_sel:[1,0]
	ds_write_b32 v14, v2 offset:1536
	v_pk_fma_f32 v[34:35], v[34:35], v[50:51], v[44:45] op_sel:[1,0,0] neg_lo:[0,0,1] neg_hi:[0,0,1]
	ds_read_b128 v[2:5], v15 offset:21504
	ds_read_b128 v[6:9], v15 offset:21760
	ds_read_b128 v[18:21], v15 offset:22016
	ds_read_b128 v[22:25], v15 offset:22272
	ds_read_b128 v[26:29], v15 offset:22528
	ds_read_b64 v[60:61], v16 offset:22784
	v_pk_fma_f32 v[50:51], v[38:39], v[58:59], v[34:35] op_sel:[1,0,0]
	v_pk_mul_f32 v[34:35], v[48:49], v[42:43] op_sel_hi:[0,1]
	v_pk_fma_f32 v[34:35], v[36:37], v[56:57], v[34:35] op_sel_hi:[0,1,1] neg_lo:[0,0,1] neg_hi:[0,0,1]
	v_mov_b32_e32 v36, v49
	v_pk_fma_f32 v[56:57], v[40:41], v[58:59], v[34:35] op_sel_hi:[0,1,1]
	v_mov_b32_e32 v34, v37
	v_pk_mul_f32 v[36:37], v[36:37], v[42:43] op_sel_hi:[0,1]
	v_pk_fma_f32 v[34:35], v[34:35], v[52:53], v[36:37] op_sel_hi:[0,1,1] neg_lo:[0,0,1] neg_hi:[0,0,1]
	v_mov_b32_e32 v36, v41
	s_waitcnt lgkmcnt(2)
	v_pk_mul_f32 v[62:63], v[22:23], v[50:51] op_sel:[1,0]
	v_pk_fma_f32 v[52:53], v[36:37], v[58:59], v[34:35] op_sel_hi:[0,1,1]
	v_pk_fma_f32 v[22:23], v[22:23], v[54:55], v[62:63] op_sel_hi:[0,1,1]
	v_mov_b32_e32 v62, v25
	v_pk_mul_f32 v[34:35], v[30:31], v[50:51] op_sel:[1,0]
	v_pk_mul_f32 v[62:63], v[62:63], v[52:53] op_sel_hi:[0,1]
	v_pk_fma_f32 v[30:31], v[30:31], v[54:55], v[34:35] op_sel_hi:[0,1,1]
	v_mov_b32_e32 v34, v33
	v_pk_fma_f32 v[24:25], v[24:25], v[56:57], v[62:63] op_sel_hi:[0,1,1]
	v_pk_mul_f32 v[34:35], v[34:35], v[52:53] op_sel_hi:[0,1]
	v_pk_add_f32 v[22:23], v[22:23], v[24:25]
	v_pk_fma_f32 v[32:33], v[32:33], v[56:57], v[34:35] op_sel_hi:[0,1,1]
	s_nop 0
	v_add_f32_dpp v22, v22, v22 quad_perm:[1,0,3,2] row_mask:0xf bank_mask:0xf bound_ctrl:1
	v_add_f32_dpp v23, v23, v23 quad_perm:[1,0,3,2] row_mask:0xf bank_mask:0xf bound_ctrl:1
	v_pk_add_f32 v[30:31], v[30:31], v[32:33]
	v_add_f32_dpp v22, v22, v22 quad_perm:[2,3,0,1] row_mask:0xf bank_mask:0xf bound_ctrl:1
	v_add_f32_dpp v23, v23, v23 quad_perm:[2,3,0,1] row_mask:0xf bank_mask:0xf bound_ctrl:1
	v_add_f32_dpp v30, v30, v30 quad_perm:[1,0,3,2] row_mask:0xf bank_mask:0xf bound_ctrl:1
	v_add_f32_dpp v31, v31, v31 quad_perm:[1,0,3,2] row_mask:0xf bank_mask:0xf bound_ctrl:1
	v_add_f32_dpp v22, v22, v22 row_half_mirror row_mask:0xf bank_mask:0xf bound_ctrl:1
	v_add_f32_dpp v23, v23, v23 row_half_mirror row_mask:0xf bank_mask:0xf bound_ctrl:1
	v_add_f32_dpp v30, v30, v30 quad_perm:[2,3,0,1] row_mask:0xf bank_mask:0xf bound_ctrl:1
	v_add_f32_dpp v31, v31, v31 quad_perm:[2,3,0,1] row_mask:0xf bank_mask:0xf bound_ctrl:1
	v_add_f32_dpp v22, v22, v22 row_mirror row_mask:0xf bank_mask:0xf bound_ctrl:1
	v_add_f32_dpp v23, v23, v23 row_mirror row_mask:0xf bank_mask:0xf bound_ctrl:1
	s_waitcnt lgkmcnt(1)
	v_pk_mul_f32 v[24:25], v[26:27], v[22:23] op_sel_hi:[0,1]
	v_add_f32_dpp v30, v30, v30 row_half_mirror row_mask:0xf bank_mask:0xf bound_ctrl:1
	v_add_f32_dpp v31, v31, v31 row_half_mirror row_mask:0xf bank_mask:0xf bound_ctrl:1
	v_pk_fma_f32 v[24:25], v[6:7], v[54:55], v[24:25] op_sel_hi:[0,1,1] neg_lo:[0,0,1] neg_hi:[0,0,1]
	v_add_f32_dpp v30, v30, v30 row_mirror row_mask:0xf bank_mask:0xf bound_ctrl:1
	v_add_f32_dpp v31, v31, v31 row_mirror row_mask:0xf bank_mask:0xf bound_ctrl:1
	s_waitcnt lgkmcnt(0)
	v_pk_fma_f32 v[54:55], v[18:19], v[60:61], v[24:25] op_sel_hi:[0,1,1]
	v_cvt_pk_bf16_f32 v17, v30, v31
	v_pk_mul_f32 v[24:25], v[26:27], v[22:23] op_sel:[1,0]
	ds_write_b32 v14, v17 offset:1664
	v_pk_fma_f32 v[6:7], v[6:7], v[50:51], v[24:25] op_sel:[1,0,0] neg_lo:[0,0,1] neg_hi:[0,0,1]
	ds_read_b128 v[30:33], v15 offset:23040
	ds_read_b128 v[34:37], v15 offset:23296
	ds_read_b128 v[38:41], v15 offset:23552
	ds_read_b128 v[42:45], v15 offset:23808
	ds_read_b128 v[46:49], v15 offset:24064
	ds_read_b64 v[58:59], v16 offset:24320
	v_pk_fma_f32 v[50:51], v[18:19], v[60:61], v[6:7] op_sel:[1,0,0]
	v_pk_mul_f32 v[6:7], v[28:29], v[22:23] op_sel_hi:[0,1]
	v_pk_fma_f32 v[6:7], v[8:9], v[56:57], v[6:7] op_sel_hi:[0,1,1] neg_lo:[0,0,1] neg_hi:[0,0,1]
	v_mov_b32_e32 v8, v29
	v_pk_fma_f32 v[56:57], v[20:21], v[60:61], v[6:7] op_sel_hi:[0,1,1]
	v_mov_b32_e32 v6, v9
	v_pk_mul_f32 v[8:9], v[8:9], v[22:23] op_sel_hi:[0,1]
	v_pk_fma_f32 v[6:7], v[6:7], v[52:53], v[8:9] op_sel_hi:[0,1,1] neg_lo:[0,0,1] neg_hi:[0,0,1]
	v_mov_b32_e32 v8, v21
	s_waitcnt lgkmcnt(2)
	v_pk_mul_f32 v[62:63], v[42:43], v[50:51] op_sel:[1,0]
	v_pk_fma_f32 v[52:53], v[8:9], v[60:61], v[6:7] op_sel_hi:[0,1,1]
	v_pk_mul_f32 v[6:7], v[2:3], v[50:51] op_sel:[1,0]
	v_pk_fma_f32 v[42:43], v[42:43], v[54:55], v[62:63] op_sel_hi:[0,1,1]
	v_mov_b32_e32 v62, v45
	v_pk_fma_f32 v[2:3], v[2:3], v[54:55], v[6:7] op_sel_hi:[0,1,1]
	v_mov_b32_e32 v6, v5
	v_pk_mul_f32 v[62:63], v[62:63], v[52:53] op_sel_hi:[0,1]
	v_pk_mul_f32 v[6:7], v[6:7], v[52:53] op_sel_hi:[0,1]
	v_pk_fma_f32 v[44:45], v[44:45], v[56:57], v[62:63] op_sel_hi:[0,1,1]
	v_pk_fma_f32 v[4:5], v[4:5], v[56:57], v[6:7] op_sel_hi:[0,1,1]
	v_pk_add_f32 v[42:43], v[42:43], v[44:45]
	v_pk_add_f32 v[2:3], v[2:3], v[4:5]
	s_nop 0
	v_add_f32_dpp v42, v42, v42 quad_perm:[1,0,3,2] row_mask:0xf bank_mask:0xf bound_ctrl:1
	v_add_f32_dpp v43, v43, v43 quad_perm:[1,0,3,2] row_mask:0xf bank_mask:0xf bound_ctrl:1
	v_add_f32_dpp v2, v2, v2 quad_perm:[1,0,3,2] row_mask:0xf bank_mask:0xf bound_ctrl:1
	v_add_f32_dpp v3, v3, v3 quad_perm:[1,0,3,2] row_mask:0xf bank_mask:0xf bound_ctrl:1
	v_add_f32_dpp v42, v42, v42 quad_perm:[2,3,0,1] row_mask:0xf bank_mask:0xf bound_ctrl:1
	v_add_f32_dpp v43, v43, v43 quad_perm:[2,3,0,1] row_mask:0xf bank_mask:0xf bound_ctrl:1
	v_add_f32_dpp v2, v2, v2 quad_perm:[2,3,0,1] row_mask:0xf bank_mask:0xf bound_ctrl:1
	v_add_f32_dpp v3, v3, v3 quad_perm:[2,3,0,1] row_mask:0xf bank_mask:0xf bound_ctrl:1
	v_add_f32_dpp v42, v42, v42 row_half_mirror row_mask:0xf bank_mask:0xf bound_ctrl:1
	v_add_f32_dpp v43, v43, v43 row_half_mirror row_mask:0xf bank_mask:0xf bound_ctrl:1
	v_add_f32_dpp v2, v2, v2 row_half_mirror row_mask:0xf bank_mask:0xf bound_ctrl:1
	v_add_f32_dpp v3, v3, v3 row_half_mirror row_mask:0xf bank_mask:0xf bound_ctrl:1
	v_add_f32_dpp v42, v42, v42 row_mirror row_mask:0xf bank_mask:0xf bound_ctrl:1
	v_add_f32_dpp v43, v43, v43 row_mirror row_mask:0xf bank_mask:0xf bound_ctrl:1
	s_waitcnt lgkmcnt(1)
; #define LAS __attribute__((address_space(3)))
; DI unsigned pk2(float a, float b) { f32x2 v = {a, b}; bf2_t r = __builtin_convertvector(v, bf2_t); return __builtin_bit_cast(unsigned, r); }
; DI f32x2 red16p(f32x2 x) { float a = x.x, b = x.y; red16x2(a, b); return (f32x2){a, b}; }
; DI void scan_bh2(const Args& a, int l, int bh, int halfsel, LAS unsigned char* lds) {
;     ...
;             for (int st = 0; st < T; ++st) {
;                 f32x4 nr4, nd4, nk4, nkk4, nb4; f32x2 nv2;
;                 if (st < T - 1) {
;                     const LAS float* o = cur + (st + 1) * 384;
;                     nr4 = *(const LAS f32x4*)(o + kq * 4); nd4 = *(const LAS f32x4*)(o + 64 + kq * 4); nk4 = *(const LAS f32x4*)(o + 128 + kq * 4);
;                     nkk4 = *(const LAS f32x4*)(o + 192 + kq * 4); nb4 = *(const LAS f32x4*)(o + 256 + kq * 4); nv2 = *(const LAS f32x2*)(o + 320 + row0);
;                 }
;                 f32x2 sa = S[0] * kk4[0]; sa += S[1] * kk4[1]; f32x2 sb = S[2] * kk4[2]; sb += S[3] * kk4[3]; sa += sb;
;                 sa = red16p(sa); sa = -sa;
; #pragma unroll
;                 for (int j = 0; j < 4; ++j) S[j] = S[j] * d4[j] + sa * b4[j] + v2 * k4[j];
;                 f32x2 y = S[0] * r4[0]; y += S[1] * r4[1]; f32x2 yc = S[2] * r4[2]; yc += S[3] * r4[3]; y += yc;
;                 y = red16p(y);
;                 *(LAS unsigned*)(yb + st * 128 + row0 * 2) = pk2(y.x, y.y);
;                 if (st < T - 1) { r4 = nr4; d4 = nd4; k4 = nk4; kk4 = nkk4; b4 = nb4; v2 = nv2; }
;             }
	v_pk_mul_f32 v[44:45], v[46:47], v[42:43] op_sel_hi:[0,1]
	v_add_f32_dpp v2, v2, v2 row_mirror row_mask:0xf bank_mask:0xf bound_ctrl:1
	v_add_f32_dpp v3, v3, v3 row_mirror row_mask:0xf bank_mask:0xf bound_ctrl:1
	v_pk_fma_f32 v[44:45], v[34:35], v[54:55], v[44:45] op_sel_hi:[0,1,1] neg_lo:[0,0,1] neg_hi:[0,0,1]
	v_cvt_pk_bf16_f32 v2, v2, v3
	s_waitcnt lgkmcnt(0)
	v_pk_fma_f32 v[54:55], v[38:39], v[58:59], v[44:45] op_sel_hi:[0,1,1]
	v_pk_mul_f32 v[44:45], v[46:47], v[42:43] op_sel:[1,0]
	ds_write_b32 v14, v2 offset:1792
	v_pk_fma_f32 v[34:35], v[34:35], v[50:51], v[44:45] op_sel:[1,0,0] neg_lo:[0,0,1] neg_hi:[0,0,1]
	ds_read_b128 v[2:5], v15 offset:24576
	ds_read_b128 v[6:9], v15 offset:24832
	ds_read_b128 v[18:21], v15 offset:25088
	ds_read_b128 v[22:25], v15 offset:25344
	ds_read_b128 v[26:29], v15 offset:25600
	ds_read_b64 v[60:61], v16 offset:25856
	v_pk_fma_f32 v[50:51], v[38:39], v[58:59], v[34:35] op_sel:[1,0,0]
	v_pk_mul_f32 v[34:35], v[48:49], v[42:43] op_sel_hi:[0,1]
	v_pk_fma_f32 v[34:35], v[36:37], v[56:57], v[34:35] op_sel_hi:[0,1,1] neg_lo:[0,0,1] neg_hi:[0,0,1]
	v_mov_b32_e32 v36, v49
	v_pk_fma_f32 v[56:57], v[40:41], v[58:59], v[34:35] op_sel_hi:[0,1,1]
	v_mov_b32_e32 v34, v37
	v_pk_mul_f32 v[36:37], v[36:37], v[42:43] op_sel_hi:[0,1]
	v_pk_fma_f32 v[34:35], v[34:35], v[52:53], v[36:37] op_sel_hi:[0,1,1] neg_lo:[0,0,1] neg_hi:[0,0,1]
	v_mov_b32_e32 v36, v41
	s_waitcnt lgkmcnt(2)
	v_pk_mul_f32 v[62:63], v[22:23], v[50:51] op_sel:[1,0]
	v_pk_fma_f32 v[52:53], v[36:37], v[58:59], v[34:35] op_sel_hi:[0,1,1]
	v_pk_fma_f32 v[22:23], v[22:23], v[54:55], v[62:63] op_sel_hi:[0,1,1]
	v_mov_b32_e32 v62, v25
	v_pk_mul_f32 v[34:35], v[30:31], v[50:51] op_sel:[1,0]
	v_pk_mul_f32 v[62:63], v[62:63], v[52:53] op_sel_hi:[0,1]
	v_pk_fma_f32 v[30:31], v[30:31], v[54:55], v[34:35] op_sel_hi:[0,1,1]
	v_mov_b32_e32 v34, v33
	v_pk_fma_f32 v[24:25], v[24:25], v[56:57], v[62:63] op_sel_hi:[0,1,1]
	v_pk_mul_f32 v[34:35], v[34:35], v[52:53] op_sel_hi:[0,1]
	v_pk_add_f32 v[22:23], v[22:23], v[24:25]
	v_pk_fma_f32 v[32:33], v[32:33], v[56:57], v[34:35] op_sel_hi:[0,1,1]
	s_nop 0
	v_add_f32_dpp v22, v22, v22 quad_perm:[1,0,3,2] row_mask:0xf bank_mask:0xf bound_ctrl:1
	v_add_f32_dpp v23, v23, v23 quad_perm:[1,0,3,2] row_mask:0xf bank_mask:0xf bound_ctrl:1
	v_pk_add_f32 v[30:31], v[30:31], v[32:33]
	v_add_f32_dpp v22, v22, v22 quad_perm:[2,3,0,1] row_mask:0xf bank_mask:0xf bound_ctrl:1
	v_add_f32_dpp v23, v23, v23 quad_perm:[2,3,0,1] row_mask:0xf bank_mask:0xf bound_ctrl:1
	v_add_f32_dpp v30, v30, v30 quad_perm:[1,0,3,2] row_mask:0xf bank_mask:0xf bound_ctrl:1
	v_add_f32_dpp v31, v31, v31 quad_perm:[1,0,3,2] row_mask:0xf bank_mask:0xf bound_ctrl:1
	v_add_f32_dpp v22, v22, v22 row_half_mirror row_mask:0xf bank_mask:0xf bound_ctrl:1
	v_add_f32_dpp v23, v23, v23 row_half_mirror row_mask:0xf bank_mask:0xf bound_ctrl:1
	v_add_f32_dpp v30, v30, v30 quad_perm:[2,3,0,1] row_mask:0xf bank_mask:0xf bound_ctrl:1
	v_add_f32_dpp v31, v31, v31 quad_perm:[2,3,0,1] row_mask:0xf bank_mask:0xf bound_ctrl:1
	v_add_f32_dpp v22, v22, v22 row_mirror row_mask:0xf bank_mask:0xf bound_ctrl:1
	v_add_f32_dpp v23, v23, v23 row_mirror row_mask:0xf bank_mask:0xf bound_ctrl:1
	s_waitcnt lgkmcnt(1)
	v_pk_mul_f32 v[24:25], v[26:27], v[22:23] op_sel_hi:[0,1]
	v_add_f32_dpp v30, v30, v30 row_half_mirror row_mask:0xf bank_mask:0xf bound_ctrl:1
	v_add_f32_dpp v31, v31, v31 row_half_mirror row_mask:0xf bank_mask:0xf bound_ctrl:1
	v_pk_fma_f32 v[24:25], v[6:7], v[54:55], v[24:25] op_sel_hi:[0,1,1] neg_lo:[0,0,1] neg_hi:[0,0,1]
	v_add_f32_dpp v30, v30, v30 row_mirror row_mask:0xf bank_mask:0xf bound_ctrl:1
	v_add_f32_dpp v31, v31, v31 row_mirror row_mask:0xf bank_mask:0xf bound_ctrl:1
	s_waitcnt lgkmcnt(0)
	v_pk_fma_f32 v[54:55], v[18:19], v[60:61], v[24:25] op_sel_hi:[0,1,1]
	v_cvt_pk_bf16_f32 v17, v30, v31
	v_pk_mul_f32 v[24:25], v[26:27], v[22:23] op_sel:[1,0]
	ds_write_b32 v14, v17 offset:1920
	v_pk_fma_f32 v[6:7], v[6:7], v[50:51], v[24:25] op_sel:[1,0,0] neg_lo:[0,0,1] neg_hi:[0,0,1]
	ds_read_b128 v[30:33], v15 offset:26112
	ds_read_b128 v[34:37], v15 offset:26368
	ds_read_b128 v[38:41], v15 offset:26624
	ds_read_b128 v[42:45], v15 offset:26880
	ds_read_b128 v[46:49], v15 offset:27136
	ds_read_b64 v[58:59], v16 offset:27392
	v_pk_fma_f32 v[50:51], v[18:19], v[60:61], v[6:7] op_sel:[1,0,0]
	v_pk_mul_f32 v[6:7], v[28:29], v[22:23] op_sel_hi:[0,1]
	v_pk_fma_f32 v[6:7], v[8:9], v[56:57], v[6:7] op_sel_hi:[0,1,1] neg_lo:[0,0,1] neg_hi:[0,0,1]
	v_mov_b32_e32 v8, v29
	v_pk_fma_f32 v[56:57], v[20:21], v[60:61], v[6:7] op_sel_hi:[0,1,1]
	v_mov_b32_e32 v6, v9
	v_pk_mul_f32 v[8:9], v[8:9], v[22:23] op_sel_hi:[0,1]
	v_pk_fma_f32 v[6:7], v[6:7], v[52:53], v[8:9] op_sel_hi:[0,1,1] neg_lo:[0,0,1] neg_hi:[0,0,1]
	v_mov_b32_e32 v8, v21
	s_waitcnt lgkmcnt(2)
; #define LAS __attribute__((address_space(3)))
; DI unsigned pk2(float a, float b) { f32x2 v = {a, b}; bf2_t r = __builtin_convertvector(v, bf2_t); return __builtin_bit_cast(unsigned, r); }
; DI f32x2 red16p(f32x2 x) { float a = x.x, b = x.y; red16x2(a, b); return (f32x2){a, b}; }
; DI void scan_bh2(const Args& a, int l, int bh, int halfsel, LAS unsigned char* lds) {
;     ...
;             for (int st = 0; st < T; ++st) {
;                 f32x4 nr4, nd4, nk4, nkk4, nb4; f32x2 nv2;
;                 if (st < T - 1) {
;                     const LAS float* o = cur + (st + 1) * 384;
;                     nr4 = *(const LAS f32x4*)(o + kq * 4); nd4 = *(const LAS f32x4*)(o + 64 + kq * 4); nk4 = *(const LAS f32x4*)(o + 128 + kq * 4);
;                     nkk4 = *(const LAS f32x4*)(o + 192 + kq * 4); nb4 = *(const LAS f32x4*)(o + 256 + kq * 4); nv2 = *(const LAS f32x2*)(o + 320 + row0);
;                 }
;                 f32x2 sa = S[0] * kk4[0]; sa += S[1] * kk4[1]; f32x2 sb = S[2] * kk4[2]; sb += S[3] * kk4[3]; sa += sb;
;                 sa = red16p(sa); sa = -sa;
; #pragma unroll
;                 for (int j = 0; j < 4; ++j) S[j] = S[j] * d4[j] + sa * b4[j] + v2 * k4[j];
;                 f32x2 y = S[0] * r4[0]; y += S[1] * r4[1]; f32x2 yc = S[2] * r4[2]; yc += S[3] * r4[3]; y += yc;
;                 y = red16p(y);
;                 *(LAS unsigned*)(yb + st * 128 + row0 * 2) = pk2(y.x, y.y);
;                 if (st < T - 1) { r4 = nr4; d4 = nd4; k4 = nk4; kk4 = nkk4; b4 = nb4; v2 = nv2; }
;             }
	v_pk_mul_f32 v[62:63], v[42:43], v[50:51] op_sel:[1,0]
	v_pk_fma_f32 v[52:53], v[8:9], v[60:61], v[6:7] op_sel_hi:[0,1,1]
	v_pk_mul_f32 v[6:7], v[2:3], v[50:51] op_sel:[1,0]
	v_pk_fma_f32 v[42:43], v[42:43], v[54:55], v[62:63] op_sel_hi:[0,1,1]
	v_mov_b32_e32 v62, v45
	v_pk_fma_f32 v[2:3], v[2:3], v[54:55], v[6:7] op_sel_hi:[0,1,1]
	v_mov_b32_e32 v6, v5
	v_pk_mul_f32 v[62:63], v[62:63], v[52:53] op_sel_hi:[0,1]
	v_pk_mul_f32 v[6:7], v[6:7], v[52:53] op_sel_hi:[0,1]
	v_pk_fma_f32 v[44:45], v[44:45], v[56:57], v[62:63] op_sel_hi:[0,1,1]
	v_pk_fma_f32 v[4:5], v[4:5], v[56:57], v[6:7] op_sel_hi:[0,1,1]
	v_pk_add_f32 v[42:43], v[42:43], v[44:45]
	v_pk_add_f32 v[2:3], v[2:3], v[4:5]
	s_nop 0
	v_add_f32_dpp v42, v42, v42 quad_perm:[1,0,3,2] row_mask:0xf bank_mask:0xf bound_ctrl:1
	v_add_f32_dpp v43, v43, v43 quad_perm:[1,0,3,2] row_mask:0xf bank_mask:0xf bound_ctrl:1
	v_add_f32_dpp v2, v2, v2 quad_perm:[1,0,3,2] row_mask:0xf bank_mask:0xf bound_ctrl:1
	v_add_f32_dpp v3, v3, v3 quad_perm:[1,0,3,2] row_mask:0xf bank_mask:0xf bound_ctrl:1
	v_add_f32_dpp v42, v42, v42 quad_perm:[2,3,0,1] row_mask:0xf bank_mask:0xf bound_ctrl:1
	v_add_f32_dpp v43, v43, v43 quad_perm:[2,3,0,1] row_mask:0xf bank_mask:0xf bound_ctrl:1
	v_add_f32_dpp v2, v2, v2 quad_perm:[2,3,0,1] row_mask:0xf bank_mask:0xf bound_ctrl:1
	v_add_f32_dpp v3, v3, v3 quad_perm:[2,3,0,1] row_mask:0xf bank_mask:0xf bound_ctrl:1
	v_add_f32_dpp v42, v42, v42 row_half_mirror row_mask:0xf bank_mask:0xf bound_ctrl:1
	v_add_f32_dpp v43, v43, v43 row_half_mirror row_mask:0xf bank_mask:0xf bound_ctrl:1
	v_add_f32_dpp v2, v2, v2 row_half_mirror row_mask:0xf bank_mask:0xf bound_ctrl:1
	v_add_f32_dpp v3, v3, v3 row_half_mirror row_mask:0xf bank_mask:0xf bound_ctrl:1
	v_add_f32_dpp v42, v42, v42 row_mirror row_mask:0xf bank_mask:0xf bound_ctrl:1
	v_add_f32_dpp v43, v43, v43 row_mirror row_mask:0xf bank_mask:0xf bound_ctrl:1
	s_waitcnt lgkmcnt(1)
	v_pk_mul_f32 v[44:45], v[46:47], v[42:43] op_sel_hi:[0,1]
	v_add_f32_dpp v2, v2, v2 row_mirror row_mask:0xf bank_mask:0xf bound_ctrl:1
	v_add_f32_dpp v3, v3, v3 row_mirror row_mask:0xf bank_mask:0xf bound_ctrl:1
	v_pk_fma_f32 v[44:45], v[34:35], v[54:55], v[44:45] op_sel_hi:[0,1,1] neg_lo:[0,0,1] neg_hi:[0,0,1]
	v_cvt_pk_bf16_f32 v2, v2, v3
	s_waitcnt lgkmcnt(0)
	v_pk_fma_f32 v[54:55], v[38:39], v[58:59], v[44:45] op_sel_hi:[0,1,1]
	v_pk_mul_f32 v[44:45], v[46:47], v[42:43] op_sel:[1,0]
	ds_write_b32 v14, v2 offset:2048
	v_pk_fma_f32 v[34:35], v[34:35], v[50:51], v[44:45] op_sel:[1,0,0] neg_lo:[0,0,1] neg_hi:[0,0,1]
	ds_read_b128 v[2:5], v15 offset:27648
	ds_read_b128 v[6:9], v15 offset:27904
	ds_read_b128 v[18:21], v15 offset:28160
	ds_read_b128 v[22:25], v15 offset:28416
	ds_read_b128 v[26:29], v15 offset:28672
	ds_read_b64 v[60:61], v16 offset:28928
	v_pk_fma_f32 v[50:51], v[38:39], v[58:59], v[34:35] op_sel:[1,0,0]
	v_pk_mul_f32 v[34:35], v[48:49], v[42:43] op_sel_hi:[0,1]
	v_pk_fma_f32 v[34:35], v[36:37], v[56:57], v[34:35] op_sel_hi:[0,1,1] neg_lo:[0,0,1] neg_hi:[0,0,1]
	v_mov_b32_e32 v36, v49
	v_pk_fma_f32 v[56:57], v[40:41], v[58:59], v[34:35] op_sel_hi:[0,1,1]
	v_mov_b32_e32 v34, v37
	v_pk_mul_f32 v[36:37], v[36:37], v[42:43] op_sel_hi:[0,1]
	v_pk_fma_f32 v[34:35], v[34:35], v[52:53], v[36:37] op_sel_hi:[0,1,1] neg_lo:[0,0,1] neg_hi:[0,0,1]
	v_mov_b32_e32 v36, v41
	s_waitcnt lgkmcnt(2)
	v_pk_mul_f32 v[62:63], v[22:23], v[50:51] op_sel:[1,0]
	v_pk_fma_f32 v[52:53], v[36:37], v[58:59], v[34:35] op_sel_hi:[0,1,1]
	v_pk_fma_f32 v[22:23], v[22:23], v[54:55], v[62:63] op_sel_hi:[0,1,1]
	v_mov_b32_e32 v62, v25
	v_pk_mul_f32 v[34:35], v[30:31], v[50:51] op_sel:[1,0]
	v_pk_mul_f32 v[62:63], v[62:63], v[52:53] op_sel_hi:[0,1]
	v_pk_fma_f32 v[30:31], v[30:31], v[54:55], v[34:35] op_sel_hi:[0,1,1]
	v_mov_b32_e32 v34, v33
	v_pk_fma_f32 v[24:25], v[24:25], v[56:57], v[62:63] op_sel_hi:[0,1,1]
	v_pk_mul_f32 v[34:35], v[34:35], v[52:53] op_sel_hi:[0,1]
	v_pk_add_f32 v[22:23], v[22:23], v[24:25]
	v_pk_fma_f32 v[32:33], v[32:33], v[56:57], v[34:35] op_sel_hi:[0,1,1]
	s_nop 0
	v_add_f32_dpp v22, v22, v22 quad_perm:[1,0,3,2] row_mask:0xf bank_mask:0xf bound_ctrl:1
	v_add_f32_dpp v23, v23, v23 quad_perm:[1,0,3,2] row_mask:0xf bank_mask:0xf bound_ctrl:1
	v_pk_add_f32 v[30:31], v[30:31], v[32:33]
	v_add_f32_dpp v22, v22, v22 quad_perm:[2,3,0,1] row_mask:0xf bank_mask:0xf bound_ctrl:1
	v_add_f32_dpp v23, v23, v23 quad_perm:[2,3,0,1] row_mask:0xf bank_mask:0xf bound_ctrl:1
	v_add_f32_dpp v30, v30, v30 quad_perm:[1,0,3,2] row_mask:0xf bank_mask:0xf bound_ctrl:1
	v_add_f32_dpp v31, v31, v31 quad_perm:[1,0,3,2] row_mask:0xf bank_mask:0xf bound_ctrl:1
	v_add_f32_dpp v22, v22, v22 row_half_mirror row_mask:0xf bank_mask:0xf bound_ctrl:1
	v_add_f32_dpp v23, v23, v23 row_half_mirror row_mask:0xf bank_mask:0xf bound_ctrl:1
	v_add_f32_dpp v30, v30, v30 quad_perm:[2,3,0,1] row_mask:0xf bank_mask:0xf bound_ctrl:1
	v_add_f32_dpp v31, v31, v31 quad_perm:[2,3,0,1] row_mask:0xf bank_mask:0xf bound_ctrl:1
	v_add_f32_dpp v22, v22, v22 row_mirror row_mask:0xf bank_mask:0xf bound_ctrl:1
	v_add_f32_dpp v23, v23, v23 row_mirror row_mask:0xf bank_mask:0xf bound_ctrl:1
	s_waitcnt lgkmcnt(1)
	v_pk_mul_f32 v[24:25], v[26:27], v[22:23] op_sel_hi:[0,1]
	v_add_f32_dpp v30, v30, v30 row_half_mirror row_mask:0xf bank_mask:0xf bound_ctrl:1
	v_add_f32_dpp v31, v31, v31 row_half_mirror row_mask:0xf bank_mask:0xf bound_ctrl:1
	v_pk_fma_f32 v[24:25], v[6:7], v[54:55], v[24:25] op_sel_hi:[0,1,1] neg_lo:[0,0,1] neg_hi:[0,0,1]
	v_add_f32_dpp v30, v30, v30 row_mirror row_mask:0xf bank_mask:0xf bound_ctrl:1
	v_add_f32_dpp v31, v31, v31 row_mirror row_mask:0xf bank_mask:0xf bound_ctrl:1
	s_waitcnt lgkmcnt(0)
; #define LAS __attribute__((address_space(3)))
; DI unsigned pk2(float a, float b) { f32x2 v = {a, b}; bf2_t r = __builtin_convertvector(v, bf2_t); return __builtin_bit_cast(unsigned, r); }
; DI f32x2 red16p(f32x2 x) { float a = x.x, b = x.y; red16x2(a, b); return (f32x2){a, b}; }
; DI void scan_bh2(const Args& a, int l, int bh, int halfsel, LAS unsigned char* lds) {
;     ...
;             for (int st = 0; st < T; ++st) {
;                 f32x4 nr4, nd4, nk4, nkk4, nb4; f32x2 nv2;
;                 if (st < T - 1) {
;                     const LAS float* o = cur + (st + 1) * 384;
;                     nr4 = *(const LAS f32x4*)(o + kq * 4); nd4 = *(const LAS f32x4*)(o + 64 + kq * 4); nk4 = *(const LAS f32x4*)(o + 128 + kq * 4);
;                     nkk4 = *(const LAS f32x4*)(o + 192 + kq * 4); nb4 = *(const LAS f32x4*)(o + 256 + kq * 4); nv2 = *(const LAS f32x2*)(o + 320 + row0);
;                 }
;                 f32x2 sa = S[0] * kk4[0]; sa += S[1] * kk4[1]; f32x2 sb = S[2] * kk4[2]; sb += S[3] * kk4[3]; sa += sb;
;                 sa = red16p(sa); sa = -sa;
; #pragma unroll
;                 for (int j = 0; j < 4; ++j) S[j] = S[j] * d4[j] + sa * b4[j] + v2 * k4[j];
;                 f32x2 y = S[0] * r4[0]; y += S[1] * r4[1]; f32x2 yc = S[2] * r4[2]; yc += S[3] * r4[3]; y += yc;
;                 y = red16p(y);
;                 *(LAS unsigned*)(yb + st * 128 + row0 * 2) = pk2(y.x, y.y);
;                 if (st < T - 1) { r4 = nr4; d4 = nd4; k4 = nk4; kk4 = nkk4; b4 = nb4; v2 = nv2; }
;             }
	v_pk_fma_f32 v[54:55], v[18:19], v[60:61], v[24:25] op_sel_hi:[0,1,1]
	v_cvt_pk_bf16_f32 v17, v30, v31
	v_pk_mul_f32 v[24:25], v[26:27], v[22:23] op_sel:[1,0]
	ds_write_b32 v14, v17 offset:2176
	v_pk_fma_f32 v[6:7], v[6:7], v[50:51], v[24:25] op_sel:[1,0,0] neg_lo:[0,0,1] neg_hi:[0,0,1]
	ds_read_b128 v[30:33], v15 offset:29184
	ds_read_b128 v[34:37], v15 offset:29440
	ds_read_b128 v[38:41], v15 offset:29696
	ds_read_b128 v[42:45], v15 offset:29952
	ds_read_b128 v[46:49], v15 offset:30208
	ds_read_b64 v[58:59], v16 offset:30464
	v_pk_fma_f32 v[50:51], v[18:19], v[60:61], v[6:7] op_sel:[1,0,0]
	v_pk_mul_f32 v[6:7], v[28:29], v[22:23] op_sel_hi:[0,1]
	v_pk_fma_f32 v[6:7], v[8:9], v[56:57], v[6:7] op_sel_hi:[0,1,1] neg_lo:[0,0,1] neg_hi:[0,0,1]
	v_mov_b32_e32 v8, v29
	v_pk_fma_f32 v[56:57], v[20:21], v[60:61], v[6:7] op_sel_hi:[0,1,1]
	v_mov_b32_e32 v6, v9
	v_pk_mul_f32 v[8:9], v[8:9], v[22:23] op_sel_hi:[0,1]
	v_pk_fma_f32 v[6:7], v[6:7], v[52:53], v[8:9] op_sel_hi:[0,1,1] neg_lo:[0,0,1] neg_hi:[0,0,1]
	v_mov_b32_e32 v8, v21
	s_waitcnt lgkmcnt(2)
	v_pk_mul_f32 v[62:63], v[42:43], v[50:51] op_sel:[1,0]
	v_pk_fma_f32 v[52:53], v[8:9], v[60:61], v[6:7] op_sel_hi:[0,1,1]
	v_pk_mul_f32 v[6:7], v[2:3], v[50:51] op_sel:[1,0]
	v_pk_fma_f32 v[42:43], v[42:43], v[54:55], v[62:63] op_sel_hi:[0,1,1]
	v_mov_b32_e32 v62, v45
	v_pk_fma_f32 v[2:3], v[2:3], v[54:55], v[6:7] op_sel_hi:[0,1,1]
	v_mov_b32_e32 v6, v5
	v_pk_mul_f32 v[62:63], v[62:63], v[52:53] op_sel_hi:[0,1]
	v_pk_mul_f32 v[6:7], v[6:7], v[52:53] op_sel_hi:[0,1]
	v_pk_fma_f32 v[44:45], v[44:45], v[56:57], v[62:63] op_sel_hi:[0,1,1]
	v_pk_fma_f32 v[4:5], v[4:5], v[56:57], v[6:7] op_sel_hi:[0,1,1]
	v_pk_add_f32 v[42:43], v[42:43], v[44:45]
	v_pk_add_f32 v[2:3], v[2:3], v[4:5]
	s_nop 0
	v_add_f32_dpp v42, v42, v42 quad_perm:[1,0,3,2] row_mask:0xf bank_mask:0xf bound_ctrl:1
	v_add_f32_dpp v43, v43, v43 quad_perm:[1,0,3,2] row_mask:0xf bank_mask:0xf bound_ctrl:1
	v_add_f32_dpp v2, v2, v2 quad_perm:[1,0,3,2] row_mask:0xf bank_mask:0xf bound_ctrl:1
	v_add_f32_dpp v3, v3, v3 quad_perm:[1,0,3,2] row_mask:0xf bank_mask:0xf bound_ctrl:1
	v_add_f32_dpp v42, v42, v42 quad_perm:[2,3,0,1] row_mask:0xf bank_mask:0xf bound_ctrl:1
	v_add_f32_dpp v43, v43, v43 quad_perm:[2,3,0,1] row_mask:0xf bank_mask:0xf bound_ctrl:1
	v_add_f32_dpp v2, v2, v2 quad_perm:[2,3,0,1] row_mask:0xf bank_mask:0xf bound_ctrl:1
	v_add_f32_dpp v3, v3, v3 quad_perm:[2,3,0,1] row_mask:0xf bank_mask:0xf bound_ctrl:1
	v_add_f32_dpp v42, v42, v42 row_half_mirror row_mask:0xf bank_mask:0xf bound_ctrl:1
	v_add_f32_dpp v43, v43, v43 row_half_mirror row_mask:0xf bank_mask:0xf bound_ctrl:1
	v_add_f32_dpp v2, v2, v2 row_half_mirror row_mask:0xf bank_mask:0xf bound_ctrl:1
	v_add_f32_dpp v3, v3, v3 row_half_mirror row_mask:0xf bank_mask:0xf bound_ctrl:1
	v_add_f32_dpp v42, v42, v42 row_mirror row_mask:0xf bank_mask:0xf bound_ctrl:1
	v_add_f32_dpp v43, v43, v43 row_mirror row_mask:0xf bank_mask:0xf bound_ctrl:1
	s_waitcnt lgkmcnt(1)
	v_pk_mul_f32 v[44:45], v[46:47], v[42:43] op_sel_hi:[0,1]
	v_add_f32_dpp v2, v2, v2 row_mirror row_mask:0xf bank_mask:0xf bound_ctrl:1
	v_add_f32_dpp v3, v3, v3 row_mirror row_mask:0xf bank_mask:0xf bound_ctrl:1
	v_pk_fma_f32 v[44:45], v[34:35], v[54:55], v[44:45] op_sel_hi:[0,1,1] neg_lo:[0,0,1] neg_hi:[0,0,1]
	v_cvt_pk_bf16_f32 v2, v2, v3
	s_waitcnt lgkmcnt(0)
	v_pk_fma_f32 v[54:55], v[38:39], v[58:59], v[44:45] op_sel_hi:[0,1,1]
	v_pk_mul_f32 v[44:45], v[46:47], v[42:43] op_sel:[1,0]
	ds_write_b32 v14, v2 offset:2304
	v_pk_fma_f32 v[34:35], v[34:35], v[50:51], v[44:45] op_sel:[1,0,0] neg_lo:[0,0,1] neg_hi:[0,0,1]
	ds_read_b128 v[2:5], v15 offset:30720
	ds_read_b128 v[6:9], v15 offset:30976
	ds_read_b128 v[18:21], v15 offset:31232
	ds_read_b128 v[22:25], v15 offset:31488
	ds_read_b128 v[26:29], v15 offset:31744
	ds_read_b64 v[60:61], v16 offset:32000
	v_pk_fma_f32 v[50:51], v[38:39], v[58:59], v[34:35] op_sel:[1,0,0]
	v_pk_mul_f32 v[34:35], v[48:49], v[42:43] op_sel_hi:[0,1]
	v_pk_fma_f32 v[34:35], v[36:37], v[56:57], v[34:35] op_sel_hi:[0,1,1] neg_lo:[0,0,1] neg_hi:[0,0,1]
	v_mov_b32_e32 v36, v49
	v_pk_fma_f32 v[56:57], v[40:41], v[58:59], v[34:35] op_sel_hi:[0,1,1]
	v_mov_b32_e32 v34, v37
	v_pk_mul_f32 v[36:37], v[36:37], v[42:43] op_sel_hi:[0,1]
	v_pk_fma_f32 v[34:35], v[34:35], v[52:53], v[36:37] op_sel_hi:[0,1,1] neg_lo:[0,0,1] neg_hi:[0,0,1]
	v_mov_b32_e32 v36, v41
	s_waitcnt lgkmcnt(2)
	v_pk_mul_f32 v[62:63], v[22:23], v[50:51] op_sel:[1,0]
	v_pk_fma_f32 v[52:53], v[36:37], v[58:59], v[34:35] op_sel_hi:[0,1,1]
	v_pk_fma_f32 v[22:23], v[22:23], v[54:55], v[62:63] op_sel_hi:[0,1,1]
	v_mov_b32_e32 v62, v25
	v_pk_mul_f32 v[62:63], v[62:63], v[52:53] op_sel_hi:[0,1]
	v_pk_fma_f32 v[24:25], v[24:25], v[56:57], v[62:63] op_sel_hi:[0,1,1]
	v_pk_mul_f32 v[34:35], v[30:31], v[50:51] op_sel:[1,0]
	v_pk_add_f32 v[22:23], v[22:23], v[24:25]
	v_pk_fma_f32 v[30:31], v[30:31], v[54:55], v[34:35] op_sel_hi:[0,1,1]
	v_mov_b32_e32 v34, v33
	v_add_f32_dpp v22, v22, v22 quad_perm:[1,0,3,2] row_mask:0xf bank_mask:0xf bound_ctrl:1
	v_add_f32_dpp v23, v23, v23 quad_perm:[1,0,3,2] row_mask:0xf bank_mask:0xf bound_ctrl:1
	v_pk_mul_f32 v[34:35], v[34:35], v[52:53] op_sel_hi:[0,1]
	v_add_f32_dpp v22, v22, v22 quad_perm:[2,3,0,1] row_mask:0xf bank_mask:0xf bound_ctrl:1
	v_add_f32_dpp v23, v23, v23 quad_perm:[2,3,0,1] row_mask:0xf bank_mask:0xf bound_ctrl:1
	v_pk_fma_f32 v[32:33], v[32:33], v[56:57], v[34:35] op_sel_hi:[0,1,1]
	v_add_f32_dpp v22, v22, v22 row_half_mirror row_mask:0xf bank_mask:0xf bound_ctrl:1
	v_add_f32_dpp v23, v23, v23 row_half_mirror row_mask:0xf bank_mask:0xf bound_ctrl:1
	v_pk_add_f32 v[30:31], v[30:31], v[32:33]
	v_add_f32_dpp v22, v22, v22 row_mirror row_mask:0xf bank_mask:0xf bound_ctrl:1
	v_add_f32_dpp v23, v23, v23 row_mirror row_mask:0xf bank_mask:0xf bound_ctrl:1
	s_waitcnt lgkmcnt(1)
; #define LAS __attribute__((address_space(3)))
; DI unsigned pk2(float a, float b) { f32x2 v = {a, b}; bf2_t r = __builtin_convertvector(v, bf2_t); return __builtin_bit_cast(unsigned, r); }
; DI f32x2 red16p(f32x2 x) { float a = x.x, b = x.y; red16x2(a, b); return (f32x2){a, b}; }
; DI void scan_bh2(const Args& a, int l, int bh, int halfsel, LAS unsigned char* lds) {
;     ...
;             for (int st = 0; st < T; ++st) {
;                 f32x4 nr4, nd4, nk4, nkk4, nb4; f32x2 nv2;
;                 if (st < T - 1) {
;                     const LAS float* o = cur + (st + 1) * 384;
;                     nr4 = *(const LAS f32x4*)(o + kq * 4); nd4 = *(const LAS f32x4*)(o + 64 + kq * 4); nk4 = *(const LAS f32x4*)(o + 128 + kq * 4);
;                     nkk4 = *(const LAS f32x4*)(o + 192 + kq * 4); nb4 = *(const LAS f32x4*)(o + 256 + kq * 4); nv2 = *(const LAS f32x2*)(o + 320 + row0);
;                 }
;                 f32x2 sa = S[0] * kk4[0]; sa += S[1] * kk4[1]; f32x2 sb = S[2] * kk4[2]; sb += S[3] * kk4[3]; sa += sb;
;                 sa = red16p(sa); sa = -sa;
; #pragma unroll
;                 for (int j = 0; j < 4; ++j) S[j] = S[j] * d4[j] + sa * b4[j] + v2 * k4[j];
;                 f32x2 y = S[0] * r4[0]; y += S[1] * r4[1]; f32x2 yc = S[2] * r4[2]; yc += S[3] * r4[3]; y += yc;
;                 y = red16p(y);
;                 *(LAS unsigned*)(yb + st * 128 + row0 * 2) = pk2(y.x, y.y);
;                 if (st < T - 1) { r4 = nr4; d4 = nd4; k4 = nk4; kk4 = nkk4; b4 = nb4; v2 = nv2; }
;             }
	v_pk_mul_f32 v[24:25], v[26:27], v[22:23] op_sel_hi:[0,1]
	v_add_f32_dpp v30, v30, v30 quad_perm:[1,0,3,2] row_mask:0xf bank_mask:0xf bound_ctrl:1
	v_add_f32_dpp v31, v31, v31 quad_perm:[1,0,3,2] row_mask:0xf bank_mask:0xf bound_ctrl:1
	v_pk_fma_f32 v[24:25], v[6:7], v[54:55], v[24:25] op_sel_hi:[0,1,1] neg_lo:[0,0,1] neg_hi:[0,0,1]
	v_add_f32_dpp v30, v30, v30 quad_perm:[2,3,0,1] row_mask:0xf bank_mask:0xf bound_ctrl:1
	v_add_f32_dpp v31, v31, v31 quad_perm:[2,3,0,1] row_mask:0xf bank_mask:0xf bound_ctrl:1
	s_waitcnt lgkmcnt(0)
	v_pk_fma_f32 v[54:55], v[18:19], v[60:61], v[24:25] op_sel_hi:[0,1,1]
	v_pk_mul_f32 v[24:25], v[26:27], v[22:23] op_sel:[1,0]
	v_add_f32_dpp v30, v30, v30 row_half_mirror row_mask:0xf bank_mask:0xf bound_ctrl:1
	v_add_f32_dpp v31, v31, v31 row_half_mirror row_mask:0xf bank_mask:0xf bound_ctrl:1
	s_nop 0
	v_pk_fma_f32 v[6:7], v[6:7], v[50:51], v[24:25] op_sel:[1,0,0] neg_lo:[0,0,1] neg_hi:[0,0,1]
	v_add_f32_dpp v30, v30, v30 row_mirror row_mask:0xf bank_mask:0xf bound_ctrl:1
	v_add_f32_dpp v31, v31, v31 row_mirror row_mask:0xf bank_mask:0xf bound_ctrl:1
	s_nop 0
	v_cvt_pk_bf16_f32 v17, v30, v31
	v_pk_fma_f32 v[50:51], v[18:19], v[60:61], v[6:7] op_sel:[1,0,0]
	v_pk_mul_f32 v[6:7], v[28:29], v[22:23] op_sel_hi:[0,1]
	ds_write_b32 v14, v17 offset:2432
	v_pk_fma_f32 v[6:7], v[8:9], v[56:57], v[6:7] op_sel_hi:[0,1,1] neg_lo:[0,0,1] neg_hi:[0,0,1]
	v_mov_b32_e32 v8, v29
	ds_read_b128 v[30:33], v15 offset:32768
	ds_read_b128 v[34:37], v15 offset:33024
	ds_read_b128 v[38:41], v15 offset:32256
	ds_read_b128 v[42:45], v15 offset:33280
	ds_read_b128 v[46:49], v15 offset:32512
	ds_read_b64 v[58:59], v16 offset:33536
	v_pk_fma_f32 v[56:57], v[20:21], v[60:61], v[6:7] op_sel_hi:[0,1,1]
	v_mov_b32_e32 v6, v9
	v_pk_mul_f32 v[8:9], v[8:9], v[22:23] op_sel_hi:[0,1]
	v_pk_fma_f32 v[6:7], v[6:7], v[52:53], v[8:9] op_sel_hi:[0,1,1] neg_lo:[0,0,1] neg_hi:[0,0,1]
	v_mov_b32_e32 v8, v21
	s_waitcnt lgkmcnt(4)
	v_pk_mul_f32 v[62:63], v[34:35], v[50:51] op_sel:[1,0]
	v_pk_fma_f32 v[52:53], v[8:9], v[60:61], v[6:7] op_sel_hi:[0,1,1]
	v_pk_fma_f32 v[34:35], v[34:35], v[54:55], v[62:63] op_sel_hi:[0,1,1]
	v_mov_b32_e32 v62, v37
	v_pk_mul_f32 v[6:7], v[2:3], v[50:51] op_sel:[1,0]
	v_pk_mul_f32 v[62:63], v[62:63], v[52:53] op_sel_hi:[0,1]
	v_pk_fma_f32 v[2:3], v[2:3], v[54:55], v[6:7] op_sel_hi:[0,1,1]
	v_mov_b32_e32 v6, v5
	v_pk_fma_f32 v[36:37], v[36:37], v[56:57], v[62:63] op_sel_hi:[0,1,1]
	v_pk_mul_f32 v[6:7], v[6:7], v[52:53] op_sel_hi:[0,1]
	v_pk_add_f32 v[34:35], v[34:35], v[36:37]
	v_pk_fma_f32 v[4:5], v[4:5], v[56:57], v[6:7] op_sel_hi:[0,1,1]
	s_nop 0
	v_add_f32_dpp v34, v34, v34 quad_perm:[1,0,3,2] row_mask:0xf bank_mask:0xf bound_ctrl:1
	v_add_f32_dpp v35, v35, v35 quad_perm:[1,0,3,2] row_mask:0xf bank_mask:0xf bound_ctrl:1
	v_pk_add_f32 v[2:3], v[2:3], v[4:5]
	v_add_f32_dpp v34, v34, v34 quad_perm:[2,3,0,1] row_mask:0xf bank_mask:0xf bound_ctrl:1
	v_add_f32_dpp v35, v35, v35 quad_perm:[2,3,0,1] row_mask:0xf bank_mask:0xf bound_ctrl:1
	v_add_f32_dpp v2, v2, v2 quad_perm:[1,0,3,2] row_mask:0xf bank_mask:0xf bound_ctrl:1
	v_add_f32_dpp v3, v3, v3 quad_perm:[1,0,3,2] row_mask:0xf bank_mask:0xf bound_ctrl:1
	v_add_f32_dpp v34, v34, v34 row_half_mirror row_mask:0xf bank_mask:0xf bound_ctrl:1
	v_add_f32_dpp v35, v35, v35 row_half_mirror row_mask:0xf bank_mask:0xf bound_ctrl:1
	v_add_f32_dpp v2, v2, v2 quad_perm:[2,3,0,1] row_mask:0xf bank_mask:0xf bound_ctrl:1
	v_add_f32_dpp v3, v3, v3 quad_perm:[2,3,0,1] row_mask:0xf bank_mask:0xf bound_ctrl:1
	v_add_f32_dpp v34, v34, v34 row_mirror row_mask:0xf bank_mask:0xf bound_ctrl:1
	v_add_f32_dpp v35, v35, v35 row_mirror row_mask:0xf bank_mask:0xf bound_ctrl:1
	s_waitcnt lgkmcnt(2)
	v_pk_mul_f32 v[36:37], v[42:43], v[34:35] op_sel_hi:[0,1]
	v_add_f32_dpp v2, v2, v2 row_half_mirror row_mask:0xf bank_mask:0xf bound_ctrl:1
	v_add_f32_dpp v3, v3, v3 row_half_mirror row_mask:0xf bank_mask:0xf bound_ctrl:1
	s_waitcnt lgkmcnt(1)
	v_pk_fma_f32 v[36:37], v[46:47], v[54:55], v[36:37] op_sel_hi:[0,1,1] neg_lo:[0,0,1] neg_hi:[0,0,1]
	v_add_f32_dpp v2, v2, v2 row_mirror row_mask:0xf bank_mask:0xf bound_ctrl:1
	v_add_f32_dpp v3, v3, v3 row_mirror row_mask:0xf bank_mask:0xf bound_ctrl:1
	s_waitcnt lgkmcnt(0)
	v_pk_fma_f32 v[54:55], v[30:31], v[58:59], v[36:37] op_sel_hi:[0,1,1]
	v_pk_mul_f32 v[36:37], v[42:43], v[34:35] op_sel:[1,0]
	v_cvt_pk_bf16_f32 v2, v2, v3
	v_pk_fma_f32 v[36:37], v[46:47], v[50:51], v[36:37] op_sel:[1,0,0] neg_lo:[0,0,1] neg_hi:[0,0,1]
	ds_write_b32 v14, v2 offset:2560
	v_pk_fma_f32 v[50:51], v[30:31], v[58:59], v[36:37] op_sel:[1,0,0]
	v_pk_mul_f32 v[30:31], v[44:45], v[34:35] op_sel_hi:[0,1]
	ds_read_b128 v[2:5], v15 offset:33792
	ds_read_b128 v[6:9], v15 offset:34048
	ds_read_b128 v[18:21], v15 offset:34304
	ds_read_b128 v[22:25], v15 offset:34560
	ds_read_b128 v[26:29], v15 offset:34816
	ds_read_b64 v[60:61], v16 offset:35072
	v_pk_fma_f32 v[30:31], v[48:49], v[56:57], v[30:31] op_sel_hi:[0,1,1] neg_lo:[0,0,1] neg_hi:[0,0,1]
	v_pk_fma_f32 v[56:57], v[32:33], v[58:59], v[30:31] op_sel_hi:[0,1,1]
	v_mov_b32_e32 v32, v45
	v_mov_b32_e32 v30, v49
	v_pk_mul_f32 v[34:35], v[32:33], v[34:35] op_sel_hi:[0,1]
	v_pk_fma_f32 v[30:31], v[30:31], v[52:53], v[34:35] op_sel_hi:[0,1,1] neg_lo:[0,0,1] neg_hi:[0,0,1]
	v_mov_b32_e32 v32, v33
	s_waitcnt lgkmcnt(2)
; #define LAS __attribute__((address_space(3)))
; DI unsigned pk2(float a, float b) { f32x2 v = {a, b}; bf2_t r = __builtin_convertvector(v, bf2_t); return __builtin_bit_cast(unsigned, r); }
; DI f32x2 red16p(f32x2 x) { float a = x.x, b = x.y; red16x2(a, b); return (f32x2){a, b}; }
; DI void scan_bh2(const Args& a, int l, int bh, int halfsel, LAS unsigned char* lds) {
;     ...
;             for (int st = 0; st < T; ++st) {
;                 f32x4 nr4, nd4, nk4, nkk4, nb4; f32x2 nv2;
;                 if (st < T - 1) {
;                     const LAS float* o = cur + (st + 1) * 384;
;                     nr4 = *(const LAS f32x4*)(o + kq * 4); nd4 = *(const LAS f32x4*)(o + 64 + kq * 4); nk4 = *(const LAS f32x4*)(o + 128 + kq * 4);
;                     nkk4 = *(const LAS f32x4*)(o + 192 + kq * 4); nb4 = *(const LAS f32x4*)(o + 256 + kq * 4); nv2 = *(const LAS f32x2*)(o + 320 + row0);
;                 }
;                 f32x2 sa = S[0] * kk4[0]; sa += S[1] * kk4[1]; f32x2 sb = S[2] * kk4[2]; sb += S[3] * kk4[3]; sa += sb;
;                 sa = red16p(sa); sa = -sa;
; #pragma unroll
;                 for (int j = 0; j < 4; ++j) S[j] = S[j] * d4[j] + sa * b4[j] + v2 * k4[j];
;                 f32x2 y = S[0] * r4[0]; y += S[1] * r4[1]; f32x2 yc = S[2] * r4[2]; yc += S[3] * r4[3]; y += yc;
;                 y = red16p(y);
;                 *(LAS unsigned*)(yb + st * 128 + row0 * 2) = pk2(y.x, y.y);
;                 if (st < T - 1) { r4 = nr4; d4 = nd4; k4 = nk4; kk4 = nkk4; b4 = nb4; v2 = nv2; }
;             }
	v_pk_mul_f32 v[62:63], v[22:23], v[50:51] op_sel:[1,0]
	v_pk_fma_f32 v[52:53], v[32:33], v[58:59], v[30:31] op_sel_hi:[0,1,1]
	v_pk_fma_f32 v[22:23], v[22:23], v[54:55], v[62:63] op_sel_hi:[0,1,1]
	v_mov_b32_e32 v62, v25
	v_pk_mul_f32 v[62:63], v[62:63], v[52:53] op_sel_hi:[0,1]
	v_mov_b32_e32 v32, v41
	v_pk_fma_f32 v[24:25], v[24:25], v[56:57], v[62:63] op_sel_hi:[0,1,1]
	v_pk_mul_f32 v[30:31], v[38:39], v[50:51] op_sel:[1,0]
	v_pk_mul_f32 v[32:33], v[32:33], v[52:53] op_sel_hi:[0,1]
	v_pk_add_f32 v[22:23], v[22:23], v[24:25]
	v_pk_fma_f32 v[30:31], v[38:39], v[54:55], v[30:31] op_sel_hi:[0,1,1]
	v_pk_fma_f32 v[32:33], v[40:41], v[56:57], v[32:33] op_sel_hi:[0,1,1]
	v_add_f32_dpp v22, v22, v22 quad_perm:[1,0,3,2] row_mask:0xf bank_mask:0xf bound_ctrl:1
	v_add_f32_dpp v23, v23, v23 quad_perm:[1,0,3,2] row_mask:0xf bank_mask:0xf bound_ctrl:1
	v_pk_add_f32 v[30:31], v[30:31], v[32:33]
	v_add_f32_dpp v22, v22, v22 quad_perm:[2,3,0,1] row_mask:0xf bank_mask:0xf bound_ctrl:1
	v_add_f32_dpp v23, v23, v23 quad_perm:[2,3,0,1] row_mask:0xf bank_mask:0xf bound_ctrl:1
	v_add_f32_dpp v30, v30, v30 quad_perm:[1,0,3,2] row_mask:0xf bank_mask:0xf bound_ctrl:1
	v_add_f32_dpp v31, v31, v31 quad_perm:[1,0,3,2] row_mask:0xf bank_mask:0xf bound_ctrl:1
	v_add_f32_dpp v22, v22, v22 row_half_mirror row_mask:0xf bank_mask:0xf bound_ctrl:1
	v_add_f32_dpp v23, v23, v23 row_half_mirror row_mask:0xf bank_mask:0xf bound_ctrl:1
	v_add_f32_dpp v30, v30, v30 quad_perm:[2,3,0,1] row_mask:0xf bank_mask:0xf bound_ctrl:1
	v_add_f32_dpp v31, v31, v31 quad_perm:[2,3,0,1] row_mask:0xf bank_mask:0xf bound_ctrl:1
	v_add_f32_dpp v22, v22, v22 row_mirror row_mask:0xf bank_mask:0xf bound_ctrl:1
	v_add_f32_dpp v23, v23, v23 row_mirror row_mask:0xf bank_mask:0xf bound_ctrl:1
	s_waitcnt lgkmcnt(1)
	v_pk_mul_f32 v[24:25], v[26:27], v[22:23] op_sel_hi:[0,1]
	v_add_f32_dpp v30, v30, v30 row_half_mirror row_mask:0xf bank_mask:0xf bound_ctrl:1
	v_add_f32_dpp v31, v31, v31 row_half_mirror row_mask:0xf bank_mask:0xf bound_ctrl:1
	v_pk_fma_f32 v[24:25], v[6:7], v[54:55], v[24:25] op_sel_hi:[0,1,1] neg_lo:[0,0,1] neg_hi:[0,0,1]
	v_add_f32_dpp v30, v30, v30 row_mirror row_mask:0xf bank_mask:0xf bound_ctrl:1
	v_add_f32_dpp v31, v31, v31 row_mirror row_mask:0xf bank_mask:0xf bound_ctrl:1
	s_waitcnt lgkmcnt(0)
	v_pk_fma_f32 v[54:55], v[18:19], v[60:61], v[24:25] op_sel_hi:[0,1,1]
	v_cvt_pk_bf16_f32 v17, v30, v31
	v_pk_mul_f32 v[24:25], v[26:27], v[22:23] op_sel:[1,0]
	ds_write_b32 v14, v17 offset:2688
	v_pk_fma_f32 v[6:7], v[6:7], v[50:51], v[24:25] op_sel:[1,0,0] neg_lo:[0,0,1] neg_hi:[0,0,1]
	ds_read_b128 v[30:33], v15 offset:35328
	ds_read_b128 v[34:37], v15 offset:35584
	ds_read_b128 v[38:41], v15 offset:35840
	ds_read_b128 v[42:45], v15 offset:36096
	ds_read_b128 v[46:49], v15 offset:36352
	ds_read_b64 v[58:59], v16 offset:36608
	v_pk_fma_f32 v[50:51], v[18:19], v[60:61], v[6:7] op_sel:[1,0,0]
	v_pk_mul_f32 v[6:7], v[28:29], v[22:23] op_sel_hi:[0,1]
	v_pk_fma_f32 v[6:7], v[8:9], v[56:57], v[6:7] op_sel_hi:[0,1,1] neg_lo:[0,0,1] neg_hi:[0,0,1]
	v_mov_b32_e32 v8, v29
	v_pk_fma_f32 v[56:57], v[20:21], v[60:61], v[6:7] op_sel_hi:[0,1,1]
	v_mov_b32_e32 v6, v9
	v_pk_mul_f32 v[8:9], v[8:9], v[22:23] op_sel_hi:[0,1]
	v_pk_fma_f32 v[6:7], v[6:7], v[52:53], v[8:9] op_sel_hi:[0,1,1] neg_lo:[0,0,1] neg_hi:[0,0,1]
	v_mov_b32_e32 v8, v21
	s_waitcnt lgkmcnt(2)
	v_pk_mul_f32 v[62:63], v[42:43], v[50:51] op_sel:[1,0]
	v_pk_fma_f32 v[52:53], v[8:9], v[60:61], v[6:7] op_sel_hi:[0,1,1]
	v_pk_mul_f32 v[6:7], v[2:3], v[50:51] op_sel:[1,0]
	v_pk_fma_f32 v[42:43], v[42:43], v[54:55], v[62:63] op_sel_hi:[0,1,1]
	v_mov_b32_e32 v62, v45
	v_pk_fma_f32 v[2:3], v[2:3], v[54:55], v[6:7] op_sel_hi:[0,1,1]
	v_mov_b32_e32 v6, v5
	v_pk_mul_f32 v[62:63], v[62:63], v[52:53] op_sel_hi:[0,1]
	v_pk_mul_f32 v[6:7], v[6:7], v[52:53] op_sel_hi:[0,1]
	v_pk_fma_f32 v[44:45], v[44:45], v[56:57], v[62:63] op_sel_hi:[0,1,1]
	v_pk_fma_f32 v[4:5], v[4:5], v[56:57], v[6:7] op_sel_hi:[0,1,1]
	v_pk_add_f32 v[42:43], v[42:43], v[44:45]
	v_pk_add_f32 v[2:3], v[2:3], v[4:5]
	s_nop 0
	v_add_f32_dpp v42, v42, v42 quad_perm:[1,0,3,2] row_mask:0xf bank_mask:0xf bound_ctrl:1
	v_add_f32_dpp v43, v43, v43 quad_perm:[1,0,3,2] row_mask:0xf bank_mask:0xf bound_ctrl:1
	v_add_f32_dpp v2, v2, v2 quad_perm:[1,0,3,2] row_mask:0xf bank_mask:0xf bound_ctrl:1
	v_add_f32_dpp v3, v3, v3 quad_perm:[1,0,3,2] row_mask:0xf bank_mask:0xf bound_ctrl:1
	v_add_f32_dpp v42, v42, v42 quad_perm:[2,3,0,1] row_mask:0xf bank_mask:0xf bound_ctrl:1
	v_add_f32_dpp v43, v43, v43 quad_perm:[2,3,0,1] row_mask:0xf bank_mask:0xf bound_ctrl:1
	v_add_f32_dpp v2, v2, v2 quad_perm:[2,3,0,1] row_mask:0xf bank_mask:0xf bound_ctrl:1
	v_add_f32_dpp v3, v3, v3 quad_perm:[2,3,0,1] row_mask:0xf bank_mask:0xf bound_ctrl:1
	v_add_f32_dpp v42, v42, v42 row_half_mirror row_mask:0xf bank_mask:0xf bound_ctrl:1
	v_add_f32_dpp v43, v43, v43 row_half_mirror row_mask:0xf bank_mask:0xf bound_ctrl:1
	v_add_f32_dpp v2, v2, v2 row_half_mirror row_mask:0xf bank_mask:0xf bound_ctrl:1
	v_add_f32_dpp v3, v3, v3 row_half_mirror row_mask:0xf bank_mask:0xf bound_ctrl:1
	v_add_f32_dpp v42, v42, v42 row_mirror row_mask:0xf bank_mask:0xf bound_ctrl:1
	v_add_f32_dpp v43, v43, v43 row_mirror row_mask:0xf bank_mask:0xf bound_ctrl:1
	s_waitcnt lgkmcnt(1)
	v_pk_mul_f32 v[44:45], v[46:47], v[42:43] op_sel_hi:[0,1]
	v_add_f32_dpp v2, v2, v2 row_mirror row_mask:0xf bank_mask:0xf bound_ctrl:1
	v_add_f32_dpp v3, v3, v3 row_mirror row_mask:0xf bank_mask:0xf bound_ctrl:1
	v_pk_fma_f32 v[44:45], v[34:35], v[54:55], v[44:45] op_sel_hi:[0,1,1] neg_lo:[0,0,1] neg_hi:[0,0,1]
	v_cvt_pk_bf16_f32 v2, v2, v3
	s_waitcnt lgkmcnt(0)
; #define LAS __attribute__((address_space(3)))
; DI unsigned pk2(float a, float b) { f32x2 v = {a, b}; bf2_t r = __builtin_convertvector(v, bf2_t); return __builtin_bit_cast(unsigned, r); }
; DI f32x2 red16p(f32x2 x) { float a = x.x, b = x.y; red16x2(a, b); return (f32x2){a, b}; }
; DI void scan_bh2(const Args& a, int l, int bh, int halfsel, LAS unsigned char* lds) {
;     ...
;             for (int st = 0; st < T; ++st) {
;                 f32x4 nr4, nd4, nk4, nkk4, nb4; f32x2 nv2;
;                 if (st < T - 1) {
;                     const LAS float* o = cur + (st + 1) * 384;
;                     nr4 = *(const LAS f32x4*)(o + kq * 4); nd4 = *(const LAS f32x4*)(o + 64 + kq * 4); nk4 = *(const LAS f32x4*)(o + 128 + kq * 4);
;                     nkk4 = *(const LAS f32x4*)(o + 192 + kq * 4); nb4 = *(const LAS f32x4*)(o + 256 + kq * 4); nv2 = *(const LAS f32x2*)(o + 320 + row0);
;                 }
;                 f32x2 sa = S[0] * kk4[0]; sa += S[1] * kk4[1]; f32x2 sb = S[2] * kk4[2]; sb += S[3] * kk4[3]; sa += sb;
;                 sa = red16p(sa); sa = -sa;
; #pragma unroll
;                 for (int j = 0; j < 4; ++j) S[j] = S[j] * d4[j] + sa * b4[j] + v2 * k4[j];
;                 f32x2 y = S[0] * r4[0]; y += S[1] * r4[1]; f32x2 yc = S[2] * r4[2]; yc += S[3] * r4[3]; y += yc;
;                 y = red16p(y);
;                 *(LAS unsigned*)(yb + st * 128 + row0 * 2) = pk2(y.x, y.y);
;                 if (st < T - 1) { r4 = nr4; d4 = nd4; k4 = nk4; kk4 = nkk4; b4 = nb4; v2 = nv2; }
;             }
	v_pk_fma_f32 v[54:55], v[38:39], v[58:59], v[44:45] op_sel_hi:[0,1,1]
	v_pk_mul_f32 v[44:45], v[46:47], v[42:43] op_sel:[1,0]
	ds_write_b32 v14, v2 offset:2816
	v_pk_fma_f32 v[34:35], v[34:35], v[50:51], v[44:45] op_sel:[1,0,0] neg_lo:[0,0,1] neg_hi:[0,0,1]
	ds_read_b128 v[2:5], v15 offset:36864
	ds_read_b128 v[6:9], v15 offset:37120
	ds_read_b128 v[18:21], v15 offset:37376
	ds_read_b128 v[22:25], v15 offset:37632
	ds_read_b128 v[26:29], v15 offset:37888
	ds_read_b64 v[60:61], v16 offset:38144
	v_pk_fma_f32 v[50:51], v[38:39], v[58:59], v[34:35] op_sel:[1,0,0]
	v_pk_mul_f32 v[34:35], v[48:49], v[42:43] op_sel_hi:[0,1]
	v_pk_fma_f32 v[34:35], v[36:37], v[56:57], v[34:35] op_sel_hi:[0,1,1] neg_lo:[0,0,1] neg_hi:[0,0,1]
	v_mov_b32_e32 v36, v49
	v_pk_fma_f32 v[56:57], v[40:41], v[58:59], v[34:35] op_sel_hi:[0,1,1]
	v_mov_b32_e32 v34, v37
	v_pk_mul_f32 v[36:37], v[36:37], v[42:43] op_sel_hi:[0,1]
	v_pk_fma_f32 v[34:35], v[34:35], v[52:53], v[36:37] op_sel_hi:[0,1,1] neg_lo:[0,0,1] neg_hi:[0,0,1]
	v_mov_b32_e32 v36, v41
	s_waitcnt lgkmcnt(2)
	v_pk_mul_f32 v[62:63], v[22:23], v[50:51] op_sel:[1,0]
	v_pk_fma_f32 v[52:53], v[36:37], v[58:59], v[34:35] op_sel_hi:[0,1,1]
	v_pk_fma_f32 v[22:23], v[22:23], v[54:55], v[62:63] op_sel_hi:[0,1,1]
	v_mov_b32_e32 v62, v25
	v_pk_mul_f32 v[34:35], v[30:31], v[50:51] op_sel:[1,0]
	v_pk_mul_f32 v[62:63], v[62:63], v[52:53] op_sel_hi:[0,1]
	v_pk_fma_f32 v[30:31], v[30:31], v[54:55], v[34:35] op_sel_hi:[0,1,1]
	v_mov_b32_e32 v34, v33
	v_pk_fma_f32 v[24:25], v[24:25], v[56:57], v[62:63] op_sel_hi:[0,1,1]
	v_pk_mul_f32 v[34:35], v[34:35], v[52:53] op_sel_hi:[0,1]
	v_pk_add_f32 v[22:23], v[22:23], v[24:25]
	v_pk_fma_f32 v[32:33], v[32:33], v[56:57], v[34:35] op_sel_hi:[0,1,1]
	s_nop 0
	v_add_f32_dpp v22, v22, v22 quad_perm:[1,0,3,2] row_mask:0xf bank_mask:0xf bound_ctrl:1
	v_add_f32_dpp v23, v23, v23 quad_perm:[1,0,3,2] row_mask:0xf bank_mask:0xf bound_ctrl:1
	v_pk_add_f32 v[30:31], v[30:31], v[32:33]
	v_add_f32_dpp v22, v22, v22 quad_perm:[2,3,0,1] row_mask:0xf bank_mask:0xf bound_ctrl:1
	v_add_f32_dpp v23, v23, v23 quad_perm:[2,3,0,1] row_mask:0xf bank_mask:0xf bound_ctrl:1
	v_add_f32_dpp v30, v30, v30 quad_perm:[1,0,3,2] row_mask:0xf bank_mask:0xf bound_ctrl:1
	v_add_f32_dpp v31, v31, v31 quad_perm:[1,0,3,2] row_mask:0xf bank_mask:0xf bound_ctrl:1
	v_add_f32_dpp v22, v22, v22 row_half_mirror row_mask:0xf bank_mask:0xf bound_ctrl:1
	v_add_f32_dpp v23, v23, v23 row_half_mirror row_mask:0xf bank_mask:0xf bound_ctrl:1
	v_add_f32_dpp v30, v30, v30 quad_perm:[2,3,0,1] row_mask:0xf bank_mask:0xf bound_ctrl:1
	v_add_f32_dpp v31, v31, v31 quad_perm:[2,3,0,1] row_mask:0xf bank_mask:0xf bound_ctrl:1
	v_add_f32_dpp v22, v22, v22 row_mirror row_mask:0xf bank_mask:0xf bound_ctrl:1
	v_add_f32_dpp v23, v23, v23 row_mirror row_mask:0xf bank_mask:0xf bound_ctrl:1
	s_waitcnt lgkmcnt(1)
	v_pk_mul_f32 v[24:25], v[26:27], v[22:23] op_sel_hi:[0,1]
	v_add_f32_dpp v30, v30, v30 row_half_mirror row_mask:0xf bank_mask:0xf bound_ctrl:1
	v_add_f32_dpp v31, v31, v31 row_half_mirror row_mask:0xf bank_mask:0xf bound_ctrl:1
	v_pk_fma_f32 v[24:25], v[6:7], v[54:55], v[24:25] op_sel_hi:[0,1,1] neg_lo:[0,0,1] neg_hi:[0,0,1]
	v_add_f32_dpp v30, v30, v30 row_mirror row_mask:0xf bank_mask:0xf bound_ctrl:1
	v_add_f32_dpp v31, v31, v31 row_mirror row_mask:0xf bank_mask:0xf bound_ctrl:1
	s_waitcnt lgkmcnt(0)
	v_pk_fma_f32 v[54:55], v[18:19], v[60:61], v[24:25] op_sel_hi:[0,1,1]
	v_cvt_pk_bf16_f32 v17, v30, v31
	v_pk_mul_f32 v[24:25], v[26:27], v[22:23] op_sel:[1,0]
	ds_write_b32 v14, v17 offset:2944
	v_pk_fma_f32 v[6:7], v[6:7], v[50:51], v[24:25] op_sel:[1,0,0] neg_lo:[0,0,1] neg_hi:[0,0,1]
	ds_read_b128 v[30:33], v15 offset:38400
	ds_read_b128 v[34:37], v15 offset:38656
	ds_read_b128 v[38:41], v15 offset:38912
	ds_read_b128 v[42:45], v15 offset:39168
	ds_read_b128 v[46:49], v15 offset:39424
	ds_read_b64 v[58:59], v16 offset:39680
	v_pk_fma_f32 v[50:51], v[18:19], v[60:61], v[6:7] op_sel:[1,0,0]
	v_pk_mul_f32 v[6:7], v[28:29], v[22:23] op_sel_hi:[0,1]
	v_pk_fma_f32 v[6:7], v[8:9], v[56:57], v[6:7] op_sel_hi:[0,1,1] neg_lo:[0,0,1] neg_hi:[0,0,1]
	v_mov_b32_e32 v8, v29
	v_pk_fma_f32 v[56:57], v[20:21], v[60:61], v[6:7] op_sel_hi:[0,1,1]
	v_mov_b32_e32 v6, v9
	v_pk_mul_f32 v[8:9], v[8:9], v[22:23] op_sel_hi:[0,1]
	v_pk_fma_f32 v[6:7], v[6:7], v[52:53], v[8:9] op_sel_hi:[0,1,1] neg_lo:[0,0,1] neg_hi:[0,0,1]
	v_mov_b32_e32 v8, v21
	s_waitcnt lgkmcnt(2)
	v_pk_mul_f32 v[62:63], v[42:43], v[50:51] op_sel:[1,0]
	v_pk_fma_f32 v[52:53], v[8:9], v[60:61], v[6:7] op_sel_hi:[0,1,1]
	v_pk_mul_f32 v[6:7], v[2:3], v[50:51] op_sel:[1,0]
	v_pk_fma_f32 v[42:43], v[42:43], v[54:55], v[62:63] op_sel_hi:[0,1,1]
	v_mov_b32_e32 v62, v45
	v_pk_fma_f32 v[2:3], v[2:3], v[54:55], v[6:7] op_sel_hi:[0,1,1]
	v_mov_b32_e32 v6, v5
	v_pk_mul_f32 v[62:63], v[62:63], v[52:53] op_sel_hi:[0,1]
	v_pk_mul_f32 v[6:7], v[6:7], v[52:53] op_sel_hi:[0,1]
	v_pk_fma_f32 v[44:45], v[44:45], v[56:57], v[62:63] op_sel_hi:[0,1,1]
	v_pk_fma_f32 v[4:5], v[4:5], v[56:57], v[6:7] op_sel_hi:[0,1,1]
	v_pk_add_f32 v[42:43], v[42:43], v[44:45]
	v_pk_add_f32 v[2:3], v[2:3], v[4:5]
	s_nop 0
	v_add_f32_dpp v42, v42, v42 quad_perm:[1,0,3,2] row_mask:0xf bank_mask:0xf bound_ctrl:1
	v_add_f32_dpp v43, v43, v43 quad_perm:[1,0,3,2] row_mask:0xf bank_mask:0xf bound_ctrl:1
	v_add_f32_dpp v2, v2, v2 quad_perm:[1,0,3,2] row_mask:0xf bank_mask:0xf bound_ctrl:1
	v_add_f32_dpp v3, v3, v3 quad_perm:[1,0,3,2] row_mask:0xf bank_mask:0xf bound_ctrl:1
	v_add_f32_dpp v42, v42, v42 quad_perm:[2,3,0,1] row_mask:0xf bank_mask:0xf bound_ctrl:1
	v_add_f32_dpp v43, v43, v43 quad_perm:[2,3,0,1] row_mask:0xf bank_mask:0xf bound_ctrl:1
	v_add_f32_dpp v2, v2, v2 quad_perm:[2,3,0,1] row_mask:0xf bank_mask:0xf bound_ctrl:1
	v_add_f32_dpp v3, v3, v3 quad_perm:[2,3,0,1] row_mask:0xf bank_mask:0xf bound_ctrl:1
	v_add_f32_dpp v42, v42, v42 row_half_mirror row_mask:0xf bank_mask:0xf bound_ctrl:1
	v_add_f32_dpp v43, v43, v43 row_half_mirror row_mask:0xf bank_mask:0xf bound_ctrl:1
	v_add_f32_dpp v2, v2, v2 row_half_mirror row_mask:0xf bank_mask:0xf bound_ctrl:1
	v_add_f32_dpp v3, v3, v3 row_half_mirror row_mask:0xf bank_mask:0xf bound_ctrl:1
	v_add_f32_dpp v42, v42, v42 row_mirror row_mask:0xf bank_mask:0xf bound_ctrl:1
	v_add_f32_dpp v43, v43, v43 row_mirror row_mask:0xf bank_mask:0xf bound_ctrl:1
	s_waitcnt lgkmcnt(1)
; #define LAS __attribute__((address_space(3)))
; DI unsigned pk2(float a, float b) { f32x2 v = {a, b}; bf2_t r = __builtin_convertvector(v, bf2_t); return __builtin_bit_cast(unsigned, r); }
; DI f32x2 red16p(f32x2 x) { float a = x.x, b = x.y; red16x2(a, b); return (f32x2){a, b}; }
; DI void scan_bh2(const Args& a, int l, int bh, int halfsel, LAS unsigned char* lds) {
;     ...
;             for (int st = 0; st < T; ++st) {
;                 f32x4 nr4, nd4, nk4, nkk4, nb4; f32x2 nv2;
;                 if (st < T - 1) {
;                     const LAS float* o = cur + (st + 1) * 384;
;                     nr4 = *(const LAS f32x4*)(o + kq * 4); nd4 = *(const LAS f32x4*)(o + 64 + kq * 4); nk4 = *(const LAS f32x4*)(o + 128 + kq * 4);
;                     nkk4 = *(const LAS f32x4*)(o + 192 + kq * 4); nb4 = *(const LAS f32x4*)(o + 256 + kq * 4); nv2 = *(const LAS f32x2*)(o + 320 + row0);
;                 }
;                 f32x2 sa = S[0] * kk4[0]; sa += S[1] * kk4[1]; f32x2 sb = S[2] * kk4[2]; sb += S[3] * kk4[3]; sa += sb;
;                 sa = red16p(sa); sa = -sa;
; #pragma unroll
;                 for (int j = 0; j < 4; ++j) S[j] = S[j] * d4[j] + sa * b4[j] + v2 * k4[j];
;                 f32x2 y = S[0] * r4[0]; y += S[1] * r4[1]; f32x2 yc = S[2] * r4[2]; yc += S[3] * r4[3]; y += yc;
;                 y = red16p(y);
;                 *(LAS unsigned*)(yb + st * 128 + row0 * 2) = pk2(y.x, y.y);
;                 if (st < T - 1) { r4 = nr4; d4 = nd4; k4 = nk4; kk4 = nkk4; b4 = nb4; v2 = nv2; }
;             }
	v_pk_mul_f32 v[44:45], v[46:47], v[42:43] op_sel_hi:[0,1]
	v_add_f32_dpp v2, v2, v2 row_mirror row_mask:0xf bank_mask:0xf bound_ctrl:1
	v_add_f32_dpp v3, v3, v3 row_mirror row_mask:0xf bank_mask:0xf bound_ctrl:1
	v_pk_fma_f32 v[44:45], v[34:35], v[54:55], v[44:45] op_sel_hi:[0,1,1] neg_lo:[0,0,1] neg_hi:[0,0,1]
	v_cvt_pk_bf16_f32 v2, v2, v3
	s_waitcnt lgkmcnt(0)
	v_pk_fma_f32 v[54:55], v[38:39], v[58:59], v[44:45] op_sel_hi:[0,1,1]
	v_pk_mul_f32 v[44:45], v[46:47], v[42:43] op_sel:[1,0]
	ds_write_b32 v14, v2 offset:3072
	v_pk_fma_f32 v[34:35], v[34:35], v[50:51], v[44:45] op_sel:[1,0,0] neg_lo:[0,0,1] neg_hi:[0,0,1]
	ds_read_b128 v[2:5], v15 offset:39936
	ds_read_b128 v[6:9], v15 offset:40192
	ds_read_b128 v[18:21], v15 offset:40448
	ds_read_b128 v[22:25], v15 offset:40704
	ds_read_b128 v[26:29], v15 offset:40960
	ds_read_b64 v[60:61], v16 offset:41216
	v_pk_fma_f32 v[50:51], v[38:39], v[58:59], v[34:35] op_sel:[1,0,0]
	v_pk_mul_f32 v[34:35], v[48:49], v[42:43] op_sel_hi:[0,1]
	v_pk_fma_f32 v[34:35], v[36:37], v[56:57], v[34:35] op_sel_hi:[0,1,1] neg_lo:[0,0,1] neg_hi:[0,0,1]
	v_mov_b32_e32 v36, v49
	v_pk_fma_f32 v[56:57], v[40:41], v[58:59], v[34:35] op_sel_hi:[0,1,1]
	v_mov_b32_e32 v34, v37
	v_pk_mul_f32 v[36:37], v[36:37], v[42:43] op_sel_hi:[0,1]
	v_pk_fma_f32 v[34:35], v[34:35], v[52:53], v[36:37] op_sel_hi:[0,1,1] neg_lo:[0,0,1] neg_hi:[0,0,1]
	v_mov_b32_e32 v36, v41
	s_waitcnt lgkmcnt(2)
	v_pk_mul_f32 v[62:63], v[22:23], v[50:51] op_sel:[1,0]
	v_pk_fma_f32 v[52:53], v[36:37], v[58:59], v[34:35] op_sel_hi:[0,1,1]
	v_pk_fma_f32 v[22:23], v[22:23], v[54:55], v[62:63] op_sel_hi:[0,1,1]
	v_mov_b32_e32 v62, v25
	v_pk_mul_f32 v[34:35], v[30:31], v[50:51] op_sel:[1,0]
	v_pk_mul_f32 v[62:63], v[62:63], v[52:53] op_sel_hi:[0,1]
	v_pk_fma_f32 v[30:31], v[30:31], v[54:55], v[34:35] op_sel_hi:[0,1,1]
	v_mov_b32_e32 v34, v33
	v_pk_fma_f32 v[24:25], v[24:25], v[56:57], v[62:63] op_sel_hi:[0,1,1]
	v_pk_mul_f32 v[34:35], v[34:35], v[52:53] op_sel_hi:[0,1]
	v_pk_add_f32 v[22:23], v[22:23], v[24:25]
	v_pk_fma_f32 v[32:33], v[32:33], v[56:57], v[34:35] op_sel_hi:[0,1,1]
	s_nop 0
	v_add_f32_dpp v22, v22, v22 quad_perm:[1,0,3,2] row_mask:0xf bank_mask:0xf bound_ctrl:1
	v_add_f32_dpp v23, v23, v23 quad_perm:[1,0,3,2] row_mask:0xf bank_mask:0xf bound_ctrl:1
	v_pk_add_f32 v[30:31], v[30:31], v[32:33]
	v_add_f32_dpp v22, v22, v22 quad_perm:[2,3,0,1] row_mask:0xf bank_mask:0xf bound_ctrl:1
	v_add_f32_dpp v23, v23, v23 quad_perm:[2,3,0,1] row_mask:0xf bank_mask:0xf bound_ctrl:1
	v_add_f32_dpp v30, v30, v30 quad_perm:[1,0,3,2] row_mask:0xf bank_mask:0xf bound_ctrl:1
	v_add_f32_dpp v31, v31, v31 quad_perm:[1,0,3,2] row_mask:0xf bank_mask:0xf bound_ctrl:1
	v_add_f32_dpp v22, v22, v22 row_half_mirror row_mask:0xf bank_mask:0xf bound_ctrl:1
	v_add_f32_dpp v23, v23, v23 row_half_mirror row_mask:0xf bank_mask:0xf bound_ctrl:1
	v_add_f32_dpp v30, v30, v30 quad_perm:[2,3,0,1] row_mask:0xf bank_mask:0xf bound_ctrl:1
	v_add_f32_dpp v31, v31, v31 quad_perm:[2,3,0,1] row_mask:0xf bank_mask:0xf bound_ctrl:1
	v_add_f32_dpp v22, v22, v22 row_mirror row_mask:0xf bank_mask:0xf bound_ctrl:1
	v_add_f32_dpp v23, v23, v23 row_mirror row_mask:0xf bank_mask:0xf bound_ctrl:1
	s_waitcnt lgkmcnt(1)
	v_pk_mul_f32 v[24:25], v[26:27], v[22:23] op_sel_hi:[0,1]
	v_add_f32_dpp v30, v30, v30 row_half_mirror row_mask:0xf bank_mask:0xf bound_ctrl:1
	v_add_f32_dpp v31, v31, v31 row_half_mirror row_mask:0xf bank_mask:0xf bound_ctrl:1
	v_pk_fma_f32 v[24:25], v[6:7], v[54:55], v[24:25] op_sel_hi:[0,1,1] neg_lo:[0,0,1] neg_hi:[0,0,1]
	v_add_f32_dpp v30, v30, v30 row_mirror row_mask:0xf bank_mask:0xf bound_ctrl:1
	v_add_f32_dpp v31, v31, v31 row_mirror row_mask:0xf bank_mask:0xf bound_ctrl:1
	s_waitcnt lgkmcnt(0)
	v_pk_fma_f32 v[54:55], v[18:19], v[60:61], v[24:25] op_sel_hi:[0,1,1]
	v_cvt_pk_bf16_f32 v17, v30, v31
	v_pk_mul_f32 v[24:25], v[26:27], v[22:23] op_sel:[1,0]
	ds_write_b32 v14, v17 offset:3200
	v_pk_fma_f32 v[6:7], v[6:7], v[50:51], v[24:25] op_sel:[1,0,0] neg_lo:[0,0,1] neg_hi:[0,0,1]
	ds_read_b128 v[30:33], v15 offset:41472
	ds_read_b128 v[34:37], v15 offset:41728
	ds_read_b128 v[38:41], v15 offset:41984
	ds_read_b128 v[42:45], v15 offset:42240
	ds_read_b128 v[46:49], v15 offset:42496
	ds_read_b64 v[58:59], v16 offset:42752
	v_pk_fma_f32 v[50:51], v[18:19], v[60:61], v[6:7] op_sel:[1,0,0]
	v_pk_mul_f32 v[6:7], v[28:29], v[22:23] op_sel_hi:[0,1]
	v_pk_fma_f32 v[6:7], v[8:9], v[56:57], v[6:7] op_sel_hi:[0,1,1] neg_lo:[0,0,1] neg_hi:[0,0,1]
	v_mov_b32_e32 v8, v29
	v_pk_fma_f32 v[56:57], v[20:21], v[60:61], v[6:7] op_sel_hi:[0,1,1]
	v_mov_b32_e32 v6, v9
	v_pk_mul_f32 v[8:9], v[8:9], v[22:23] op_sel_hi:[0,1]
	v_pk_fma_f32 v[6:7], v[6:7], v[52:53], v[8:9] op_sel_hi:[0,1,1] neg_lo:[0,0,1] neg_hi:[0,0,1]
	v_mov_b32_e32 v8, v21
	s_waitcnt lgkmcnt(2)
; #define LAS __attribute__((address_space(3)))
; DI unsigned pk2(float a, float b) { f32x2 v = {a, b}; bf2_t r = __builtin_convertvector(v, bf2_t); return __builtin_bit_cast(unsigned, r); }
; DI f32x2 red16p(f32x2 x) { float a = x.x, b = x.y; red16x2(a, b); return (f32x2){a, b}; }
; DI void scan_bh2(const Args& a, int l, int bh, int halfsel, LAS unsigned char* lds) {
;     ...
;             for (int st = 0; st < T; ++st) {
;                 f32x4 nr4, nd4, nk4, nkk4, nb4; f32x2 nv2;
;                 if (st < T - 1) {
;                     const LAS float* o = cur + (st + 1) * 384;
;                     nr4 = *(const LAS f32x4*)(o + kq * 4); nd4 = *(const LAS f32x4*)(o + 64 + kq * 4); nk4 = *(const LAS f32x4*)(o + 128 + kq * 4);
;                     nkk4 = *(const LAS f32x4*)(o + 192 + kq * 4); nb4 = *(const LAS f32x4*)(o + 256 + kq * 4); nv2 = *(const LAS f32x2*)(o + 320 + row0);
;                 }
;                 f32x2 sa = S[0] * kk4[0]; sa += S[1] * kk4[1]; f32x2 sb = S[2] * kk4[2]; sb += S[3] * kk4[3]; sa += sb;
;                 sa = red16p(sa); sa = -sa;
; #pragma unroll
;                 for (int j = 0; j < 4; ++j) S[j] = S[j] * d4[j] + sa * b4[j] + v2 * k4[j];
;                 f32x2 y = S[0] * r4[0]; y += S[1] * r4[1]; f32x2 yc = S[2] * r4[2]; yc += S[3] * r4[3]; y += yc;
;                 y = red16p(y);
;                 *(LAS unsigned*)(yb + st * 128 + row0 * 2) = pk2(y.x, y.y);
;                 if (st < T - 1) { r4 = nr4; d4 = nd4; k4 = nk4; kk4 = nkk4; b4 = nb4; v2 = nv2; }
;             }
	v_pk_mul_f32 v[62:63], v[42:43], v[50:51] op_sel:[1,0]
	v_pk_fma_f32 v[52:53], v[8:9], v[60:61], v[6:7] op_sel_hi:[0,1,1]
	v_pk_mul_f32 v[6:7], v[2:3], v[50:51] op_sel:[1,0]
	v_pk_fma_f32 v[42:43], v[42:43], v[54:55], v[62:63] op_sel_hi:[0,1,1]
	v_mov_b32_e32 v62, v45
	v_pk_fma_f32 v[2:3], v[2:3], v[54:55], v[6:7] op_sel_hi:[0,1,1]
	v_mov_b32_e32 v6, v5
	v_pk_mul_f32 v[62:63], v[62:63], v[52:53] op_sel_hi:[0,1]
	v_pk_mul_f32 v[6:7], v[6:7], v[52:53] op_sel_hi:[0,1]
	v_pk_fma_f32 v[44:45], v[44:45], v[56:57], v[62:63] op_sel_hi:[0,1,1]
	v_pk_fma_f32 v[4:5], v[4:5], v[56:57], v[6:7] op_sel_hi:[0,1,1]
	v_pk_add_f32 v[42:43], v[42:43], v[44:45]
	v_pk_add_f32 v[2:3], v[2:3], v[4:5]
	s_nop 0
	v_add_f32_dpp v42, v42, v42 quad_perm:[1,0,3,2] row_mask:0xf bank_mask:0xf bound_ctrl:1
	v_add_f32_dpp v43, v43, v43 quad_perm:[1,0,3,2] row_mask:0xf bank_mask:0xf bound_ctrl:1
	v_add_f32_dpp v2, v2, v2 quad_perm:[1,0,3,2] row_mask:0xf bank_mask:0xf bound_ctrl:1
	v_add_f32_dpp v3, v3, v3 quad_perm:[1,0,3,2] row_mask:0xf bank_mask:0xf bound_ctrl:1
	v_add_f32_dpp v42, v42, v42 quad_perm:[2,3,0,1] row_mask:0xf bank_mask:0xf bound_ctrl:1
	v_add_f32_dpp v43, v43, v43 quad_perm:[2,3,0,1] row_mask:0xf bank_mask:0xf bound_ctrl:1
	v_add_f32_dpp v2, v2, v2 quad_perm:[2,3,0,1] row_mask:0xf bank_mask:0xf bound_ctrl:1
	v_add_f32_dpp v3, v3, v3 quad_perm:[2,3,0,1] row_mask:0xf bank_mask:0xf bound_ctrl:1
	v_add_f32_dpp v42, v42, v42 row_half_mirror row_mask:0xf bank_mask:0xf bound_ctrl:1
	v_add_f32_dpp v43, v43, v43 row_half_mirror row_mask:0xf bank_mask:0xf bound_ctrl:1
	v_add_f32_dpp v2, v2, v2 row_half_mirror row_mask:0xf bank_mask:0xf bound_ctrl:1
	v_add_f32_dpp v3, v3, v3 row_half_mirror row_mask:0xf bank_mask:0xf bound_ctrl:1
	v_add_f32_dpp v42, v42, v42 row_mirror row_mask:0xf bank_mask:0xf bound_ctrl:1
	v_add_f32_dpp v43, v43, v43 row_mirror row_mask:0xf bank_mask:0xf bound_ctrl:1
	s_waitcnt lgkmcnt(1)
	v_pk_mul_f32 v[44:45], v[46:47], v[42:43] op_sel_hi:[0,1]
	v_add_f32_dpp v2, v2, v2 row_mirror row_mask:0xf bank_mask:0xf bound_ctrl:1
	v_add_f32_dpp v3, v3, v3 row_mirror row_mask:0xf bank_mask:0xf bound_ctrl:1
	v_pk_fma_f32 v[44:45], v[34:35], v[54:55], v[44:45] op_sel_hi:[0,1,1] neg_lo:[0,0,1] neg_hi:[0,0,1]
	v_cvt_pk_bf16_f32 v2, v2, v3
	s_waitcnt lgkmcnt(0)
	v_pk_fma_f32 v[54:55], v[38:39], v[58:59], v[44:45] op_sel_hi:[0,1,1]
	v_pk_mul_f32 v[44:45], v[46:47], v[42:43] op_sel:[1,0]
	ds_write_b32 v14, v2 offset:3328
	v_pk_fma_f32 v[34:35], v[34:35], v[50:51], v[44:45] op_sel:[1,0,0] neg_lo:[0,0,1] neg_hi:[0,0,1]
	ds_read_b128 v[2:5], v15 offset:43008
	ds_read_b128 v[6:9], v15 offset:43264
	ds_read_b128 v[18:21], v15 offset:43520
	ds_read_b128 v[22:25], v15 offset:43776
	ds_read_b128 v[26:29], v15 offset:44032
	ds_read_b64 v[60:61], v16 offset:44288
	v_pk_fma_f32 v[50:51], v[38:39], v[58:59], v[34:35] op_sel:[1,0,0]
	v_pk_mul_f32 v[34:35], v[48:49], v[42:43] op_sel_hi:[0,1]
	v_pk_fma_f32 v[34:35], v[36:37], v[56:57], v[34:35] op_sel_hi:[0,1,1] neg_lo:[0,0,1] neg_hi:[0,0,1]
	v_mov_b32_e32 v36, v49
	v_pk_fma_f32 v[56:57], v[40:41], v[58:59], v[34:35] op_sel_hi:[0,1,1]
	v_mov_b32_e32 v34, v37
	v_pk_mul_f32 v[36:37], v[36:37], v[42:43] op_sel_hi:[0,1]
	v_pk_fma_f32 v[34:35], v[34:35], v[52:53], v[36:37] op_sel_hi:[0,1,1] neg_lo:[0,0,1] neg_hi:[0,0,1]
	v_mov_b32_e32 v36, v41
	s_waitcnt lgkmcnt(2)
	v_pk_mul_f32 v[62:63], v[22:23], v[50:51] op_sel:[1,0]
	v_pk_fma_f32 v[52:53], v[36:37], v[58:59], v[34:35] op_sel_hi:[0,1,1]
	v_pk_fma_f32 v[22:23], v[22:23], v[54:55], v[62:63] op_sel_hi:[0,1,1]
	v_mov_b32_e32 v62, v25
	v_pk_mul_f32 v[34:35], v[30:31], v[50:51] op_sel:[1,0]
	v_pk_mul_f32 v[62:63], v[62:63], v[52:53] op_sel_hi:[0,1]
	v_pk_fma_f32 v[30:31], v[30:31], v[54:55], v[34:35] op_sel_hi:[0,1,1]
	v_mov_b32_e32 v34, v33
	v_pk_fma_f32 v[24:25], v[24:25], v[56:57], v[62:63] op_sel_hi:[0,1,1]
	v_pk_mul_f32 v[34:35], v[34:35], v[52:53] op_sel_hi:[0,1]
	v_pk_add_f32 v[22:23], v[22:23], v[24:25]
	v_pk_fma_f32 v[32:33], v[32:33], v[56:57], v[34:35] op_sel_hi:[0,1,1]
	s_nop 0
	v_add_f32_dpp v22, v22, v22 quad_perm:[1,0,3,2] row_mask:0xf bank_mask:0xf bound_ctrl:1
	v_add_f32_dpp v23, v23, v23 quad_perm:[1,0,3,2] row_mask:0xf bank_mask:0xf bound_ctrl:1
	v_pk_add_f32 v[30:31], v[30:31], v[32:33]
	v_add_f32_dpp v22, v22, v22 quad_perm:[2,3,0,1] row_mask:0xf bank_mask:0xf bound_ctrl:1
	v_add_f32_dpp v23, v23, v23 quad_perm:[2,3,0,1] row_mask:0xf bank_mask:0xf bound_ctrl:1
	v_add_f32_dpp v30, v30, v30 quad_perm:[1,0,3,2] row_mask:0xf bank_mask:0xf bound_ctrl:1
	v_add_f32_dpp v31, v31, v31 quad_perm:[1,0,3,2] row_mask:0xf bank_mask:0xf bound_ctrl:1
	v_add_f32_dpp v22, v22, v22 row_half_mirror row_mask:0xf bank_mask:0xf bound_ctrl:1
	v_add_f32_dpp v23, v23, v23 row_half_mirror row_mask:0xf bank_mask:0xf bound_ctrl:1
	v_add_f32_dpp v30, v30, v30 quad_perm:[2,3,0,1] row_mask:0xf bank_mask:0xf bound_ctrl:1
	v_add_f32_dpp v31, v31, v31 quad_perm:[2,3,0,1] row_mask:0xf bank_mask:0xf bound_ctrl:1
	v_add_f32_dpp v22, v22, v22 row_mirror row_mask:0xf bank_mask:0xf bound_ctrl:1
	v_add_f32_dpp v23, v23, v23 row_mirror row_mask:0xf bank_mask:0xf bound_ctrl:1
	s_waitcnt lgkmcnt(1)
	v_pk_mul_f32 v[24:25], v[26:27], v[22:23] op_sel_hi:[0,1]
	v_add_f32_dpp v30, v30, v30 row_half_mirror row_mask:0xf bank_mask:0xf bound_ctrl:1
	v_add_f32_dpp v31, v31, v31 row_half_mirror row_mask:0xf bank_mask:0xf bound_ctrl:1
	v_pk_fma_f32 v[24:25], v[6:7], v[54:55], v[24:25] op_sel_hi:[0,1,1] neg_lo:[0,0,1] neg_hi:[0,0,1]
	v_add_f32_dpp v30, v30, v30 row_mirror row_mask:0xf bank_mask:0xf bound_ctrl:1
	v_add_f32_dpp v31, v31, v31 row_mirror row_mask:0xf bank_mask:0xf bound_ctrl:1
	s_waitcnt lgkmcnt(0)
; #define LAS __attribute__((address_space(3)))
; DI unsigned pk2(float a, float b) { f32x2 v = {a, b}; bf2_t r = __builtin_convertvector(v, bf2_t); return __builtin_bit_cast(unsigned, r); }
; DI f32x2 red16p(f32x2 x) { float a = x.x, b = x.y; red16x2(a, b); return (f32x2){a, b}; }
; DI void scan_bh2(const Args& a, int l, int bh, int halfsel, LAS unsigned char* lds) {
;     ...
;             for (int st = 0; st < T; ++st) {
;                 f32x4 nr4, nd4, nk4, nkk4, nb4; f32x2 nv2;
;                 if (st < T - 1) {
;                     const LAS float* o = cur + (st + 1) * 384;
;                     nr4 = *(const LAS f32x4*)(o + kq * 4); nd4 = *(const LAS f32x4*)(o + 64 + kq * 4); nk4 = *(const LAS f32x4*)(o + 128 + kq * 4);
;                     nkk4 = *(const LAS f32x4*)(o + 192 + kq * 4); nb4 = *(const LAS f32x4*)(o + 256 + kq * 4); nv2 = *(const LAS f32x2*)(o + 320 + row0);
;                 }
;                 f32x2 sa = S[0] * kk4[0]; sa += S[1] * kk4[1]; f32x2 sb = S[2] * kk4[2]; sb += S[3] * kk4[3]; sa += sb;
;                 sa = red16p(sa); sa = -sa;
; #pragma unroll
;                 for (int j = 0; j < 4; ++j) S[j] = S[j] * d4[j] + sa * b4[j] + v2 * k4[j];
;                 f32x2 y = S[0] * r4[0]; y += S[1] * r4[1]; f32x2 yc = S[2] * r4[2]; yc += S[3] * r4[3]; y += yc;
;                 y = red16p(y);
;                 *(LAS unsigned*)(yb + st * 128 + row0 * 2) = pk2(y.x, y.y);
;                 if (st < T - 1) { r4 = nr4; d4 = nd4; k4 = nk4; kk4 = nkk4; b4 = nb4; v2 = nv2; }
;             }
	v_pk_fma_f32 v[54:55], v[18:19], v[60:61], v[24:25] op_sel_hi:[0,1,1]
	v_cvt_pk_bf16_f32 v17, v30, v31
	v_pk_mul_f32 v[24:25], v[26:27], v[22:23] op_sel:[1,0]
	ds_write_b32 v14, v17 offset:3456
	v_pk_fma_f32 v[6:7], v[6:7], v[50:51], v[24:25] op_sel:[1,0,0] neg_lo:[0,0,1] neg_hi:[0,0,1]
	ds_read_b128 v[30:33], v15 offset:44544
	ds_read_b128 v[34:37], v15 offset:44800
	ds_read_b128 v[38:41], v15 offset:45056
	ds_read_b128 v[42:45], v15 offset:45312
	ds_read_b128 v[46:49], v15 offset:45568
	ds_read_b64 v[58:59], v16 offset:45824
	v_pk_fma_f32 v[50:51], v[18:19], v[60:61], v[6:7] op_sel:[1,0,0]
	v_pk_mul_f32 v[6:7], v[28:29], v[22:23] op_sel_hi:[0,1]
	v_pk_fma_f32 v[6:7], v[8:9], v[56:57], v[6:7] op_sel_hi:[0,1,1] neg_lo:[0,0,1] neg_hi:[0,0,1]
	v_mov_b32_e32 v8, v29
	v_pk_fma_f32 v[56:57], v[20:21], v[60:61], v[6:7] op_sel_hi:[0,1,1]
	v_mov_b32_e32 v6, v9
	v_pk_mul_f32 v[8:9], v[8:9], v[22:23] op_sel_hi:[0,1]
	v_pk_fma_f32 v[6:7], v[6:7], v[52:53], v[8:9] op_sel_hi:[0,1,1] neg_lo:[0,0,1] neg_hi:[0,0,1]
	v_mov_b32_e32 v8, v21
	s_waitcnt lgkmcnt(2)
	v_pk_mul_f32 v[62:63], v[42:43], v[50:51] op_sel:[1,0]
	v_pk_fma_f32 v[52:53], v[8:9], v[60:61], v[6:7] op_sel_hi:[0,1,1]
	v_pk_fma_f32 v[42:43], v[42:43], v[54:55], v[62:63] op_sel_hi:[0,1,1]
	v_mov_b32_e32 v62, v45
	v_pk_mul_f32 v[6:7], v[2:3], v[50:51] op_sel:[1,0]
	v_pk_mul_f32 v[62:63], v[62:63], v[52:53] op_sel_hi:[0,1]
	v_pk_fma_f32 v[2:3], v[2:3], v[54:55], v[6:7] op_sel_hi:[0,1,1]
	v_mov_b32_e32 v6, v5
	v_pk_fma_f32 v[44:45], v[44:45], v[56:57], v[62:63] op_sel_hi:[0,1,1]
	v_pk_mul_f32 v[6:7], v[6:7], v[52:53] op_sel_hi:[0,1]
	v_pk_add_f32 v[42:43], v[42:43], v[44:45]
	v_pk_fma_f32 v[4:5], v[4:5], v[56:57], v[6:7] op_sel_hi:[0,1,1]
	s_nop 0
	v_add_f32_dpp v42, v42, v42 quad_perm:[1,0,3,2] row_mask:0xf bank_mask:0xf bound_ctrl:1
	v_add_f32_dpp v43, v43, v43 quad_perm:[1,0,3,2] row_mask:0xf bank_mask:0xf bound_ctrl:1
	v_pk_add_f32 v[2:3], v[2:3], v[4:5]
	v_add_f32_dpp v42, v42, v42 quad_perm:[2,3,0,1] row_mask:0xf bank_mask:0xf bound_ctrl:1
	v_add_f32_dpp v43, v43, v43 quad_perm:[2,3,0,1] row_mask:0xf bank_mask:0xf bound_ctrl:1
	v_add_f32_dpp v2, v2, v2 quad_perm:[1,0,3,2] row_mask:0xf bank_mask:0xf bound_ctrl:1
	v_add_f32_dpp v3, v3, v3 quad_perm:[1,0,3,2] row_mask:0xf bank_mask:0xf bound_ctrl:1
	v_add_f32_dpp v42, v42, v42 row_half_mirror row_mask:0xf bank_mask:0xf bound_ctrl:1
	v_add_f32_dpp v43, v43, v43 row_half_mirror row_mask:0xf bank_mask:0xf bound_ctrl:1
	v_add_f32_dpp v2, v2, v2 quad_perm:[2,3,0,1] row_mask:0xf bank_mask:0xf bound_ctrl:1
	v_add_f32_dpp v3, v3, v3 quad_perm:[2,3,0,1] row_mask:0xf bank_mask:0xf bound_ctrl:1
	v_add_f32_dpp v42, v42, v42 row_mirror row_mask:0xf bank_mask:0xf bound_ctrl:1
	v_add_f32_dpp v43, v43, v43 row_mirror row_mask:0xf bank_mask:0xf bound_ctrl:1
	s_waitcnt lgkmcnt(1)
	v_pk_mul_f32 v[44:45], v[46:47], v[42:43] op_sel_hi:[0,1]
	v_add_f32_dpp v2, v2, v2 row_half_mirror row_mask:0xf bank_mask:0xf bound_ctrl:1
	v_add_f32_dpp v3, v3, v3 row_half_mirror row_mask:0xf bank_mask:0xf bound_ctrl:1
	v_pk_fma_f32 v[44:45], v[34:35], v[54:55], v[44:45] op_sel_hi:[0,1,1] neg_lo:[0,0,1] neg_hi:[0,0,1]
	v_add_f32_dpp v2, v2, v2 row_mirror row_mask:0xf bank_mask:0xf bound_ctrl:1
	v_add_f32_dpp v3, v3, v3 row_mirror row_mask:0xf bank_mask:0xf bound_ctrl:1
	s_waitcnt lgkmcnt(0)
	v_pk_fma_f32 v[54:55], v[38:39], v[58:59], v[44:45] op_sel_hi:[0,1,1]
	v_pk_mul_f32 v[44:45], v[46:47], v[42:43] op_sel:[1,0]
	v_cvt_pk_bf16_f32 v2, v2, v3
	v_pk_fma_f32 v[34:35], v[34:35], v[50:51], v[44:45] op_sel:[1,0,0] neg_lo:[0,0,1] neg_hi:[0,0,1]
	ds_write_b32 v14, v2 offset:3584
	v_pk_fma_f32 v[50:51], v[38:39], v[58:59], v[34:35] op_sel:[1,0,0]
	v_pk_mul_f32 v[34:35], v[48:49], v[42:43] op_sel_hi:[0,1]
	ds_read_b128 v[2:5], v15 offset:46080
	ds_read_b128 v[6:9], v15 offset:46336
	ds_read_b128 v[18:21], v15 offset:46592
	ds_read_b128 v[22:25], v15 offset:46848
	ds_read_b128 v[26:29], v15 offset:47104
	ds_read_b64 v[60:61], v16 offset:47360
	v_pk_fma_f32 v[34:35], v[36:37], v[56:57], v[34:35] op_sel_hi:[0,1,1] neg_lo:[0,0,1] neg_hi:[0,0,1]
	v_mov_b32_e32 v36, v49
	v_pk_fma_f32 v[56:57], v[40:41], v[58:59], v[34:35] op_sel_hi:[0,1,1]
	v_mov_b32_e32 v34, v37
	v_pk_mul_f32 v[36:37], v[36:37], v[42:43] op_sel_hi:[0,1]
	v_pk_fma_f32 v[34:35], v[34:35], v[52:53], v[36:37] op_sel_hi:[0,1,1] neg_lo:[0,0,1] neg_hi:[0,0,1]
	v_mov_b32_e32 v36, v41
	v_pk_fma_f32 v[52:53], v[36:37], v[58:59], v[34:35] op_sel_hi:[0,1,1]
	s_waitcnt lgkmcnt(2)
	v_pk_mul_f32 v[58:59], v[22:23], v[50:51] op_sel:[1,0]
	v_pk_mul_f32 v[34:35], v[30:31], v[50:51] op_sel:[1,0]
	v_pk_fma_f32 v[22:23], v[22:23], v[54:55], v[58:59] op_sel_hi:[0,1,1]
	v_mov_b32_e32 v58, v25
	v_pk_mul_f32 v[58:59], v[58:59], v[52:53] op_sel_hi:[0,1]
	v_pk_fma_f32 v[24:25], v[24:25], v[56:57], v[58:59] op_sel_hi:[0,1,1]
	v_pk_add_f32 v[22:23], v[22:23], v[24:25]
	v_pk_fma_f32 v[30:31], v[30:31], v[54:55], v[34:35] op_sel_hi:[0,1,1]
	s_nop 0
	v_add_f32_dpp v22, v22, v22 quad_perm:[1,0,3,2] row_mask:0xf bank_mask:0xf bound_ctrl:1
	v_add_f32_dpp v23, v23, v23 quad_perm:[1,0,3,2] row_mask:0xf bank_mask:0xf bound_ctrl:1
	v_mov_b32_e32 v34, v33
	v_add_f32_dpp v22, v22, v22 quad_perm:[2,3,0,1] row_mask:0xf bank_mask:0xf bound_ctrl:1
	v_add_f32_dpp v23, v23, v23 quad_perm:[2,3,0,1] row_mask:0xf bank_mask:0xf bound_ctrl:1
	v_pk_mul_f32 v[34:35], v[34:35], v[52:53] op_sel_hi:[0,1]
	v_add_f32_dpp v22, v22, v22 row_half_mirror row_mask:0xf bank_mask:0xf bound_ctrl:1
	v_add_f32_dpp v23, v23, v23 row_half_mirror row_mask:0xf bank_mask:0xf bound_ctrl:1
	v_pk_fma_f32 v[32:33], v[32:33], v[56:57], v[34:35] op_sel_hi:[0,1,1]
	v_add_f32_dpp v22, v22, v22 row_mirror row_mask:0xf bank_mask:0xf bound_ctrl:1
	v_add_f32_dpp v23, v23, v23 row_mirror row_mask:0xf bank_mask:0xf bound_ctrl:1
	v_pk_add_f32 v[30:31], v[30:31], v[32:33]
	s_waitcnt lgkmcnt(1)
; #define LAS __attribute__((address_space(3)))
; DI unsigned pk2(float a, float b) { f32x2 v = {a, b}; bf2_t r = __builtin_convertvector(v, bf2_t); return __builtin_bit_cast(unsigned, r); }
; DI f32x2 red16p(f32x2 x) { float a = x.x, b = x.y; red16x2(a, b); return (f32x2){a, b}; }
; DI void scan_bh2(const Args& a, int l, int bh, int halfsel, LAS unsigned char* lds) {
;     ...
;             for (int st = 0; st < T; ++st) {
;                 f32x4 nr4, nd4, nk4, nkk4, nb4; f32x2 nv2;
;                 if (st < T - 1) {
;                     const LAS float* o = cur + (st + 1) * 384;
;                     nr4 = *(const LAS f32x4*)(o + kq * 4); nd4 = *(const LAS f32x4*)(o + 64 + kq * 4); nk4 = *(const LAS f32x4*)(o + 128 + kq * 4);
;                     nkk4 = *(const LAS f32x4*)(o + 192 + kq * 4); nb4 = *(const LAS f32x4*)(o + 256 + kq * 4); nv2 = *(const LAS f32x2*)(o + 320 + row0);
;                 }
;                 f32x2 sa = S[0] * kk4[0]; sa += S[1] * kk4[1]; f32x2 sb = S[2] * kk4[2]; sb += S[3] * kk4[3]; sa += sb;
;                 sa = red16p(sa); sa = -sa;
; #pragma unroll
;                 for (int j = 0; j < 4; ++j) S[j] = S[j] * d4[j] + sa * b4[j] + v2 * k4[j];
;                 f32x2 y = S[0] * r4[0]; y += S[1] * r4[1]; f32x2 yc = S[2] * r4[2]; yc += S[3] * r4[3]; y += yc;
;                 y = red16p(y);
;                 *(LAS unsigned*)(yb + st * 128 + row0 * 2) = pk2(y.x, y.y);
;                 if (st < T - 1) { r4 = nr4; d4 = nd4; k4 = nk4; kk4 = nkk4; b4 = nb4; v2 = nv2; }
;             }
;             __syncthreads();
;             if (tid < T * 4) { const int rowi = tid >> 2, seg = tid & 3;
;                 *(u32x4*)(Y + ((size_t)b * SEQ + c * T + rowi) * 512 + h * 64 + halfsel * 32 + seg * 8) = *(const LAS u32x4*)(yb + rowi * 128 + halfsel * 64 + seg * 16); }
	v_pk_mul_f32 v[24:25], v[26:27], v[22:23] op_sel_hi:[0,1]
	v_pk_mul_f32 v[26:27], v[26:27], v[22:23] op_sel:[1,0]
	v_pk_fma_f32 v[24:25], v[6:7], v[54:55], v[24:25] op_sel_hi:[0,1,1] neg_lo:[0,0,1] neg_hi:[0,0,1]
	v_pk_fma_f32 v[6:7], v[6:7], v[50:51], v[26:27] op_sel:[1,0,0] neg_lo:[0,0,1] neg_hi:[0,0,1]
	s_waitcnt lgkmcnt(0)
	v_pk_fma_f32 v[24:25], v[18:19], v[60:61], v[24:25] op_sel_hi:[0,1,1]
	v_pk_fma_f32 v[6:7], v[18:19], v[60:61], v[6:7] op_sel:[1,0,0]
	v_pk_mul_f32 v[18:19], v[28:29], v[22:23] op_sel_hi:[0,1]
	v_pk_fma_f32 v[18:19], v[8:9], v[56:57], v[18:19] op_sel_hi:[0,1,1] neg_lo:[0,0,1] neg_hi:[0,0,1]
	v_pk_fma_f32 v[18:19], v[20:21], v[60:61], v[18:19] op_sel_hi:[0,1,1]
	v_mov_b32_e32 v20, v29
	v_mov_b32_e32 v8, v9
	v_pk_mul_f32 v[22:23], v[20:21], v[22:23] op_sel_hi:[0,1]
	v_pk_fma_f32 v[8:9], v[8:9], v[52:53], v[22:23] op_sel_hi:[0,1,1] neg_lo:[0,0,1] neg_hi:[0,0,1]
	v_mov_b32_e32 v20, v21
	v_add_f32_dpp v30, v30, v30 quad_perm:[1,0,3,2] row_mask:0xf bank_mask:0xf bound_ctrl:1
	v_add_f32_dpp v31, v31, v31 quad_perm:[1,0,3,2] row_mask:0xf bank_mask:0xf bound_ctrl:1
	v_pk_fma_f32 v[8:9], v[20:21], v[60:61], v[8:9] op_sel_hi:[0,1,1]
	v_pk_mul_f32 v[20:21], v[2:3], v[6:7] op_sel:[1,0]
	v_add_f32_dpp v30, v30, v30 quad_perm:[2,3,0,1] row_mask:0xf bank_mask:0xf bound_ctrl:1
	v_add_f32_dpp v31, v31, v31 quad_perm:[2,3,0,1] row_mask:0xf bank_mask:0xf bound_ctrl:1
	s_nop 0
	v_pk_fma_f32 v[2:3], v[2:3], v[24:25], v[20:21] op_sel_hi:[0,1,1]
	v_mov_b32_e32 v20, v5
	v_add_f32_dpp v30, v30, v30 row_half_mirror row_mask:0xf bank_mask:0xf bound_ctrl:1
	v_add_f32_dpp v31, v31, v31 row_half_mirror row_mask:0xf bank_mask:0xf bound_ctrl:1
	v_pk_mul_f32 v[20:21], v[20:21], v[8:9] op_sel_hi:[0,1]
	v_add_f32_dpp v30, v30, v30 row_mirror row_mask:0xf bank_mask:0xf bound_ctrl:1
	v_add_f32_dpp v31, v31, v31 row_mirror row_mask:0xf bank_mask:0xf bound_ctrl:1
	v_pk_fma_f32 v[4:5], v[4:5], v[18:19], v[20:21] op_sel_hi:[0,1,1]
	v_cvt_pk_bf16_f32 v17, v30, v31
	ds_write_b32 v14, v17 offset:3712
	v_pk_add_f32 v[2:3], v[2:3], v[4:5]
	ds_read_b128 v[30:33], v15 offset:47616
	ds_read_b128 v[34:37], v15 offset:47872
	ds_read_b128 v[38:41], v15 offset:48128
	ds_read_b128 v[42:45], v15 offset:48384
	ds_read_b128 v[46:49], v15 offset:48640
	ds_read_b64 v[16:17], v16 offset:48896
	v_add_f32_dpp v2, v2, v2 quad_perm:[1,0,3,2] row_mask:0xf bank_mask:0xf bound_ctrl:1
	v_add_f32_dpp v3, v3, v3 quad_perm:[1,0,3,2] row_mask:0xf bank_mask:0xf bound_ctrl:1
	v_add_u32_e32 v14, 0xc00, v14
	v_add_f32_dpp v2, v2, v2 quad_perm:[2,3,0,1] row_mask:0xf bank_mask:0xf bound_ctrl:1
	v_add_f32_dpp v3, v3, v3 quad_perm:[2,3,0,1] row_mask:0xf bank_mask:0xf bound_ctrl:1
	s_waitcnt lgkmcnt(2)
	v_mov_b32_e32 v4, v45
	v_add_f32_dpp v2, v2, v2 row_half_mirror row_mask:0xf bank_mask:0xf bound_ctrl:1
	v_add_f32_dpp v3, v3, v3 row_half_mirror row_mask:0xf bank_mask:0xf bound_ctrl:1
	v_pk_mul_f32 v[4:5], v[4:5], v[8:9] op_sel_hi:[0,1]
	v_add_f32_dpp v2, v2, v2 row_mirror row_mask:0xf bank_mask:0xf bound_ctrl:1
	v_add_f32_dpp v3, v3, v3 row_mirror row_mask:0xf bank_mask:0xf bound_ctrl:1
	v_pk_fma_f32 v[4:5], v[44:45], v[18:19], v[4:5] op_sel_hi:[0,1,1]
	v_cvt_pk_bf16_f32 v15, v2, v3
	v_pk_mul_f32 v[2:3], v[42:43], v[6:7] op_sel:[1,0]
	s_waitcnt lgkmcnt(1)
	v_mov_b32_e32 v22, v49
	v_pk_fma_f32 v[2:3], v[42:43], v[24:25], v[2:3] op_sel_hi:[0,1,1]
	v_pk_add_f32 v[20:21], v[2:3], v[4:5]
	s_nop 0
	s_nop 0
	v_add_f32_dpp v20, v20, v20 quad_perm:[1,0,3,2] row_mask:0xf bank_mask:0xf bound_ctrl:1
	v_add_f32_dpp v21, v21, v21 quad_perm:[1,0,3,2] row_mask:0xf bank_mask:0xf bound_ctrl:1
	s_nop 0
	v_add_f32_dpp v20, v20, v20 quad_perm:[2,3,0,1] row_mask:0xf bank_mask:0xf bound_ctrl:1
	v_add_f32_dpp v21, v21, v21 quad_perm:[2,3,0,1] row_mask:0xf bank_mask:0xf bound_ctrl:1
	s_nop 0
	v_add_f32_dpp v20, v20, v20 row_half_mirror row_mask:0xf bank_mask:0xf bound_ctrl:1
	v_add_f32_dpp v21, v21, v21 row_half_mirror row_mask:0xf bank_mask:0xf bound_ctrl:1
	s_nop 0
	v_add_f32_dpp v20, v20, v20 row_mirror row_mask:0xf bank_mask:0xf bound_ctrl:1
	v_add_f32_dpp v21, v21, v21 row_mirror row_mask:0xf bank_mask:0xf bound_ctrl:1
	s_nop 0
	v_pk_mul_f32 v[4:5], v[46:47], v[20:21] op_sel:[1,0]
	v_pk_mul_f32 v[2:3], v[46:47], v[20:21] op_sel_hi:[0,1]
	v_pk_fma_f32 v[4:5], v[34:35], v[6:7], v[4:5] op_sel:[1,0,0] neg_lo:[0,0,1] neg_hi:[0,0,1]
	v_pk_mul_f32 v[6:7], v[48:49], v[20:21] op_sel_hi:[0,1]
	v_pk_fma_f32 v[6:7], v[36:37], v[18:19], v[6:7] op_sel_hi:[0,1,1] neg_lo:[0,0,1] neg_hi:[0,0,1]
	v_mov_b32_e32 v18, v37
	v_pk_mul_f32 v[20:21], v[22:23], v[20:21] op_sel_hi:[0,1]
	v_pk_fma_f32 v[8:9], v[18:19], v[8:9], v[20:21] op_sel_hi:[0,1,1] neg_lo:[0,0,1] neg_hi:[0,0,1]
	v_mov_b32_e32 v18, v41
	v_pk_fma_f32 v[2:3], v[34:35], v[24:25], v[2:3] op_sel_hi:[0,1,1] neg_lo:[0,0,1] neg_hi:[0,0,1]
	s_waitcnt lgkmcnt(0)
	v_pk_fma_f32 v[4:5], v[38:39], v[16:17], v[4:5] op_sel:[1,0,0]
	v_pk_fma_f32 v[8:9], v[18:19], v[16:17], v[8:9] op_sel_hi:[0,1,1]
	v_mov_b32_e32 v18, v33
	v_pk_fma_f32 v[2:3], v[38:39], v[16:17], v[2:3] op_sel_hi:[0,1,1]
	v_pk_fma_f32 v[6:7], v[40:41], v[16:17], v[6:7] op_sel_hi:[0,1,1]
	v_pk_mul_f32 v[16:17], v[30:31], v[4:5] op_sel:[1,0]
	v_pk_mul_f32 v[18:19], v[18:19], v[8:9] op_sel_hi:[0,1]
	v_pk_fma_f32 v[16:17], v[30:31], v[2:3], v[16:17] op_sel_hi:[0,1,1]
	v_pk_fma_f32 v[18:19], v[32:33], v[6:7], v[18:19] op_sel_hi:[0,1,1]
	v_pk_add_f32 v[16:17], v[16:17], v[18:19]
	s_nop 0
	s_nop 0
	v_add_f32_dpp v16, v16, v16 quad_perm:[1,0,3,2] row_mask:0xf bank_mask:0xf bound_ctrl:1
	v_add_f32_dpp v17, v17, v17 quad_perm:[1,0,3,2] row_mask:0xf bank_mask:0xf bound_ctrl:1
	s_nop 0
	v_add_f32_dpp v16, v16, v16 quad_perm:[2,3,0,1] row_mask:0xf bank_mask:0xf bound_ctrl:1
	v_add_f32_dpp v17, v17, v17 quad_perm:[2,3,0,1] row_mask:0xf bank_mask:0xf bound_ctrl:1
	s_nop 0
	v_add_f32_dpp v16, v16, v16 row_half_mirror row_mask:0xf bank_mask:0xf bound_ctrl:1
	v_add_f32_dpp v17, v17, v17 row_half_mirror row_mask:0xf bank_mask:0xf bound_ctrl:1
	s_nop 0
	v_add_f32_dpp v16, v16, v16 row_mirror row_mask:0xf bank_mask:0xf bound_ctrl:1
	v_add_f32_dpp v17, v17, v17 row_mirror row_mask:0xf bank_mask:0xf bound_ctrl:1
	s_nop 0
	v_cvt_pk_bf16_f32 v16, v16, v17
	ds_write2_b32 v14, v15, v16 offset0:192 offset1:224
	s_waitcnt lgkmcnt(0)
	s_barrier
	s_and_saveexec_b64 s[2:3], vcc
	s_cbranch_execz .LBB0_496
	v_readlane_b32 s6, v247, 9
	s_add_i32 s5, s6, s5
	v_add3_u32 v14, s5, v13, v128
	ds_read_b128 v[14:17], v14
	s_waitcnt lgkmcnt(0)
	global_store_dwordx4 v[0:1], v[14:17], off
	s_branch .LBB0_496
